# conv4x8 row loads: all seven rows in flight (one round trip)
# speedup vs baseline: 1.0096x; 1.0010x over previous
.LBB0_220:
	s_or_b64 exec, exec, s[2:3]
	v_cmp_lt_i32_e64 s[6:7], -1, v7
	v_mov_b32_e32 v110, 0
	v_mov_b32_e32 v104, 0
	v_mov_b32_e32 v100, 0
	v_mov_b32_e32 v94, 0
	v_mov_b32_e32 v88, 0
	v_mov_b32_e32 v78, 0
	v_mov_b32_e32 v70, 0
	v_mov_b32_e32 v188, 0
	v_mov_b32_e32 v189, 0
	v_mov_b32_e32 v190, 0
	v_mov_b32_e32 v191, 0
	s_and_saveexec_b64 s[2:3], s[6:7]
	s_cbranch_execz .LBB0_222
	v_mov_b32_e32 v5, v2
	v_lshl_add_u64 v[8:9], v[42:43], 0, v[4:5]
	global_load_dwordx4 v[188:191], v[8:9], off
.LBB0_222:
	s_or_b64 exec, exec, s[2:3]
	v_cmp_lt_i32_e64 s[8:9], -2, v7
	v_mov_b32_e32 v84, 0
	v_mov_b32_e32 v86, 0
	v_mov_b32_e32 v76, 0
	v_mov_b32_e32 v68, 0
	v_mov_b32_e32 v60, 0
	v_mov_b32_e32 v54, 0
	v_mov_b32_e32 v50, 0
	v_mov_b32_e32 v46, 0
	v_mov_b32_e32 v44, 0
	v_mov_b32_e32 v192, 0
	v_mov_b32_e32 v193, 0
	v_mov_b32_e32 v194, 0
	v_mov_b32_e32 v195, 0
	s_and_saveexec_b64 s[2:3], s[8:9]
	s_cbranch_execz .LBB0_224
	v_mov_b32_e32 v5, v2
	v_lshl_add_u64 v[8:9], v[42:43], 0, v[4:5]
	v_add_co_u32_e32 v8, vcc, 0x2000, v8
	s_nop 1
	v_addc_co_u32_e32 v9, vcc, 0, v9, vcc
	global_load_dwordx4 v[192:195], v[8:9], off offset:1024
.LBB0_224:
	s_or_b64 exec, exec, s[2:3]
	v_cmp_lt_i32_e64 s[10:11], -3, v7
	v_mov_b32_e32 v92, 0
	v_mov_b32_e32 v82, 0
	v_mov_b32_e32 v74, 0
	v_mov_b32_e32 v64, 0
	v_mov_b32_e32 v58, 0
	v_mov_b32_e32 v52, 0
	v_mov_b32_e32 v48, 0
	v_mov_b32_e32 v196, 0
	v_mov_b32_e32 v197, 0
	v_mov_b32_e32 v198, 0
	v_mov_b32_e32 v199, 0
	s_and_saveexec_b64 s[2:3], s[10:11]
	s_cbranch_execz .LBB0_226
	v_mov_b32_e32 v5, v2
	v_lshl_add_u64 v[8:9], v[42:43], 0, v[4:5]
	v_add_co_u32_e32 v8, vcc, 0x4000, v8
	s_nop 1
	v_addc_co_u32_e32 v9, vcc, 0, v9, vcc
	global_load_dwordx4 v[196:199], v[8:9], off offset:2048
.LBB0_226:
	s_or_b64 exec, exec, s[2:3]
	v_cmp_lt_i32_e64 s[12:13], -4, v7
	v_mov_b32_e32 v41, 0
	v_mov_b32_e32 v106, 0
	v_mov_b32_e32 v102, 0
	v_mov_b32_e32 v96, 0
	v_mov_b32_e32 v90, 0
	v_mov_b32_e32 v80, 0
	v_mov_b32_e32 v72, 0
	v_mov_b32_e32 v62, 0
	v_mov_b32_e32 v56, 0
	v_mov_b32_e32 v200, 0
	v_mov_b32_e32 v201, 0
	v_mov_b32_e32 v202, 0
	v_mov_b32_e32 v203, 0
	s_and_saveexec_b64 s[2:3], s[12:13]
	s_cbranch_execz .LBB0_228
	v_mov_b32_e32 v5, v2
	v_lshl_add_u64 v[4:5], v[42:43], 0, v[4:5]
	v_add_co_u32_e32 v4, vcc, 0x6000, v4
	s_nop 1
	v_addc_co_u32_e32 v5, vcc, 0, v5, vcc
	global_load_dwordx4 v[200:203], v[4:5], off offset:3072
.LBB0_228:
	s_or_b64 exec, exec, s[2:3]
	s_waitcnt vmcnt(0)
	v_lshlrev_b32_e32 v129, 16, v244
	v_and_b32_e32 v125, 0xffff0000, v244
	v_lshlrev_b32_e32 v121, 16, v245
	v_and_b32_e32 v119, 0xffff0000, v245
	v_lshlrev_b32_e32 v117, 16, v246
	v_and_b32_e32 v115, 0xffff0000, v246
	v_lshlrev_b32_e32 v109, 16, v247
	v_and_b32_e32 v99, 0xffff0000, v247
	v_lshlrev_b32_e32 v128, 16, v248
	v_and_b32_e32 v124, 0xffff0000, v248
	v_lshlrev_b32_e32 v120, 16, v249
	v_and_b32_e32 v118, 0xffff0000, v249
	v_lshlrev_b32_e32 v116, 16, v250
	v_and_b32_e32 v114, 0xffff0000, v250
	v_lshlrev_b32_e32 v108, 16, v251
	v_and_b32_e32 v98, 0xffff0000, v251
	v_lshlrev_b32_e32 v113, 16, v252
	v_and_b32_e32 v111, 0xffff0000, v252
	v_lshlrev_b32_e32 v105, 16, v253
	v_and_b32_e32 v101, 0xffff0000, v253
	v_lshlrev_b32_e32 v95, 16, v254
	v_and_b32_e32 v89, 0xffff0000, v254
	v_lshlrev_b32_e32 v79, 16, v255
	v_and_b32_e32 v71, 0xffff0000, v255
	v_lshlrev_b32_e32 v112, 16, v188
	v_and_b32_e32 v110, 0xffff0000, v188
	v_lshlrev_b32_e32 v104, 16, v189
	v_and_b32_e32 v100, 0xffff0000, v189
	v_lshlrev_b32_e32 v94, 16, v190
	v_and_b32_e32 v88, 0xffff0000, v190
	v_lshlrev_b32_e32 v78, 16, v191
	v_and_b32_e32 v70, 0xffff0000, v191
	v_lshlrev_b32_e32 v86, 16, v192
	v_and_b32_e32 v76, 0xffff0000, v192
	v_lshlrev_b32_e32 v68, 16, v193
	v_and_b32_e32 v60, 0xffff0000, v193
	v_lshlrev_b32_e32 v54, 16, v194
	v_and_b32_e32 v50, 0xffff0000, v194
	v_lshlrev_b32_e32 v46, 16, v195
	v_and_b32_e32 v44, 0xffff0000, v195
	v_lshlrev_b32_e32 v84, 16, v196
	v_and_b32_e32 v92, 0xffff0000, v196
	v_lshlrev_b32_e32 v82, 16, v197
	v_and_b32_e32 v74, 0xffff0000, v197
	v_lshlrev_b32_e32 v64, 16, v198
	v_and_b32_e32 v58, 0xffff0000, v198
	v_lshlrev_b32_e32 v52, 16, v199
	v_and_b32_e32 v48, 0xffff0000, v199
	v_lshlrev_b32_e32 v106, 16, v200
	v_and_b32_e32 v102, 0xffff0000, v200
	v_lshlrev_b32_e32 v96, 16, v201
	v_and_b32_e32 v90, 0xffff0000, v201
	v_lshlrev_b32_e32 v80, 16, v202
	v_and_b32_e32 v72, 0xffff0000, v202
	v_lshlrev_b32_e32 v62, 16, v203
	v_and_b32_e32 v56, 0xffff0000, v203
	v_readlane_b32 s36, v242, 2
	v_readlane_b32 s40, v242, 6
	v_readlane_b32 s41, v242, 7
	v_lshlrev_b32_e32 v24, 2, v6
	v_mov_b32_e32 v25, v2
	v_readlane_b32 s42, v242, 8
	v_readlane_b32 s43, v242, 9
	v_readlane_b32 s44, v242, 10
	v_readlane_b32 s45, v242, 11
	v_readlane_b32 s46, v242, 12
	v_readlane_b32 s47, v242, 13
	v_readlane_b32 s48, v242, 14
	v_readlane_b32 s49, v242, 15
	v_readlane_b32 s50, v242, 16
	v_readlane_b32 s51, v242, 17
	s_mov_b64 s[20:21], s[40:41]
	v_lshl_add_u64 v[12:13], s[20:21], 0, v[24:25]
	s_mov_b64 s[2:3], 0x1800
	v_add_co_u32_e32 v10, vcc, s34, v12
	v_lshl_add_u64 v[8:9], v[12:13], 0, s[2:3]
	s_nop 0
	v_addc_co_u32_e32 v11, vcc, 0, v13, vcc
	s_mov_b64 s[2:3], 0x3000
	global_load_dwordx4 v[4:7], v24, s[20:21] offset:16
	global_load_dwordx4 v[16:19], v24, s[20:21]
	global_load_dwordx4 v[36:39], v[10:11], off offset:2048
	global_load_dwordx4 v[28:31], v[8:9], off offset:16
	v_lshl_add_u64 v[8:9], v[12:13], 0, s[2:3]
	s_movk_i32 s2, 0x3000
	v_add_co_u32_e32 v10, vcc, s2, v12
	s_mov_b64 s[2:3], 0x4800
	s_nop 0
	v_addc_co_u32_e32 v11, vcc, 0, v13, vcc
	v_lshl_add_u64 v[14:15], v[12:13], 0, s[2:3]
	v_add_co_u32_e32 v12, vcc, s35, v12
	s_mov_b64 s[22:23], s[42:43]
	s_nop 0
	v_addc_co_u32_e32 v13, vcc, 0, v13, vcc
	global_load_dwordx4 v[20:23], v[10:11], off
	s_nop 0
	global_load_dwordx4 v[8:11], v[8:9], off offset:16
	s_nop 0
	global_load_dwordx4 v[130:133], v[12:13], off offset:2048
	global_load_dwordx4 v[32:35], v[14:15], off offset:16
	s_nop 0
	global_load_dwordx4 v[12:15], v24, s[22:23] offset:16
	s_nop 0
	global_load_dwordx4 v[24:27], v24, s[22:23]
	v_mov_b32_e32 v87, v112
	v_mov_b32_e32 v77, v110
	v_mov_b32_e32 v69, v104
	v_mov_b32_e32 v61, v100
	v_mov_b32_e32 v55, v94
	v_mov_b32_e32 v51, v88
	v_mov_b32_e32 v85, v86
	v_mov_b32_e32 v93, v76
	v_mov_b32_e32 v83, v68
	v_mov_b32_e32 v75, v60
	v_mov_b32_e32 v65, v54
	v_mov_b32_e32 v59, v50
	v_mov_b32_e32 v103, v92
	v_mov_b32_e32 v73, v58
	v_mov_b32_e32 v97, v82
	v_mov_b32_e32 v63, v52
	v_mov_b32_e32 v107, v84
	v_mov_b32_e32 v91, v74
	v_mov_b32_e32 v81, v64
	v_lshlrev_b32_e32 v137, 1, v40
	v_readlane_b32 s37, v242, 3
	v_readlane_b32 s38, v242, 4
	v_readlane_b32 s39, v242, 5
	s_mov_b64 s[24:25], s[44:45]
	s_mov_b64 s[26:27], s[46:47]
	s_mov_b64 s[28:29], s[48:49]
	s_mov_b64 s[30:31], s[50:51]
	s_waitcnt vmcnt(8)
	v_mov_b32_e32 v123, v16
	s_waitcnt vmcnt(7)
	v_mov_b32_e32 v122, v36
	v_pk_mul_f32 v[126:127], v[128:129], v[122:123]
	s_waitcnt vmcnt(0)
	v_add_f32_e32 v16, v127, v24
	v_add_f32_e32 v16, v126, v16
	v_mov_b32_e32 v126, v130
	v_mov_b32_e32 v127, v20
	v_pk_mul_f32 v[138:139], v[112:113], v[126:127]
	s_nop 0
	v_add_f32_e32 v16, v139, v16
	v_add_f32_e32 v16, v138, v16
	v_mul_f32_e32 v20, 0xbfb8aa3b, v16
	v_exp_f32_e32 v20, v20
	s_nop 0
	v_add_f32_e32 v20, 1.0, v20
	v_rcp_f32_e32 v20, v20
	s_nop 0
	v_mul_f32_e32 v129, v16, v20
	v_mov_b32_e32 v16, v37
	v_pk_mul_f32 v[36:37], v[124:125], v[16:17]
	s_nop 0
	v_add_f32_e32 v20, v37, v25
	v_add_f32_e32 v45, v36, v20
	v_mov_b32_e32 v20, v131
	v_pk_mul_f32 v[36:37], v[110:111], v[20:21]
	s_nop 0
	v_add_f32_e32 v37, v37, v45
	v_add_f32_e32 v36, v36, v37
	v_mul_f32_e32 v37, 0xbfb8aa3b, v36
	v_exp_f32_e32 v37, v37
	s_nop 0
	v_add_f32_e32 v37, 1.0, v37
	v_rcp_f32_e32 v37, v37
	s_nop 0
	v_mul_f32_e32 v125, v36, v37
	v_mov_b32_e32 v36, v38
	v_mov_b32_e32 v37, v18
	v_pk_mul_f32 v[130:131], v[120:121], v[36:37]
	s_nop 0
	v_add_f32_e32 v18, v131, v26
	v_add_f32_e32 v18, v130, v18
	v_mov_b32_e32 v130, v132
	v_mov_b32_e32 v131, v22
	v_pk_mul_f32 v[138:139], v[104:105], v[130:131]
	s_nop 0
	v_add_f32_e32 v18, v139, v18
	v_add_f32_e32 v18, v138, v18
	v_mul_f32_e32 v22, 0xbfb8aa3b, v18
	v_exp_f32_e32 v22, v22
	s_nop 0
	v_add_f32_e32 v22, 1.0, v22
	v_rcp_f32_e32 v22, v22
	s_nop 0
	v_mul_f32_e32 v121, v18, v22
	v_mov_b32_e32 v18, v39
	v_pk_mul_f32 v[38:39], v[118:119], v[18:19]
	s_nop 0
	v_add_f32_e32 v22, v39, v27
	v_add_f32_e32 v45, v38, v22
	v_mov_b32_e32 v22, v133
	v_pk_mul_f32 v[38:39], v[100:101], v[22:23]
	s_nop 0
	v_add_f32_e32 v39, v39, v45
	v_add_f32_e32 v38, v38, v39
	v_mul_f32_e32 v39, 0xbfb8aa3b, v38
	v_exp_f32_e32 v39, v39
	s_nop 0
	v_add_f32_e32 v39, 1.0, v39
	v_rcp_f32_e32 v39, v39
	s_nop 0
	v_mul_f32_e32 v119, v38, v39
	v_mov_b32_e32 v38, v28
	v_mov_b32_e32 v39, v4
	v_pk_mul_f32 v[132:133], v[116:117], v[38:39]
	s_nop 0
	v_add_f32_e32 v4, v133, v12
	v_add_f32_e32 v4, v132, v4
	v_mov_b32_e32 v132, v32
	v_mov_b32_e32 v133, v8
	v_pk_mul_f32 v[138:139], v[94:95], v[132:133]
	s_nop 0
	v_add_f32_e32 v4, v139, v4
	v_add_f32_e32 v4, v138, v4
	v_mul_f32_e32 v8, 0xbfb8aa3b, v4
	v_exp_f32_e32 v8, v8
	s_nop 0
	v_add_f32_e32 v8, 1.0, v8
	v_rcp_f32_e32 v8, v8
	s_nop 0
	v_mul_f32_e32 v117, v4, v8
	v_mov_b32_e32 v4, v29
	v_pk_mul_f32 v[28:29], v[114:115], v[4:5]
	s_nop 0
	v_add_f32_e32 v8, v29, v13
	v_add_f32_e32 v32, v28, v8
	v_mov_b32_e32 v8, v33
	v_pk_mul_f32 v[28:29], v[88:89], v[8:9]
	s_nop 0
	v_add_f32_e32 v29, v29, v32
	v_add_f32_e32 v28, v28, v29
	v_mul_f32_e32 v29, 0xbfb8aa3b, v28
	v_exp_f32_e32 v29, v29
	s_nop 0
	v_add_f32_e32 v29, 1.0, v29
	v_rcp_f32_e32 v29, v29
	s_nop 0
	v_mul_f32_e32 v115, v28, v29
	v_mov_b32_e32 v28, v30
	v_mov_b32_e32 v29, v6
	v_pk_mul_f32 v[32:33], v[108:109], v[28:29]
	s_nop 0
	v_add_f32_e32 v6, v33, v14
	v_add_f32_e32 v6, v32, v6
	v_mov_b32_e32 v32, v34
	v_mov_b32_e32 v33, v10
	v_pk_mul_f32 v[138:139], v[78:79], v[32:33]
	s_nop 0
	v_add_f32_e32 v6, v139, v6
	v_add_f32_e32 v6, v138, v6
	v_mul_f32_e32 v10, 0xbfb8aa3b, v6
	v_exp_f32_e32 v10, v10
	s_nop 0
	v_add_f32_e32 v10, 1.0, v10
	v_rcp_f32_e32 v10, v10
	s_nop 0
	v_mul_f32_e32 v30, v6, v10
	v_mov_b32_e32 v6, v31
	v_pk_mul_f32 v[138:139], v[98:99], v[6:7]
	s_nop 0
	v_add_f32_e32 v10, v139, v15
	v_add_f32_e32 v31, v138, v10
	v_mov_b32_e32 v10, v35
	v_pk_mul_f32 v[34:35], v[70:71], v[10:11]
	v_mov_b32_e32 v138, v111
	v_add_f32_e32 v31, v35, v31
	v_add_f32_e32 v31, v34, v31
	v_mul_f32_e32 v34, 0xbfb8aa3b, v31
	v_exp_f32_e32 v34, v34
	v_mov_b32_e32 v35, v128
	v_mov_b32_e32 v139, v124
	v_pk_mul_f32 v[138:139], v[138:139], v[16:17]
	v_add_f32_e32 v34, 1.0, v34
	v_rcp_f32_e32 v34, v34
	v_pk_mul_f32 v[110:111], v[110:111], v[16:17]
	v_pk_mul_f32 v[16:17], v[76:77], v[16:17]
	v_mul_f32_e32 v31, v31, v34
	v_mov_b32_e32 v34, v113
	v_pk_mul_f32 v[34:35], v[34:35], v[122:123]
	v_pk_mul_f32 v[112:113], v[112:113], v[122:123]
	v_add_f32_e32 v35, v35, v24
	v_add_f32_e32 v45, v34, v35
	v_pk_mul_f32 v[34:35], v[86:87], v[126:127]
	v_add_f32_e32 v17, v17, v25
	v_add_f32_e32 v35, v35, v45
	v_add_f32_e32 v34, v34, v35
	v_mul_f32_e32 v35, 0xbfb8aa3b, v34
	v_exp_f32_e32 v35, v35
	s_nop 0
	v_add_f32_e32 v35, 1.0, v35
	v_rcp_f32_e32 v35, v35
	s_nop 0
	v_mul_f32_e32 v34, v34, v35
	v_add_f32_e32 v35, v139, v25
	v_add_f32_e32 v35, v138, v35
	v_pk_mul_f32 v[138:139], v[76:77], v[20:21]
	s_nop 0
	v_add_f32_e32 v35, v139, v35
	v_add_f32_e32 v35, v138, v35
	v_mul_f32_e32 v45, 0xbfb8aa3b, v35
	v_exp_f32_e32 v45, v45
	v_mov_b32_e32 v138, v105
	v_mov_b32_e32 v139, v120
	v_pk_mul_f32 v[138:139], v[138:139], v[36:37]
	v_add_f32_e32 v45, 1.0, v45
	v_rcp_f32_e32 v45, v45
	v_pk_mul_f32 v[104:105], v[104:105], v[36:37]
	v_mul_f32_e32 v35, v35, v45
	v_add_f32_e32 v45, v139, v26
	v_add_f32_e32 v45, v138, v45
	v_pk_mul_f32 v[138:139], v[68:69], v[130:131]
	s_nop 0
	v_add_f32_e32 v45, v139, v45
	v_add_f32_e32 v45, v138, v45
	v_mul_f32_e32 v47, 0xbfb8aa3b, v45
	v_exp_f32_e32 v47, v47
	v_mov_b32_e32 v138, v101
	v_mov_b32_e32 v139, v118
	v_pk_mul_f32 v[138:139], v[138:139], v[18:19]
	v_add_f32_e32 v47, 1.0, v47
	v_rcp_f32_e32 v47, v47
	v_pk_mul_f32 v[100:101], v[100:101], v[18:19]
	v_mul_f32_e32 v99, v45, v47
	v_add_f32_e32 v45, v139, v27
	v_add_f32_e32 v45, v138, v45
	v_pk_mul_f32 v[138:139], v[60:61], v[22:23]
	s_nop 0
	v_add_f32_e32 v45, v139, v45
	v_add_f32_e32 v45, v138, v45
	v_mul_f32_e32 v47, 0xbfb8aa3b, v45
	v_exp_f32_e32 v47, v47
	v_mov_b32_e32 v138, v95
	v_mov_b32_e32 v139, v116
	v_pk_mul_f32 v[138:139], v[138:139], v[38:39]
	v_add_f32_e32 v47, 1.0, v47
	v_rcp_f32_e32 v47, v47
	v_pk_mul_f32 v[94:95], v[94:95], v[38:39]
	v_mul_f32_e32 v109, v45, v47
	v_add_f32_e32 v45, v139, v12
	v_add_f32_e32 v45, v138, v45
	v_pk_mul_f32 v[138:139], v[54:55], v[132:133]
	s_nop 0
	v_add_f32_e32 v45, v139, v45
	v_add_f32_e32 v45, v138, v45
	v_mul_f32_e32 v47, 0xbfb8aa3b, v45
	v_exp_f32_e32 v47, v47
	v_mov_b32_e32 v138, v89
	v_mov_b32_e32 v139, v114
	v_pk_mul_f32 v[138:139], v[138:139], v[4:5]
	v_add_f32_e32 v47, 1.0, v47
	v_rcp_f32_e32 v47, v47
	v_pk_mul_f32 v[88:89], v[88:89], v[4:5]
	v_pk_mul_f32 v[4:5], v[50:51], v[4:5]
	v_mul_f32_e32 v116, v45, v47
	v_add_f32_e32 v45, v139, v13
	v_add_f32_e32 v45, v138, v45
	v_pk_mul_f32 v[138:139], v[50:51], v[8:9]
	v_add_f32_e32 v5, v5, v13
	v_add_f32_e32 v45, v139, v45
	v_add_f32_e32 v45, v138, v45
	v_mul_f32_e32 v47, 0xbfb8aa3b, v45
	v_exp_f32_e32 v47, v47
	v_mov_b32_e32 v138, v79
	v_mov_b32_e32 v139, v108
	v_pk_mul_f32 v[138:139], v[138:139], v[28:29]
	v_add_f32_e32 v47, 1.0, v47
	v_rcp_f32_e32 v47, v47
	s_nop 0
	v_mul_f32_e32 v114, v45, v47
	v_add_f32_e32 v45, v139, v14
	v_mov_b32_e32 v47, v78
	v_add_f32_e32 v45, v138, v45
	v_pk_mul_f32 v[138:139], v[46:47], v[32:33]
	v_pk_mul_f32 v[78:79], v[78:79], v[28:29]
	v_add_f32_e32 v45, v139, v45
	v_add_f32_e32 v45, v138, v45
	v_mul_f32_e32 v49, 0xbfb8aa3b, v45
	v_exp_f32_e32 v49, v49
	v_mov_b32_e32 v138, v71
	v_mov_b32_e32 v139, v98
	v_pk_mul_f32 v[138:139], v[138:139], v[6:7]
	v_add_f32_e32 v49, 1.0, v49
	v_rcp_f32_e32 v49, v49
	s_nop 0
	v_mul_f32_e32 v108, v45, v49
	v_add_f32_e32 v45, v139, v15
	v_add_f32_e32 v49, v138, v45
	v_mov_b32_e32 v45, v70
	v_pk_mul_f32 v[138:139], v[44:45], v[10:11]
	v_pk_mul_f32 v[70:71], v[70:71], v[6:7]
	v_add_f32_e32 v49, v139, v49
	v_add_f32_e32 v49, v138, v49
	v_mul_f32_e32 v53, 0xbfb8aa3b, v49
	v_exp_f32_e32 v53, v53
	s_nop 0
	v_add_f32_e32 v53, 1.0, v53
	v_rcp_f32_e32 v53, v53
	s_nop 0
	v_mul_f32_e32 v98, v49, v53
	v_add_f32_e32 v49, v113, v24
	v_add_f32_e32 v49, v112, v49
	v_pk_mul_f32 v[112:113], v[84:85], v[126:127]
	s_nop 0
	v_add_f32_e32 v49, v113, v49
	v_add_f32_e32 v49, v112, v49
	v_mul_f32_e32 v53, 0xbfb8aa3b, v49
	v_exp_f32_e32 v53, v53
	v_mov_b32_e32 v113, 0
	v_add_f32_e32 v53, 1.0, v53
	v_rcp_f32_e32 v53, v53
	s_nop 0
	v_mul_f32_e32 v85, v49, v53
	v_add_f32_e32 v49, v111, v25
	v_add_f32_e32 v49, v110, v49
	v_pk_mul_f32 v[110:111], v[92:93], v[20:21]
	v_add_f32_e32 v25, v16, v17
	v_add_f32_e32 v49, v111, v49
	v_add_f32_e32 v49, v110, v49
	v_mul_f32_e32 v53, 0xbfb8aa3b, v49
	v_exp_f32_e32 v53, v53
	v_pk_mul_f32 v[16:17], v[102:103], v[20:21]
	v_add_f32_e32 v53, 1.0, v53
	v_rcp_f32_e32 v53, v53
	v_add_f32_e32 v17, v17, v25
	v_add_f32_e32 v16, v16, v17
	v_mul_f32_e32 v17, 0xbfb8aa3b, v16
	v_mul_f32_e32 v93, v49, v53
	v_add_f32_e32 v49, v105, v26
	v_add_f32_e32 v49, v104, v49
	v_pk_mul_f32 v[104:105], v[82:83], v[130:131]
	v_exp_f32_e32 v17, v17
	v_add_f32_e32 v49, v105, v49
	v_add_f32_e32 v49, v104, v49
	v_mul_f32_e32 v53, 0xbfb8aa3b, v49
	v_exp_f32_e32 v53, v53
	v_add_f32_e32 v17, 1.0, v17
	v_rcp_f32_e32 v17, v17
	v_add_f32_e32 v53, 1.0, v53
	v_rcp_f32_e32 v53, v53
	v_mul_f32_e32 v20, v16, v17
	v_pk_mul_f32 v[16:17], v[68:69], v[36:37]
	v_mul_f32_e32 v83, v49, v53
	v_add_f32_e32 v49, v101, v27
	v_add_f32_e32 v49, v100, v49
	v_pk_mul_f32 v[100:101], v[74:75], v[22:23]
	v_add_f32_e32 v17, v17, v26
	v_add_f32_e32 v49, v101, v49
	v_add_f32_e32 v49, v100, v49
	v_mul_f32_e32 v53, 0xbfb8aa3b, v49
	v_exp_f32_e32 v53, v53
	v_add_f32_e32 v21, v16, v17
	v_pk_mul_f32 v[16:17], v[96:97], v[130:131]
	v_add_f32_e32 v53, 1.0, v53
	v_rcp_f32_e32 v53, v53
	v_add_f32_e32 v17, v17, v21
	v_add_f32_e32 v16, v16, v17
	v_mul_f32_e32 v17, 0xbfb8aa3b, v16
	v_mul_f32_e32 v75, v49, v53
	v_add_f32_e32 v49, v95, v12
	v_add_f32_e32 v49, v94, v49
	v_pk_mul_f32 v[94:95], v[64:65], v[132:133]
	v_exp_f32_e32 v17, v17
	v_add_f32_e32 v49, v95, v49
	v_add_f32_e32 v49, v94, v49
	v_mul_f32_e32 v53, 0xbfb8aa3b, v49
	v_exp_f32_e32 v53, v53
	v_add_f32_e32 v17, 1.0, v17
	v_rcp_f32_e32 v17, v17
	v_add_f32_e32 v53, 1.0, v53
	v_rcp_f32_e32 v53, v53
	v_mul_f32_e32 v21, v16, v17
	v_pk_mul_f32 v[16:17], v[60:61], v[18:19]
	v_mul_f32_e32 v65, v49, v53
	v_add_f32_e32 v49, v89, v13
	v_add_f32_e32 v49, v88, v49
	v_pk_mul_f32 v[88:89], v[58:59], v[8:9]
	v_add_f32_e32 v13, v4, v5
	v_add_f32_e32 v49, v89, v49
	v_add_f32_e32 v49, v88, v49
	v_mul_f32_e32 v53, 0xbfb8aa3b, v49
	v_exp_f32_e32 v53, v53
	v_pk_mul_f32 v[4:5], v[72:73], v[8:9]
	v_add_f32_e32 v17, v17, v27
	v_add_f32_e32 v5, v5, v13
	v_add_f32_e32 v53, 1.0, v53
	v_rcp_f32_e32 v53, v53
	v_add_f32_e32 v4, v4, v5
	v_mul_f32_e32 v5, 0xbfb8aa3b, v4
	v_exp_f32_e32 v5, v5
	v_mul_f32_e32 v59, v49, v53
	v_add_f32_e32 v49, v79, v14
	v_mov_b32_e32 v53, v46
	v_add_f32_e32 v49, v78, v49
	v_pk_mul_f32 v[78:79], v[52:53], v[32:33]
	v_add_f32_e32 v5, 1.0, v5
	v_add_f32_e32 v49, v79, v49
	v_add_f32_e32 v49, v78, v49
	v_mul_f32_e32 v53, 0xbfb8aa3b, v49
	v_exp_f32_e32 v53, v53
	v_rcp_f32_e32 v5, v5
	v_add_f32_e32 v18, v16, v17
	v_pk_mul_f32 v[16:17], v[90:91], v[22:23]
	v_add_f32_e32 v53, 1.0, v53
	v_rcp_f32_e32 v53, v53
	v_mul_f32_e32 v8, v4, v5
	v_pk_mul_f32 v[4:5], v[46:47], v[28:29]
	v_add_f32_e32 v17, v17, v18
	v_mul_f32_e32 v53, v49, v53
	v_add_f32_e32 v49, v71, v15
	v_add_f32_e32 v57, v70, v49
	v_mov_b32_e32 v49, v44
	v_pk_mul_f32 v[70:71], v[48:49], v[10:11]
	v_add_f32_e32 v5, v5, v14
	v_add_f32_e32 v49, v71, v57
	v_add_f32_e32 v49, v70, v49
	v_mul_f32_e32 v57, 0xbfb8aa3b, v49
	v_exp_f32_e32 v57, v57
	v_pk_mul_f32 v[70:71], v[86:87], v[122:123]
	v_add_f32_e32 v9, v4, v5
	v_add_f32_e32 v24, v71, v24
	v_add_f32_e32 v57, 1.0, v57
	v_rcp_f32_e32 v57, v57
	v_pk_mul_f32 v[4:5], v[62:63], v[32:33]
	v_add_f32_e32 v24, v70, v24
	v_pk_mul_f32 v[70:71], v[106:107], v[126:127]
	v_add_f32_e32 v5, v5, v9
	v_add_f32_e32 v24, v71, v24
	v_add_f32_e32 v4, v4, v5
	v_add_f32_e32 v24, v70, v24
	v_mul_f32_e32 v5, 0xbfb8aa3b, v4
	v_mul_f32_e32 v49, v49, v57
	v_mul_f32_e32 v57, 0xbfb8aa3b, v24
	v_add_f32_e32 v16, v16, v17
	v_exp_f32_e32 v5, v5
	v_exp_f32_e32 v57, v57
	v_mul_f32_e32 v17, 0xbfb8aa3b, v16
	v_exp_f32_e32 v17, v17
	v_add_f32_e32 v5, 1.0, v5
	v_add_f32_e32 v57, 1.0, v57
	v_rcp_f32_e32 v5, v5
	v_rcp_f32_e32 v57, v57
	v_add_f32_e32 v17, 1.0, v17
	v_rcp_f32_e32 v17, v17
	v_mul_f32_e32 v9, v4, v5
	v_pk_mul_f32 v[4:5], v[44:45], v[6:7]
	v_mul_f32_e32 v24, v24, v57
	v_add_f32_e32 v5, v5, v15
	v_mov_b32_e32 v57, v48
	v_mul_f32_e32 v18, v16, v17
	v_pk_mul_f32 v[16:17], v[54:55], v[38:39]
	v_add_f32_e32 v6, v4, v5
	v_pk_mul_f32 v[4:5], v[56:57], v[10:11]
	v_add_f32_e32 v12, v17, v12
	v_add_f32_e32 v5, v5, v6
	v_add_f32_e32 v12, v16, v12
	v_pk_mul_f32 v[16:17], v[80:81], v[132:133]
	v_add_f32_e32 v4, v4, v5
	v_add_f32_e32 v12, v17, v12
	v_mul_f32_e32 v5, 0xbfb8aa3b, v4
	v_add_f32_e32 v12, v16, v12
	v_exp_f32_e32 v5, v5
	v_mul_f32_e32 v16, 0xbfb8aa3b, v12
	v_exp_f32_e32 v16, v16
	v_lshl_add_u32 v11, v135, 1, 0
	v_add_f32_e32 v5, 1.0, v5
	v_rcp_f32_e32 v5, v5
	v_add_f32_e32 v16, 1.0, v16
	v_rcp_f32_e32 v16, v16
	v_mul_lo_u32 v13, v40, s55
	v_cvt_pk_bf16_f32 v6, v117, v115
	v_add_u32_e32 v130, v11, v13
	v_mul_f32_e32 v10, v4, v5
	v_cvt_pk_bf16_f32 v4, v129, v125
	v_cvt_pk_bf16_f32 v5, v121, v119
	v_cvt_pk_bf16_f32 v7, v30, v31
	ds_write_b128 v130, v[4:7] offset:34816
	v_cvt_pk_bf16_f32 v6, v116, v114
	v_or_b32_e32 v13, 3, v136
	v_cvt_pk_bf16_f32 v4, v34, v35
	v_cvt_pk_bf16_f32 v5, v99, v109
	v_cvt_pk_bf16_f32 v7, v108, v98
	ds_write_b128 v130, v[4:7] offset:35088
	v_cvt_pk_bf16_f32 v6, v65, v59
	v_mul_lo_u32 v13, v13, s55
	v_mul_f32_e32 v12, v12, v16
	v_cvt_pk_bf16_f32 v4, v85, v93
	v_cvt_pk_bf16_f32 v5, v83, v75
	v_cvt_pk_bf16_f32 v7, v53, v49
	ds_write_b128 v130, v[4:7] offset:35360
	v_cvt_pk_bf16_f32 v6, v12, v8
	v_add_u32_e32 v131, v11, v13
	v_cvt_pk_bf16_f32 v4, v24, v20
	v_cvt_pk_bf16_f32 v5, v21, v18
	v_cvt_pk_bf16_f32 v7, v9, v10
	ds_write_b128 v131, v[4:7] offset:34816
	v_mul_u32_u24_e32 v6, 0x110, v135
	v_add3_u32 v11, s52, v137, v6
	v_cvt_pk_bf16_f32 v6, v125, v35
	v_cvt_pk_bf16_f32 v4, v129, v34
	v_cvt_pk_bf16_f32 v5, v85, v24
	v_cvt_pk_bf16_f32 v7, v93, v20
	ds_write2_b64 v11, v[4:5], v[6:7] offset1:34
	v_cvt_pk_bf16_f32 v6, v119, v109
	v_cvt_pk_bf16_f32 v4, v121, v99
	v_cvt_pk_bf16_f32 v5, v83, v21
	v_cvt_pk_bf16_f32 v7, v75, v18
	ds_write2_b64 v11, v[4:5], v[6:7] offset0:68 offset1:102
	v_cvt_pk_bf16_f32 v6, v115, v114
	v_cvt_pk_bf16_f32 v4, v117, v116
	v_cvt_pk_bf16_f32 v5, v65, v12
	v_cvt_pk_bf16_f32 v7, v59, v8
	ds_write2_b64 v11, v[4:5], v[6:7] offset0:136 offset1:170
	v_cvt_pk_bf16_f32 v6, v31, v98
	v_cvt_pk_bf16_f32 v4, v30, v108
	v_cvt_pk_bf16_f32 v5, v53, v9
	v_cvt_pk_bf16_f32 v7, v49, v10
	ds_write2_b64 v11, v[4:5], v[6:7] offset0:204 offset1:238
	v_or_b32_e32 v6, 0x500, v67
	v_lshlrev_b32_e32 v4, 1, v6
	v_mov_b32_e32 v109, 0
	v_mov_b32_e32 v115, 0
	v_mov_b32_e32 v117, 0
	v_mov_b32_e32 v119, 0
	v_mov_b32_e32 v121, 0
	v_mov_b32_e32 v125, 0
	v_mov_b32_e32 v244, 0
	v_mov_b32_e32 v245, 0
	v_mov_b32_e32 v246, 0
	v_mov_b32_e32 v247, 0
	s_and_saveexec_b64 s[2:3], s[0:1]
	s_cbranch_execz .LBB0_230
	v_mov_b32_e32 v5, v2
	v_lshl_add_u64 v[8:9], v[42:43], 0, v[4:5]
	v_add_co_u32_e32 v8, vcc, 0xffffa000, v8
	s_nop 1
	v_addc_co_u32_e32 v9, vcc, -1, v9, vcc
	global_load_dwordx4 v[244:247], v[8:9], off offset:-3072

.LBB0_234:
	s_or_b64 exec, exec, s[0:1]
	v_mov_b32_e32 v72, 0
	v_mov_b32_e32 v106, 0
	v_mov_b32_e32 v110, 0
	v_mov_b32_e32 v104, 0
	v_mov_b32_e32 v100, 0
	v_mov_b32_e32 v92, 0
	v_mov_b32_e32 v86, 0
	v_mov_b32_e32 v80, 0
	v_mov_b32_e32 v70, 0
	v_mov_b32_e32 v188, 0
	v_mov_b32_e32 v189, 0
	v_mov_b32_e32 v190, 0
	v_mov_b32_e32 v191, 0
	s_and_saveexec_b64 s[0:1], s[6:7]
	s_cbranch_execz .LBB0_236
	v_mov_b32_e32 v5, v2
	v_lshl_add_u64 v[8:9], v[42:43], 0, v[4:5]
	global_load_dwordx4 v[188:191], v[8:9], off
.LBB0_236:
	s_or_b64 exec, exec, s[0:1]
	v_mov_b32_e32 v78, 0
	v_mov_b32_e32 v68, 0
	v_mov_b32_e32 v60, 0
	v_mov_b32_e32 v54, 0
	v_mov_b32_e32 v50, 0
	v_mov_b32_e32 v46, 0
	v_mov_b32_e32 v44, 0
	v_mov_b32_e32 v192, 0
	v_mov_b32_e32 v193, 0
	v_mov_b32_e32 v194, 0
	v_mov_b32_e32 v195, 0
	s_and_saveexec_b64 s[0:1], s[8:9]
	s_cbranch_execz .LBB0_238
	v_mov_b32_e32 v5, v2
	v_lshl_add_u64 v[8:9], v[42:43], 0, v[4:5]
	v_add_co_u32_e32 v8, vcc, 0x2000, v8
	s_nop 1
	v_addc_co_u32_e32 v9, vcc, 0, v9, vcc
	global_load_dwordx4 v[192:195], v[8:9], off offset:1024
.LBB0_238:
	s_or_b64 exec, exec, s[0:1]
	v_mov_b32_e32 v96, 0
	v_mov_b32_e32 v98, 0
	v_mov_b32_e32 v90, 0
	v_mov_b32_e32 v84, 0
	v_mov_b32_e32 v76, 0
	v_mov_b32_e32 v64, 0
	v_mov_b32_e32 v58, 0
	v_mov_b32_e32 v52, 0
	v_mov_b32_e32 v48, 0
	v_mov_b32_e32 v196, 0
	v_mov_b32_e32 v197, 0
	v_mov_b32_e32 v198, 0
	v_mov_b32_e32 v199, 0
	s_and_saveexec_b64 s[0:1], s[10:11]
	s_cbranch_execz .LBB0_240
	v_mov_b32_e32 v5, v2
	v_lshl_add_u64 v[8:9], v[42:43], 0, v[4:5]
	v_add_co_u32_e32 v8, vcc, 0x4000, v8
	s_nop 1
	v_addc_co_u32_e32 v9, vcc, 0, v9, vcc
	global_load_dwordx4 v[196:199], v[8:9], off offset:2048
.LBB0_240:
	s_or_b64 exec, exec, s[0:1]
	v_mov_b32_e32 v102, 0
	v_mov_b32_e32 v94, 0
	v_mov_b32_e32 v88, 0
	v_mov_b32_e32 v82, 0
	v_mov_b32_e32 v74, 0
	v_mov_b32_e32 v62, 0
	v_mov_b32_e32 v56, 0
	v_mov_b32_e32 v200, 0
	v_mov_b32_e32 v201, 0
	v_mov_b32_e32 v202, 0
	v_mov_b32_e32 v203, 0
	s_and_saveexec_b64 s[0:1], s[12:13]
	s_cbranch_execz .LBB0_242
	v_mov_b32_e32 v5, v2
	v_lshl_add_u64 v[4:5], v[42:43], 0, v[4:5]
	v_add_co_u32_e32 v4, vcc, 0x6000, v4
	s_nop 1
	v_addc_co_u32_e32 v5, vcc, 0, v5, vcc
	global_load_dwordx4 v[200:203], v[4:5], off offset:3072
.LBB0_242:
	s_or_b64 exec, exec, s[0:1]
	s_waitcnt vmcnt(0)
	v_lshlrev_b32_e32 v125, 16, v244
	v_and_b32_e32 v121, 0xffff0000, v244
	v_lshlrev_b32_e32 v119, 16, v245
	v_and_b32_e32 v117, 0xffff0000, v245
	v_lshlrev_b32_e32 v115, 16, v246
	v_and_b32_e32 v113, 0xffff0000, v246
	v_lshlrev_b32_e32 v109, 16, v247
	v_and_b32_e32 v41, 0xffff0000, v247
	v_lshlrev_b32_e32 v124, 16, v248
	v_and_b32_e32 v120, 0xffff0000, v248
	v_lshlrev_b32_e32 v118, 16, v249
	v_and_b32_e32 v116, 0xffff0000, v249
	v_lshlrev_b32_e32 v114, 16, v250
	v_and_b32_e32 v112, 0xffff0000, v250
	v_lshlrev_b32_e32 v108, 16, v251
	v_and_b32_e32 v40, 0xffff0000, v251
	v_lshlrev_b32_e32 v107, 16, v252
	v_and_b32_e32 v111, 0xffff0000, v252
	v_lshlrev_b32_e32 v105, 16, v253
	v_and_b32_e32 v101, 0xffff0000, v253
	v_lshlrev_b32_e32 v93, 16, v254
	v_and_b32_e32 v87, 0xffff0000, v254
	v_lshlrev_b32_e32 v81, 16, v255
	v_and_b32_e32 v71, 0xffff0000, v255
	v_lshlrev_b32_e32 v106, 16, v188
	v_and_b32_e32 v110, 0xffff0000, v188
	v_lshlrev_b32_e32 v104, 16, v189
	v_and_b32_e32 v100, 0xffff0000, v189
	v_lshlrev_b32_e32 v92, 16, v190
	v_and_b32_e32 v86, 0xffff0000, v190
	v_lshlrev_b32_e32 v80, 16, v191
	v_and_b32_e32 v70, 0xffff0000, v191
	v_lshlrev_b32_e32 v72, 16, v192
	v_and_b32_e32 v78, 0xffff0000, v192
	v_lshlrev_b32_e32 v68, 16, v193
	v_and_b32_e32 v60, 0xffff0000, v193
	v_lshlrev_b32_e32 v54, 16, v194
	v_and_b32_e32 v50, 0xffff0000, v194
	v_lshlrev_b32_e32 v46, 16, v195
	v_and_b32_e32 v44, 0xffff0000, v195
	v_lshlrev_b32_e32 v98, 16, v196
	v_and_b32_e32 v90, 0xffff0000, v196
	v_lshlrev_b32_e32 v84, 16, v197
	v_and_b32_e32 v76, 0xffff0000, v197
	v_lshlrev_b32_e32 v64, 16, v198
	v_and_b32_e32 v58, 0xffff0000, v198
	v_lshlrev_b32_e32 v52, 16, v199
	v_and_b32_e32 v48, 0xffff0000, v199
	v_lshlrev_b32_e32 v96, 16, v200
	v_and_b32_e32 v102, 0xffff0000, v200
	v_lshlrev_b32_e32 v94, 16, v201
	v_and_b32_e32 v88, 0xffff0000, v201
	v_lshlrev_b32_e32 v82, 16, v202
	v_and_b32_e32 v74, 0xffff0000, v202
	v_lshlrev_b32_e32 v62, 16, v203
	v_and_b32_e32 v56, 0xffff0000, v203
	v_readlane_b32 s0, v242, 2
	v_lshlrev_b32_e32 v24, 2, v6
	v_mov_b32_e32 v25, v2
	v_readlane_b32 s4, v242, 6
	v_readlane_b32 s5, v242, 7
	v_readlane_b32 s1, v242, 3
	s_mov_b64 s[0:1], 0x1800
	v_lshl_add_u64 v[12:13], s[4:5], 0, v[24:25]
	v_add_co_u32_e32 v10, vcc, s34, v12
	v_lshl_add_u64 v[8:9], v[12:13], 0, s[0:1]
	s_nop 0
	v_addc_co_u32_e32 v11, vcc, 0, v13, vcc
	s_mov_b64 s[0:1], 0x3000
	global_load_dwordx4 v[4:7], v24, s[4:5] offset:16
	global_load_dwordx4 v[16:19], v24, s[4:5]
	global_load_dwordx4 v[36:39], v[10:11], off offset:2048
	global_load_dwordx4 v[28:31], v[8:9], off offset:16
	v_lshl_add_u64 v[8:9], v[12:13], 0, s[0:1]
	s_movk_i32 s0, 0x3000
	v_add_co_u32_e32 v10, vcc, s0, v12
	s_mov_b64 s[0:1], 0x4800
	s_nop 0
	v_addc_co_u32_e32 v11, vcc, 0, v13, vcc
	v_lshl_add_u64 v[14:15], v[12:13], 0, s[0:1]
	v_add_co_u32_e32 v12, vcc, s35, v12
	v_readlane_b32 s6, v242, 8
	s_nop 0
	v_addc_co_u32_e32 v13, vcc, 0, v13, vcc
	v_readlane_b32 s7, v242, 9
	global_load_dwordx4 v[20:23], v[10:11], off
	s_nop 0
	global_load_dwordx4 v[8:11], v[8:9], off offset:16
	s_nop 0
	global_load_dwordx4 v[126:129], v[12:13], off offset:2048
	global_load_dwordx4 v[32:35], v[14:15], off offset:16
	s_nop 0
	global_load_dwordx4 v[12:15], v24, s[6:7] offset:16
	s_nop 0
	global_load_dwordx4 v[24:27], v24, s[6:7]
	v_mov_b32_e32 v73, v106
	v_mov_b32_e32 v79, v110
	v_mov_b32_e32 v69, v104
	v_mov_b32_e32 v61, v100
	v_mov_b32_e32 v55, v92
	v_mov_b32_e32 v51, v86
	v_mov_b32_e32 v99, v72
	v_mov_b32_e32 v91, v78
	v_mov_b32_e32 v85, v68
	v_mov_b32_e32 v77, v60
	v_mov_b32_e32 v65, v54
	v_mov_b32_e32 v103, v90
	v_mov_b32_e32 v59, v50
	v_mov_b32_e32 v75, v58
	v_mov_b32_e32 v95, v84
	v_mov_b32_e32 v63, v52
	v_mov_b32_e32 v89, v76
	v_mov_b32_e32 v83, v64
	v_mov_b32_e32 v97, v98
	v_and_b32_e32 v67, 15, v66
	s_movk_i32 s0, 0x100
	v_cmp_gt_i32_e64 s[90:91], s0, v66
	s_movk_i32 s0, 0xff
	v_cmp_lt_i32_e32 vcc, s0, v66
	v_readlane_b32 s2, v242, 4
	v_readlane_b32 s3, v242, 5
	v_readlane_b32 s8, v242, 10
	v_readlane_b32 s9, v242, 11
	v_readlane_b32 s10, v242, 12
	v_readlane_b32 s11, v242, 13
	v_readlane_b32 s12, v242, 14
	v_readlane_b32 s13, v242, 15
	v_readlane_b32 s14, v242, 16
	v_readlane_b32 s15, v242, 17
	s_waitcnt vmcnt(8)
	v_mov_b32_e32 v43, v16
	s_waitcnt vmcnt(7)
	v_mov_b32_e32 v42, v36
	v_pk_mul_f32 v[122:123], v[124:125], v[42:43]
	s_waitcnt vmcnt(0)
	v_add_f32_e32 v16, v123, v24
	v_add_f32_e32 v16, v122, v16
	v_mov_b32_e32 v122, v126
	v_mov_b32_e32 v123, v20
	v_pk_mul_f32 v[132:133], v[106:107], v[122:123]
	s_nop 0
	v_add_f32_e32 v16, v133, v16
	v_add_f32_e32 v16, v132, v16
	v_mul_f32_e32 v20, 0xbfb8aa3b, v16
	v_exp_f32_e32 v20, v20
	s_nop 0
	v_add_f32_e32 v20, 1.0, v20
	v_rcp_f32_e32 v20, v20
	s_nop 0
	v_mul_f32_e32 v125, v16, v20
	v_mov_b32_e32 v16, v37
	v_pk_mul_f32 v[36:37], v[120:121], v[16:17]
	s_nop 0
	v_add_f32_e32 v20, v37, v25
	v_add_f32_e32 v45, v36, v20
	v_mov_b32_e32 v20, v127
	v_pk_mul_f32 v[36:37], v[110:111], v[20:21]
	s_nop 0
	v_add_f32_e32 v37, v37, v45
	v_add_f32_e32 v36, v36, v37
	v_mul_f32_e32 v37, 0xbfb8aa3b, v36
	v_exp_f32_e32 v37, v37
	s_nop 0
	v_add_f32_e32 v37, 1.0, v37
	v_rcp_f32_e32 v37, v37
	s_nop 0
	v_mul_f32_e32 v121, v36, v37
	v_mov_b32_e32 v36, v38
	v_mov_b32_e32 v37, v18
	v_pk_mul_f32 v[126:127], v[118:119], v[36:37]
	s_nop 0
	v_add_f32_e32 v18, v127, v26
	v_add_f32_e32 v18, v126, v18
	v_mov_b32_e32 v126, v128
	v_mov_b32_e32 v127, v22
	v_pk_mul_f32 v[132:133], v[104:105], v[126:127]
	s_nop 0
	v_add_f32_e32 v18, v133, v18
	v_add_f32_e32 v18, v132, v18
	v_mul_f32_e32 v22, 0xbfb8aa3b, v18
	v_exp_f32_e32 v22, v22
	s_nop 0
	v_add_f32_e32 v22, 1.0, v22
	v_rcp_f32_e32 v22, v22
	s_nop 0
	v_mul_f32_e32 v119, v18, v22
	v_mov_b32_e32 v18, v39
	v_pk_mul_f32 v[38:39], v[116:117], v[18:19]
	s_nop 0
	v_add_f32_e32 v22, v39, v27
	v_add_f32_e32 v45, v38, v22
	v_mov_b32_e32 v22, v129
	v_pk_mul_f32 v[38:39], v[100:101], v[22:23]
	s_nop 0
	v_add_f32_e32 v39, v39, v45
	v_add_f32_e32 v38, v38, v39
	v_mul_f32_e32 v39, 0xbfb8aa3b, v38
	v_exp_f32_e32 v39, v39
	s_nop 0
	v_add_f32_e32 v39, 1.0, v39
	v_rcp_f32_e32 v39, v39
	s_nop 0
	v_mul_f32_e32 v117, v38, v39
	v_mov_b32_e32 v38, v28
	v_mov_b32_e32 v39, v4
	v_pk_mul_f32 v[128:129], v[114:115], v[38:39]
	s_nop 0
	v_add_f32_e32 v4, v129, v12
	v_add_f32_e32 v4, v128, v4
	v_mov_b32_e32 v128, v32
	v_mov_b32_e32 v129, v8
	v_pk_mul_f32 v[132:133], v[92:93], v[128:129]
	s_nop 0
	v_add_f32_e32 v4, v133, v4
	v_add_f32_e32 v4, v132, v4
	v_mul_f32_e32 v8, 0xbfb8aa3b, v4
	v_exp_f32_e32 v8, v8
	s_nop 0
	v_add_f32_e32 v8, 1.0, v8
	v_rcp_f32_e32 v8, v8
	s_nop 0
	v_mul_f32_e32 v115, v4, v8
	v_mov_b32_e32 v4, v29
	v_pk_mul_f32 v[28:29], v[112:113], v[4:5]
	s_nop 0
	v_add_f32_e32 v8, v29, v13
	v_add_f32_e32 v32, v28, v8
	v_mov_b32_e32 v8, v33
	v_pk_mul_f32 v[28:29], v[86:87], v[8:9]
	s_nop 0
	v_add_f32_e32 v29, v29, v32
	v_add_f32_e32 v28, v28, v29
	v_mul_f32_e32 v29, 0xbfb8aa3b, v28
	v_exp_f32_e32 v29, v29
	s_nop 0
	v_add_f32_e32 v29, 1.0, v29
	v_rcp_f32_e32 v29, v29
	s_nop 0
	v_mul_f32_e32 v113, v28, v29
	v_mov_b32_e32 v28, v30
	v_mov_b32_e32 v29, v6
	v_pk_mul_f32 v[32:33], v[108:109], v[28:29]
	s_nop 0
	v_add_f32_e32 v6, v33, v14
	v_add_f32_e32 v6, v32, v6
	v_mov_b32_e32 v32, v34
	v_mov_b32_e32 v33, v10
	v_pk_mul_f32 v[132:133], v[80:81], v[32:33]
	s_nop 0
	v_add_f32_e32 v6, v133, v6
	v_add_f32_e32 v6, v132, v6
	v_mul_f32_e32 v10, 0xbfb8aa3b, v6
	v_exp_f32_e32 v10, v10
	s_nop 0
	v_add_f32_e32 v10, 1.0, v10
	v_rcp_f32_e32 v10, v10
	s_nop 0
	v_mul_f32_e32 v30, v6, v10
	v_mov_b32_e32 v6, v31
	v_pk_mul_f32 v[132:133], v[40:41], v[6:7]
	s_nop 0
	v_add_f32_e32 v10, v133, v15
	v_add_f32_e32 v31, v132, v10
	v_mov_b32_e32 v10, v35
	v_pk_mul_f32 v[34:35], v[70:71], v[10:11]
	v_mov_b32_e32 v132, v111
	v_add_f32_e32 v31, v35, v31
	v_add_f32_e32 v31, v34, v31
	v_mul_f32_e32 v34, 0xbfb8aa3b, v31
	v_exp_f32_e32 v34, v34
	v_mov_b32_e32 v35, v124
	v_mov_b32_e32 v133, v120
	v_pk_mul_f32 v[132:133], v[132:133], v[16:17]
	v_add_f32_e32 v34, 1.0, v34
	v_rcp_f32_e32 v34, v34
	s_nop 0
	v_mul_f32_e32 v31, v31, v34
	v_mov_b32_e32 v34, v107
	v_pk_mul_f32 v[34:35], v[34:35], v[42:43]
	v_pk_mul_f32 v[106:107], v[106:107], v[42:43]
	v_add_f32_e32 v35, v35, v24
	v_add_f32_e32 v41, v34, v35
	v_pk_mul_f32 v[34:35], v[72:73], v[122:123]
	v_pk_mul_f32 v[42:43], v[72:73], v[42:43]
	v_add_f32_e32 v35, v35, v41
	v_add_f32_e32 v34, v34, v35
	v_mul_f32_e32 v35, 0xbfb8aa3b, v34
	v_exp_f32_e32 v35, v35
	s_nop 0
	v_add_f32_e32 v35, 1.0, v35
	v_rcp_f32_e32 v35, v35
	s_nop 0
	v_mul_f32_e32 v34, v34, v35
	v_add_f32_e32 v35, v133, v25
	v_add_f32_e32 v35, v132, v35
	v_pk_mul_f32 v[132:133], v[78:79], v[20:21]
	s_nop 0
	v_add_f32_e32 v35, v133, v35
	v_add_f32_e32 v35, v132, v35
	v_mul_f32_e32 v41, 0xbfb8aa3b, v35
	v_exp_f32_e32 v41, v41
	v_mov_b32_e32 v132, v105
	v_mov_b32_e32 v133, v118
	v_pk_mul_f32 v[132:133], v[132:133], v[36:37]
	v_add_f32_e32 v41, 1.0, v41
	v_rcp_f32_e32 v41, v41
	v_pk_mul_f32 v[104:105], v[104:105], v[36:37]
	v_mul_f32_e32 v35, v35, v41
	v_add_f32_e32 v41, v133, v26
	v_add_f32_e32 v41, v132, v41
	v_pk_mul_f32 v[132:133], v[68:69], v[126:127]
	s_nop 0
	v_add_f32_e32 v41, v133, v41
	v_add_f32_e32 v41, v132, v41
	v_mul_f32_e32 v45, 0xbfb8aa3b, v41
	v_exp_f32_e32 v45, v45
	v_mov_b32_e32 v132, v101
	v_mov_b32_e32 v133, v116
	v_pk_mul_f32 v[132:133], v[132:133], v[18:19]
	v_add_f32_e32 v45, 1.0, v45
	v_rcp_f32_e32 v45, v45
	v_pk_mul_f32 v[100:101], v[100:101], v[18:19]
	v_mul_f32_e32 v41, v41, v45
	v_add_f32_e32 v45, v133, v27
	v_add_f32_e32 v45, v132, v45
	v_pk_mul_f32 v[132:133], v[60:61], v[22:23]
	s_nop 0
	v_add_f32_e32 v45, v133, v45
	v_add_f32_e32 v45, v132, v45
	v_mul_f32_e32 v47, 0xbfb8aa3b, v45
	v_exp_f32_e32 v47, v47
	v_mov_b32_e32 v132, v93
	v_mov_b32_e32 v133, v114
	v_pk_mul_f32 v[132:133], v[132:133], v[38:39]
	v_add_f32_e32 v47, 1.0, v47
	v_rcp_f32_e32 v47, v47
	v_pk_mul_f32 v[92:93], v[92:93], v[38:39]
	v_mul_f32_e32 v109, v45, v47
	v_add_f32_e32 v45, v133, v12
	v_add_f32_e32 v45, v132, v45
	v_pk_mul_f32 v[132:133], v[54:55], v[128:129]
	s_nop 0
	v_add_f32_e32 v45, v133, v45
	v_add_f32_e32 v45, v132, v45
	v_mul_f32_e32 v47, 0xbfb8aa3b, v45
	v_exp_f32_e32 v47, v47
	v_mov_b32_e32 v132, v87
	v_mov_b32_e32 v133, v112
	v_pk_mul_f32 v[132:133], v[132:133], v[4:5]
	v_add_f32_e32 v47, 1.0, v47
	v_rcp_f32_e32 v47, v47
	v_pk_mul_f32 v[86:87], v[86:87], v[4:5]
	v_pk_mul_f32 v[4:5], v[50:51], v[4:5]
	v_mul_f32_e32 v114, v45, v47
	v_add_f32_e32 v45, v133, v13
	v_add_f32_e32 v45, v132, v45
	v_pk_mul_f32 v[132:133], v[50:51], v[8:9]
	v_add_f32_e32 v5, v5, v13
	v_add_f32_e32 v45, v133, v45
	v_add_f32_e32 v45, v132, v45
	v_mul_f32_e32 v47, 0xbfb8aa3b, v45
	v_exp_f32_e32 v47, v47
	v_mov_b32_e32 v132, v81
	v_mov_b32_e32 v133, v108
	v_pk_mul_f32 v[132:133], v[132:133], v[28:29]
	v_add_f32_e32 v47, 1.0, v47
	v_rcp_f32_e32 v47, v47
	s_nop 0
	v_mul_f32_e32 v112, v45, v47
	v_add_f32_e32 v45, v133, v14
	v_mov_b32_e32 v47, v80
	v_add_f32_e32 v45, v132, v45
	v_pk_mul_f32 v[132:133], v[46:47], v[32:33]
	v_pk_mul_f32 v[80:81], v[80:81], v[28:29]
	v_add_f32_e32 v45, v133, v45
	v_add_f32_e32 v45, v132, v45
	v_mul_f32_e32 v49, 0xbfb8aa3b, v45
	v_exp_f32_e32 v49, v49
	v_mov_b32_e32 v132, v71
	v_mov_b32_e32 v133, v40
	v_pk_mul_f32 v[132:133], v[132:133], v[6:7]
	v_add_f32_e32 v49, 1.0, v49
	v_rcp_f32_e32 v49, v49
	v_add_f32_e32 v40, v133, v15
	v_add_f32_e32 v40, v132, v40
	v_mul_f32_e32 v108, v45, v49
	v_mov_b32_e32 v45, v70
	v_pk_mul_f32 v[132:133], v[44:45], v[10:11]
	v_pk_mul_f32 v[70:71], v[70:71], v[6:7]
	v_add_f32_e32 v40, v133, v40
	v_add_f32_e32 v40, v132, v40
	v_mul_f32_e32 v49, 0xbfb8aa3b, v40
	v_exp_f32_e32 v49, v49
	s_nop 0
	v_add_f32_e32 v49, 1.0, v49
	v_rcp_f32_e32 v49, v49
	s_nop 0
	v_mul_f32_e32 v40, v40, v49
	v_add_f32_e32 v49, v107, v24
	v_add_f32_e32 v49, v106, v49
	v_pk_mul_f32 v[106:107], v[98:99], v[122:123]
	v_add_f32_e32 v24, v43, v24
	v_add_f32_e32 v49, v107, v49
	v_add_f32_e32 v49, v106, v49
	v_mul_f32_e32 v53, 0xbfb8aa3b, v49
	v_exp_f32_e32 v53, v53
	v_pk_mul_f32 v[106:107], v[110:111], v[16:17]
	v_pk_mul_f32 v[16:17], v[78:79], v[16:17]
	v_add_f32_e32 v24, v42, v24
	v_add_f32_e32 v53, 1.0, v53
	v_rcp_f32_e32 v53, v53
	v_add_f32_e32 v17, v17, v25
	v_pk_mul_f32 v[42:43], v[96:97], v[122:123]
	v_bfe_u32 v78, v66, 6, 1
	v_mul_f32_e32 v99, v49, v53
	v_add_f32_e32 v49, v107, v25
	v_add_f32_e32 v49, v106, v49
	v_pk_mul_f32 v[106:107], v[90:91], v[20:21]
	v_add_f32_e32 v25, v16, v17
	v_add_f32_e32 v49, v107, v49
	v_add_f32_e32 v49, v106, v49
	v_mul_f32_e32 v53, 0xbfb8aa3b, v49
	v_exp_f32_e32 v53, v53
	v_pk_mul_f32 v[16:17], v[102:103], v[20:21]
	v_add_f32_e32 v24, v43, v24
	v_add_f32_e32 v17, v17, v25
	v_add_f32_e32 v53, 1.0, v53
	v_rcp_f32_e32 v53, v53
	v_add_f32_e32 v16, v16, v17
	v_mul_f32_e32 v17, 0xbfb8aa3b, v16
	v_exp_f32_e32 v17, v17
	v_mul_f32_e32 v91, v49, v53
	v_add_f32_e32 v49, v105, v26
	v_add_f32_e32 v49, v104, v49
	v_pk_mul_f32 v[104:105], v[84:85], v[126:127]
	v_add_f32_e32 v17, 1.0, v17
	v_add_f32_e32 v49, v105, v49
	v_add_f32_e32 v49, v104, v49
	v_mul_f32_e32 v53, 0xbfb8aa3b, v49
	v_exp_f32_e32 v53, v53
	v_rcp_f32_e32 v17, v17
	v_add_f32_e32 v24, v42, v24
	v_mul_f32_e32 v42, 0xbfb8aa3b, v24
	v_add_f32_e32 v53, 1.0, v53
	v_rcp_f32_e32 v53, v53
	v_mul_f32_e32 v20, v16, v17
	v_pk_mul_f32 v[16:17], v[68:69], v[36:37]
	v_exp_f32_e32 v42, v42
	v_mul_f32_e32 v85, v49, v53
	v_add_f32_e32 v49, v101, v27
	v_add_f32_e32 v49, v100, v49
	v_pk_mul_f32 v[100:101], v[76:77], v[22:23]
	v_add_f32_e32 v17, v17, v26
	v_add_f32_e32 v49, v101, v49
	v_add_f32_e32 v49, v100, v49
	v_mul_f32_e32 v53, 0xbfb8aa3b, v49
	v_exp_f32_e32 v53, v53
	v_add_f32_e32 v21, v16, v17
	v_pk_mul_f32 v[16:17], v[94:95], v[126:127]
	v_add_f32_e32 v42, 1.0, v42
	v_add_f32_e32 v53, 1.0, v53
	v_rcp_f32_e32 v53, v53
	v_add_f32_e32 v17, v17, v21
	v_add_f32_e32 v16, v16, v17
	v_mul_f32_e32 v17, 0xbfb8aa3b, v16
	v_mul_f32_e32 v77, v49, v53
	v_add_f32_e32 v49, v93, v12
	v_add_f32_e32 v49, v92, v49
	v_pk_mul_f32 v[92:93], v[64:65], v[128:129]
	v_exp_f32_e32 v17, v17
	v_add_f32_e32 v49, v93, v49
	v_add_f32_e32 v49, v92, v49
	v_mul_f32_e32 v53, 0xbfb8aa3b, v49
	v_exp_f32_e32 v53, v53
	v_add_f32_e32 v17, 1.0, v17
	v_rcp_f32_e32 v17, v17
	v_rcp_f32_e32 v42, v42
	v_add_f32_e32 v53, 1.0, v53
	v_rcp_f32_e32 v53, v53
	v_mul_f32_e32 v21, v16, v17
	v_pk_mul_f32 v[16:17], v[60:61], v[18:19]
	v_ashrrev_i32_e32 v76, 7, v66
	v_mul_f32_e32 v65, v49, v53
	v_add_f32_e32 v49, v87, v13
	v_add_f32_e32 v49, v86, v49
	v_pk_mul_f32 v[86:87], v[58:59], v[8:9]
	v_add_f32_e32 v13, v4, v5
	v_add_f32_e32 v49, v87, v49
	v_add_f32_e32 v49, v86, v49
	v_mul_f32_e32 v53, 0xbfb8aa3b, v49
	v_exp_f32_e32 v53, v53
	v_pk_mul_f32 v[4:5], v[74:75], v[8:9]
	v_add_f32_e32 v17, v17, v27
	v_add_f32_e32 v5, v5, v13
	v_add_f32_e32 v53, 1.0, v53
	v_rcp_f32_e32 v53, v53
	v_add_f32_e32 v4, v4, v5
	v_mul_f32_e32 v5, 0xbfb8aa3b, v4
	v_exp_f32_e32 v5, v5
	v_mul_f32_e32 v59, v49, v53
	v_add_f32_e32 v49, v81, v14
	v_mov_b32_e32 v53, v46
	v_add_f32_e32 v49, v80, v49
	v_pk_mul_f32 v[80:81], v[52:53], v[32:33]
	v_add_f32_e32 v5, 1.0, v5
	v_add_f32_e32 v49, v81, v49
	v_add_f32_e32 v49, v80, v49
	v_mul_f32_e32 v53, 0xbfb8aa3b, v49
	v_exp_f32_e32 v53, v53
	v_rcp_f32_e32 v5, v5
	v_add_f32_e32 v18, v16, v17
	v_pk_mul_f32 v[16:17], v[88:89], v[22:23]
	v_add_f32_e32 v53, 1.0, v53
	v_rcp_f32_e32 v53, v53
	v_mul_f32_e32 v8, v4, v5
	v_pk_mul_f32 v[4:5], v[46:47], v[28:29]
	v_add_f32_e32 v17, v17, v18
	v_mul_f32_e32 v53, v49, v53
	v_add_f32_e32 v49, v71, v15
	v_add_f32_e32 v5, v5, v14
	v_add_f32_e32 v57, v70, v49
	v_mov_b32_e32 v49, v44
	v_add_f32_e32 v9, v4, v5
	v_pk_mul_f32 v[4:5], v[62:63], v[32:33]
	v_pk_mul_f32 v[70:71], v[48:49], v[10:11]
	v_add_f32_e32 v5, v5, v9
	v_add_f32_e32 v49, v71, v57
	v_add_f32_e32 v4, v4, v5
	v_add_f32_e32 v49, v70, v49
	v_add_f32_e32 v16, v16, v17
	v_mul_f32_e32 v5, 0xbfb8aa3b, v4
	v_mul_f32_e32 v57, 0xbfb8aa3b, v49
	v_mul_f32_e32 v17, 0xbfb8aa3b, v16
	v_exp_f32_e32 v5, v5
	v_exp_f32_e32 v57, v57
	v_exp_f32_e32 v17, v17
	v_lshlrev_b32_e32 v80, 5, v76
	v_add_f32_e32 v5, 1.0, v5
	v_add_f32_e32 v57, 1.0, v57
	v_add_f32_e32 v17, 1.0, v17
	v_rcp_f32_e32 v5, v5
	v_rcp_f32_e32 v57, v57
	v_rcp_f32_e32 v17, v17
	v_or_b32_e32 v68, v80, v67
	v_mul_f32_e32 v9, v4, v5
	v_pk_mul_f32 v[4:5], v[44:45], v[6:7]
	v_mul_f32_e32 v49, v49, v57
	v_mul_f32_e32 v18, v16, v17
	v_pk_mul_f32 v[16:17], v[54:55], v[38:39]
	v_add_f32_e32 v5, v5, v15
	v_mov_b32_e32 v57, v48
	v_add_f32_e32 v12, v17, v12
	v_add_f32_e32 v6, v4, v5
	v_pk_mul_f32 v[4:5], v[56:57], v[10:11]
	v_add_f32_e32 v12, v16, v12
	v_pk_mul_f32 v[16:17], v[82:83], v[128:129]
	v_add_f32_e32 v5, v5, v6
	v_add_f32_e32 v12, v17, v12
	v_add_f32_e32 v4, v4, v5
	v_add_f32_e32 v12, v16, v12
	v_mul_f32_e32 v5, 0xbfb8aa3b, v4
	v_mul_f32_e32 v16, 0xbfb8aa3b, v12
	v_exp_f32_e32 v5, v5
	v_exp_f32_e32 v16, v16
	v_cvt_pk_bf16_f32 v6, v115, v113
	v_cvt_pk_bf16_f32 v7, v30, v31
	v_add_f32_e32 v5, 1.0, v5
	v_add_f32_e32 v16, 1.0, v16
	v_rcp_f32_e32 v5, v5
	v_rcp_f32_e32 v16, v16
	v_and_b32_e32 v79, 48, v66
	v_lshlrev_b32_e32 v81, 6, v78
	v_mul_f32_e32 v10, v4, v5
	v_cvt_pk_bf16_f32 v4, v125, v121
	v_cvt_pk_bf16_f32 v5, v119, v117
	ds_write_b128 v130, v[4:7]
	v_cvt_pk_bf16_f32 v6, v114, v112
	v_mul_f32_e32 v12, v12, v16
	v_cvt_pk_bf16_f32 v4, v34, v35
	v_cvt_pk_bf16_f32 v5, v41, v109
	v_cvt_pk_bf16_f32 v7, v108, v40
	ds_write_b128 v130, v[4:7] offset:272
	v_cvt_pk_bf16_f32 v6, v65, v59
	v_cvt_pk_bf16_f32 v4, v99, v91
	v_cvt_pk_bf16_f32 v5, v85, v77
	v_cvt_pk_bf16_f32 v7, v53, v49
	ds_write_b128 v130, v[4:7] offset:544
	v_cvt_pk_bf16_f32 v6, v12, v8
	v_add_u32_e32 v77, 0, v79
	v_or_b32_e32 v12, v81, v67
	v_mul_lo_u32 v69, v68, s55
	v_mul_f32_e32 v24, v24, v42
	v_cvt_pk_bf16_f32 v4, v24, v20
	v_cvt_pk_bf16_f32 v5, v21, v18
	v_cvt_pk_bf16_f32 v7, v9, v10
	v_add_u32_e32 v167, v77, v69
	v_mad_u32_u24 v64, v12, s55, v77
	ds_write_b128 v131, v[4:7]
	s_waitcnt lgkmcnt(0)
	s_barrier
	ds_read_b128 v[4:7], v167
	ds_read_b128 v[8:11], v167 offset:4352
	ds_read_b128 v[12:15], v64 offset:34816
	ds_read_b128 v[16:19], v64 offset:39168
	ds_read_b128 v[20:23], v64 offset:43520
	ds_read_b128 v[24:27], v64 offset:47872
	s_waitcnt lgkmcnt(3)
	v_mfma_f32_16x16x32_bf16 v[28:31], v[12:15], v[4:7], 0
	s_waitcnt lgkmcnt(2)
	v_mfma_f32_16x16x32_bf16 v[32:35], v[16:19], v[4:7], 0
	s_waitcnt lgkmcnt(1)
	v_mfma_f32_16x16x32_bf16 v[36:39], v[20:23], v[4:7], 0
	s_waitcnt lgkmcnt(0)
	v_mfma_f32_16x16x32_bf16 v[4:7], v[24:27], v[4:7], 0
	v_mfma_f32_16x16x32_bf16 v[12:15], v[12:15], v[8:11], 0
	v_mfma_f32_16x16x32_bf16 v[16:19], v[16:19], v[8:11], 0
	v_mfma_f32_16x16x32_bf16 v[20:23], v[20:23], v[8:11], 0
	v_mfma_f32_16x16x32_bf16 v[8:11], v[24:27], v[8:11], 0
	ds_read_b128 v[24:27], v167 offset:64
	ds_read_b128 v[40:43], v167 offset:4416
	ds_read_b128 v[44:47], v64 offset:34880
	ds_read_b128 v[48:51], v64 offset:39232
	ds_read_b128 v[52:55], v64 offset:43584
	ds_read_b128 v[56:59], v64 offset:47936
	s_waitcnt lgkmcnt(3)
	v_mfma_f32_16x16x32_bf16 v[28:31], v[44:47], v[24:27], v[28:31]
	s_waitcnt lgkmcnt(2)
	v_mfma_f32_16x16x32_bf16 v[32:35], v[48:51], v[24:27], v[32:35]
	s_waitcnt lgkmcnt(1)
	v_mfma_f32_16x16x32_bf16 v[36:39], v[52:55], v[24:27], v[36:39]
	s_waitcnt lgkmcnt(0)
	v_mfma_f32_16x16x32_bf16 v[4:7], v[56:59], v[24:27], v[4:7]
	v_mfma_f32_16x16x32_bf16 v[12:15], v[44:47], v[40:43], v[12:15]
	v_mfma_f32_16x16x32_bf16 v[16:19], v[48:51], v[40:43], v[16:19]
	v_mfma_f32_16x16x32_bf16 v[20:23], v[52:55], v[40:43], v[20:23]
	v_mfma_f32_16x16x32_bf16 v[8:11], v[56:59], v[40:43], v[8:11]
	ds_read_b128 v[24:27], v167 offset:128
	ds_read_b128 v[40:43], v167 offset:4480
	ds_read_b128 v[44:47], v64 offset:34944
	ds_read_b128 v[48:51], v64 offset:39296
	ds_read_b128 v[52:55], v64 offset:43648
	ds_read_b128 v[56:59], v64 offset:48000
	s_waitcnt lgkmcnt(3)
	v_mfma_f32_16x16x32_bf16 v[28:31], v[44:47], v[24:27], v[28:31]
	s_waitcnt lgkmcnt(2)
	v_mfma_f32_16x16x32_bf16 v[32:35], v[48:51], v[24:27], v[32:35]
	s_waitcnt lgkmcnt(1)
	v_mfma_f32_16x16x32_bf16 v[36:39], v[52:55], v[24:27], v[36:39]
	s_waitcnt lgkmcnt(0)
	v_mfma_f32_16x16x32_bf16 v[24:27], v[56:59], v[24:27], v[4:7]
	v_mfma_f32_16x16x32_bf16 v[44:47], v[44:47], v[40:43], v[12:15]
	v_mfma_f32_16x16x32_bf16 v[48:51], v[48:51], v[40:43], v[16:19]
	v_mfma_f32_16x16x32_bf16 v[52:55], v[52:55], v[40:43], v[20:23]
	v_mfma_f32_16x16x32_bf16 v[40:43], v[56:59], v[40:43], v[8:11]
	s_nop 1
	ds_read_b128 v[18:21], v167 offset:192
	ds_read_b128 v[56:59], v167 offset:4544
	ds_read_b128 v[60:63], v64 offset:35008
	ds_read_b128 v[70:73], v64 offset:39360
	ds_read_b128 v[82:85], v64 offset:43712
	ds_read_b128 v[86:89], v64 offset:48064
	s_waitcnt lgkmcnt(0)
	s_barrier
	v_mfma_f32_16x16x32_bf16 v[6:9], v[60:63], v[18:21], v[28:31]
	v_mfma_f32_16x16x32_bf16 v[10:13], v[70:73], v[18:21], v[32:35]
	v_mfma_f32_16x16x32_bf16 v[14:17], v[82:85], v[18:21], v[36:39]
	v_mfma_f32_16x16x32_bf16 v[18:21], v[86:89], v[18:21], v[24:27]
	v_mfma_f32_16x16x32_bf16 v[22:25], v[60:63], v[56:59], v[44:47]
	v_mfma_f32_16x16x32_bf16 v[26:29], v[70:73], v[56:59], v[48:51]
	v_mfma_f32_16x16x32_bf16 v[30:33], v[82:85], v[56:59], v[52:55]
	v_and_b32_e32 v82, 56, v3
	v_mfma_f32_16x16x32_bf16 v[34:37], v[86:89], v[56:59], v[40:43]
	s_and_saveexec_b64 s[0:1], vcc
	s_xor_b64 s[0:1], exec, s[0:1]
	v_lshrrev_b32_e32 v4, 1, v66
	v_and_b32_e32 v72, 0x3ffffffc, v4
	v_mov_b32_e32 v73, v2
	v_and_b32_e32 v82, 56, v3
	v_lshl_add_u64 v[70:71], s[16:17], 0, v[72:73]
	v_add_u32_e32 v73, s18, v72
	s_or_saveexec_b64 s[0:1], s[0:1]
	s_xor_b64 exec, exec, s[0:1]
	s_cbranch_execz .LBB0_260
	v_ashrrev_i32_e32 v3, 1, v66
	s_lshl_b32 s2, s19, 10
	v_readlane_b32 s4, v242, 63
	v_and_b32_e32 v72, -4, v3
	v_readlane_b32 s5, v241, 0
	s_add_u32 s2, s4, s2
	v_ashrrev_i32_e32 v73, 31, v72
	v_mov_b32_e32 v40, v2
	v_mov_b32_e32 v41, v2
	s_addc_u32 s3, s5, 0
	v_lshlrev_b32_e32 v4, 1, v82
	v_mov_b32_e32 v5, v2
	v_lshl_add_u64 v[70:71], s[16:17], 0, v[72:73]
	v_add_u32_e32 v73, s18, v72
	v_mov_b32_e32 v38, v2
	v_mov_b32_e32 v39, v2
	v_mov_b64_e32 v[44:45], v[40:41]
	v_lshl_add_u64 v[74:75], s[2:3], 0, v[4:5]
	v_cmp_lt_i32_e32 vcc, 2, v73
	v_mov_b64_e32 v[42:43], v[38:39]
	s_and_saveexec_b64 s[2:3], vcc
	s_cbranch_execz .LBB0_247
	v_mad_u64_u32 v[4:5], s[4:5], v70, s68, v[74:75]
	v_mov_b32_e32 v42, v5
	v_mad_u64_u32 v[42:43], s[4:5], v71, s68, v[42:43]
	v_add_co_u32_e32 v4, vcc, 0xffffa000, v4
	s_nop 1
	v_addc_co_u32_e32 v5, vcc, -1, v42, vcc
	global_load_dwordx4 v[42:45], v[4:5], off offset:-3072

.LBB0_536:
	s_or_b64 exec, exec, s[22:23]
	v_cmp_lt_i32_e32 vcc, -1, v23
	v_mov_b32_e32 v62, 0
	v_mov_b32_e32 v68, 0
	v_mov_b32_e32 v94, 0
	v_mov_b32_e32 v86, 0
	v_mov_b32_e32 v80, 0
	v_mov_b32_e32 v70, 0
	v_mov_b32_e32 v60, 0
	v_mov_b32_e32 v54, 0
	v_mov_b32_e32 v50, 0
	v_mov_b32_e32 v128, 0
	v_mov_b32_e32 v129, 0
	v_mov_b32_e32 v130, 0
	v_mov_b32_e32 v131, 0
	s_and_saveexec_b64 s[22:23], vcc
	s_cbranch_execz .LBB0_538
	v_mov_b64_e32 v[24:25], s[2:3]
	v_mad_u64_u32 v[24:25], s[42:43], v20, s28, v[24:25]
	v_mov_b32_e32 v26, v25
	v_mad_u64_u32 v[26:27], s[42:43], v21, s28, v[26:27]
	v_mov_b32_e32 v25, v26
	v_mov_b32_e32 v19, v75
	v_lshl_add_u64 v[24:25], v[24:25], 0, v[18:19]
	global_load_dwordx4 v[128:131], v[24:25], off
.LBB0_538:
	s_or_b64 exec, exec, s[22:23]
	v_cmp_lt_i32_e32 vcc, -2, v23
	v_mov_b32_e32 v90, 0
	v_mov_b32_e32 v82, 0
	v_mov_b32_e32 v72, 0
	v_mov_b32_e32 v64, 0
	v_mov_b32_e32 v58, 0
	v_mov_b32_e32 v52, 0
	v_mov_b32_e32 v44, 0
	v_mov_b32_e32 v132, 0
	v_mov_b32_e32 v133, 0
	v_mov_b32_e32 v134, 0
	v_mov_b32_e32 v135, 0
	s_and_saveexec_b64 s[22:23], vcc
	s_cbranch_execz .LBB0_540
	v_mov_b64_e32 v[24:25], s[2:3]
	v_mad_u64_u32 v[24:25], s[42:43], v20, s28, v[24:25]
	v_mov_b32_e32 v26, v25
	v_mad_u64_u32 v[26:27], s[42:43], v21, s28, v[26:27]
	v_mov_b32_e32 v25, v26
	v_mov_b32_e32 v19, v75
	v_lshl_add_u64 v[24:25], v[24:25], 0, v[18:19]
	v_add_co_u32_e32 v24, vcc, 0x2000, v24
	s_nop 1
	v_addc_co_u32_e32 v25, vcc, 0, v25, vcc
	global_load_dwordx4 v[132:135], v[24:25], off offset:1024
.LBB0_540:
	s_or_b64 exec, exec, s[22:23]
	v_cmp_lt_i32_e32 vcc, -3, v23
	v_mov_b32_e32 v116, 0
	v_mov_b32_e32 v118, 0
	v_mov_b32_e32 v112, 0
	v_mov_b32_e32 v106, 0
	v_mov_b32_e32 v100, 0
	v_mov_b32_e32 v98, 0
	v_mov_b32_e32 v92, 0
	v_mov_b32_e32 v84, 0
	v_mov_b32_e32 v78, 0
	v_mov_b32_e32 v136, 0
	v_mov_b32_e32 v137, 0
	v_mov_b32_e32 v138, 0
	v_mov_b32_e32 v139, 0
	s_and_saveexec_b64 s[22:23], vcc
	s_cbranch_execz .LBB0_542
	v_mov_b64_e32 v[24:25], s[2:3]
	v_mad_u64_u32 v[24:25], s[42:43], v20, s28, v[24:25]
	v_mov_b32_e32 v26, v25
	v_mad_u64_u32 v[26:27], s[42:43], v21, s28, v[26:27]
	v_mov_b32_e32 v25, v26
	v_mov_b32_e32 v19, v75
	v_lshl_add_u64 v[24:25], v[24:25], 0, v[18:19]
	v_add_co_u32_e32 v24, vcc, 0x4000, v24
	s_nop 1
	v_addc_co_u32_e32 v25, vcc, 0, v25, vcc
	global_load_dwordx4 v[136:139], v[24:25], off offset:2048
.LBB0_542:
	s_or_b64 exec, exec, s[22:23]
	v_cmp_lt_i32_e32 vcc, -4, v23
	v_mov_b32_e32 v126, 0
	v_mov_b32_e32 v124, 0
	v_mov_b32_e32 v122, 0
	v_mov_b32_e32 v120, 0
	v_mov_b32_e32 v114, 0
	v_mov_b32_e32 v108, 0
	v_mov_b32_e32 v104, 0
	v_mov_b32_e32 v140, 0
	v_mov_b32_e32 v141, 0
	v_mov_b32_e32 v142, 0
	v_mov_b32_e32 v143, 0
	s_and_saveexec_b64 s[22:23], vcc
	s_cbranch_execz .LBB0_544
	v_mov_b64_e32 v[24:25], s[2:3]
	v_mad_u64_u32 v[24:25], s[42:43], v20, s28, v[24:25]
	v_mov_b32_e32 v20, v25
	v_mad_u64_u32 v[20:21], s[42:43], v21, s28, v[20:21]
	v_mov_b32_e32 v25, v20
	v_mov_b32_e32 v19, v75
	v_lshl_add_u64 v[18:19], v[24:25], 0, v[18:19]
	v_add_co_u32_e32 v18, vcc, 0x6000, v18
	s_nop 1
	v_addc_co_u32_e32 v19, vcc, 0, v19, vcc
	global_load_dwordx4 v[140:143], v[18:19], off offset:3072
.LBB0_544:
	s_or_b64 exec, exec, s[22:23]
	s_waitcnt vmcnt(0)
	v_lshlrev_b32_e32 v111, 16, v244
	v_and_b32_e32 v103, 0xffff0000, v244
	v_lshlrev_b32_e32 v97, 16, v245
	v_and_b32_e32 v89, 0xffff0000, v245
	v_lshlrev_b32_e32 v77, 16, v246
	v_and_b32_e32 v67, 0xffff0000, v246
	v_lshlrev_b32_e32 v57, 16, v247
	v_and_b32_e32 v49, 0xffff0000, v247
	v_lshlrev_b32_e32 v110, 16, v248
	v_and_b32_e32 v102, 0xffff0000, v248
	v_lshlrev_b32_e32 v96, 16, v249
	v_and_b32_e32 v88, 0xffff0000, v249
	v_lshlrev_b32_e32 v76, 16, v250
	v_and_b32_e32 v66, 0xffff0000, v250
	v_lshlrev_b32_e32 v56, 16, v251
	v_and_b32_e32 v48, 0xffff0000, v251
	v_lshlrev_b32_e32 v69, 16, v252
	v_and_b32_e32 v95, 0xffff0000, v252
	v_lshlrev_b32_e32 v87, 16, v253
	v_and_b32_e32 v81, 0xffff0000, v253
	v_lshlrev_b32_e32 v71, 16, v254
	v_and_b32_e32 v61, 0xffff0000, v254
	v_lshlrev_b32_e32 v55, 16, v255
	v_and_b32_e32 v51, 0xffff0000, v255
	v_lshlrev_b32_e32 v68, 16, v128
	v_and_b32_e32 v94, 0xffff0000, v128
	v_lshlrev_b32_e32 v86, 16, v129
	v_and_b32_e32 v80, 0xffff0000, v129
	v_lshlrev_b32_e32 v70, 16, v130
	v_and_b32_e32 v60, 0xffff0000, v130
	v_lshlrev_b32_e32 v54, 16, v131
	v_and_b32_e32 v50, 0xffff0000, v131
	v_lshlrev_b32_e32 v62, 16, v132
	v_and_b32_e32 v90, 0xffff0000, v132
	v_lshlrev_b32_e32 v82, 16, v133
	v_and_b32_e32 v72, 0xffff0000, v133
	v_lshlrev_b32_e32 v64, 16, v134
	v_and_b32_e32 v58, 0xffff0000, v134
	v_lshlrev_b32_e32 v52, 16, v135
	v_and_b32_e32 v44, 0xffff0000, v135
	v_lshlrev_b32_e32 v118, 16, v136
	v_and_b32_e32 v112, 0xffff0000, v136
	v_lshlrev_b32_e32 v106, 16, v137
	v_and_b32_e32 v100, 0xffff0000, v137
	v_lshlrev_b32_e32 v98, 16, v138
	v_and_b32_e32 v92, 0xffff0000, v138
	v_lshlrev_b32_e32 v84, 16, v139
	v_and_b32_e32 v78, 0xffff0000, v139
	v_lshlrev_b32_e32 v116, 16, v140
	v_and_b32_e32 v126, 0xffff0000, v140
	v_lshlrev_b32_e32 v124, 16, v141
	v_and_b32_e32 v122, 0xffff0000, v141
	v_lshlrev_b32_e32 v120, 16, v142
	v_and_b32_e32 v114, 0xffff0000, v142
	v_lshlrev_b32_e32 v108, 16, v143
	v_and_b32_e32 v104, 0xffff0000, v143
	v_readlane_b32 s80, v242, 2
	v_readlane_b32 s84, v242, 6
	v_readlane_b32 s85, v242, 7
	v_lshlrev_b32_e32 v26, 2, v22
	v_mov_b32_e32 v27, v75
	v_readlane_b32 s86, v242, 8
	v_readlane_b32 s87, v242, 9
	s_mov_b64 s[44:45], s[84:85]
	v_lshl_add_u64 v[22:23], s[44:45], 0, v[26:27]
	v_add_co_u32_e32 v24, vcc, s30, v22
	global_load_dwordx4 v[18:21], v26, s[44:45] offset:16
	global_load_dwordx4 v[30:33], v26, s[44:45]
	v_addc_co_u32_e32 v25, vcc, 0, v23, vcc
	global_load_dwordx4 v[140:143], v[24:25], off offset:2048
	v_add_co_u32_e32 v24, vcc, s31, v22
	s_mov_b64 s[46:47], s[86:87]
	s_nop 0
	v_addc_co_u32_e32 v25, vcc, 0, v23, vcc
	v_add_co_u32_e32 v28, vcc, s29, v22
	v_mov_b32_e32 v91, v94
	s_nop 0
	v_addc_co_u32_e32 v29, vcc, 0, v23, vcc
	global_load_dwordx4 v[154:157], v[28:29], off offset:2048
	global_load_dwordx4 v[34:37], v[24:25], off
	v_lshl_add_u64 v[24:25], v[22:23], 0, s[8:9]
	global_load_dwordx4 v[158:161], v[24:25], off offset:16
	v_lshl_add_u64 v[24:25], v[22:23], 0, s[10:11]
	v_lshl_add_u64 v[22:23], v[22:23], 0, s[12:13]
	global_load_dwordx4 v[162:165], v[22:23], off offset:16
	s_nop 0
	global_load_dwordx4 v[22:25], v[24:25], off offset:16
	s_nop 0
	global_load_dwordx4 v[38:41], v26, s[46:47]
	s_nop 0
	global_load_dwordx4 v[26:29], v26, s[46:47] offset:16
	v_mov_b32_e32 v83, v86
	v_mov_b32_e32 v119, v62
	v_mov_b32_e32 v113, v90
	v_mov_b32_e32 v107, v82
	v_mov_b32_e32 v101, v72
	v_mov_b32_e32 v99, v64
	v_mov_b32_e32 v93, v58
	v_mov_b32_e32 v127, v112
	v_mov_b32_e32 v117, v118
	v_mov_b32_e32 v125, v106
	v_mov_b32_e32 v123, v100
	v_mov_b32_e32 v121, v98
	v_mov_b32_e32 v115, v92
	v_mov_b32_e32 v109, v84
	v_mov_b32_e32 v105, v78
	v_and_b32_e32 v147, 15, v146
	v_bfe_u32 v148, v146, 4, 2
	s_waitcnt vmcnt(12)
	v_cvt_pk_bf16_f32 v6, v6, v7
	v_cvt_pk_bf16_f32 v7, v8, v9
	v_cvt_pk_bf16_f32 v8, v2, v3
	v_lshlrev_b32_e32 v2, 1, v149
	s_waitcnt vmcnt(10)
	v_cvt_pk_bf16_f32 v14, v14, v15
	v_cvt_pk_bf16_f32 v15, v16, v17
	v_cvt_pk_bf16_f32 v16, v10, v11
	v_cvt_pk_bf16_f32 v17, v12, v13
	v_cvt_pk_bf16_f32 v9, v4, v5
	v_readlane_b32 s81, v242, 3
	v_readlane_b32 s82, v242, 4
	v_readlane_b32 s83, v242, 5
	v_readlane_b32 s88, v242, 10
	v_readlane_b32 s89, v242, 11
	v_readlane_b32 s90, v242, 12
	v_readlane_b32 s91, v242, 13
	v_readlane_b32 s92, v242, 14
	v_readlane_b32 s93, v242, 15
	v_readlane_b32 s94, v242, 16
	v_readlane_b32 s95, v242, 17
	s_waitcnt vmcnt(9)
	v_mov_b32_e32 v133, v18
	s_waitcnt vmcnt(8)
	v_mov_b32_e32 v129, v30
	v_mov_b32_e32 v131, v32
	s_waitcnt vmcnt(7)
	v_mov_b32_e32 v128, v140
	v_mov_b32_e32 v30, v141
	v_mov_b32_e32 v130, v142
	v_pk_mul_f32 v[140:141], v[110:111], v[128:129]
	v_mov_b32_e32 v32, v143
	v_pk_mul_f32 v[168:169], v[88:89], v[32:33]
	s_waitcnt vmcnt(6)
	v_mov_b32_e32 v138, v154
	s_waitcnt vmcnt(5)
	v_mov_b32_e32 v139, v34
	v_mov_b32_e32 v34, v155
	s_waitcnt vmcnt(4)
	v_mov_b32_e32 v132, v158
	s_waitcnt vmcnt(2)
	v_mov_b32_e32 v135, v22
	v_mov_b32_e32 v18, v159
	v_pk_mul_f32 v[158:159], v[96:97], v[130:131]
	s_waitcnt vmcnt(1)
	v_add_f32_e32 v22, v141, v38
	v_mov_b32_e32 v136, v156
	v_mov_b32_e32 v137, v36
	v_pk_mul_f32 v[142:143], v[68:69], v[138:139]
	v_pk_mul_f32 v[154:155], v[102:103], v[30:31]
	v_add_f32_e32 v47, v159, v40
	v_add_f32_e32 v22, v140, v22
	v_pk_mul_f32 v[166:167], v[86:87], v[136:137]
	v_add_f32_e32 v45, v155, v39
	v_add_f32_e32 v47, v158, v47
	v_add_f32_e32 v22, v143, v22
	v_mov_b32_e32 v36, v157
	v_pk_mul_f32 v[156:157], v[94:95], v[34:35]
	v_add_f32_e32 v45, v154, v45
	v_add_f32_e32 v47, v167, v47
	v_add_f32_e32 v22, v142, v22
	v_add_f32_e32 v45, v157, v45
	v_add_f32_e32 v65, v166, v47
	v_mul_f32_e32 v47, 0xbfb8aa3b, v22
	v_add_f32_e32 v45, v156, v45
	v_exp_f32_e32 v47, v47
	v_pk_mul_f32 v[176:177], v[66:67], v[18:19]
	v_mul_f32_e32 v67, 0xbfb8aa3b, v45
	v_exp_f32_e32 v67, v67
	v_add_f32_e32 v47, 1.0, v47
	v_rcp_f32_e32 v47, v47
	s_waitcnt vmcnt(0)
	v_add_f32_e32 v63, v177, v27
	v_add_f32_e32 v67, 1.0, v67
	v_rcp_f32_e32 v67, v67
	v_mul_f32_e32 v47, v22, v47
	v_mov_b32_e32 v22, v163
	v_add_f32_e32 v63, v176, v63
	v_pk_mul_f32 v[140:141], v[60:61], v[22:23]
	v_mul_f32_e32 v67, v45, v67
	v_add_f32_e32 v45, v141, v63
	v_add_f32_e32 v45, v140, v45
	v_mov_b32_e32 v140, v160
	v_mov_b32_e32 v141, v20
	v_pk_mul_f32 v[142:143], v[56:57], v[140:141]
	v_mul_f32_e32 v63, 0xbfb8aa3b, v45
	v_add_f32_e32 v20, v143, v28
	v_exp_f32_e32 v63, v63
	v_add_f32_e32 v20, v142, v20
	v_mov_b32_e32 v142, v164
	v_mov_b32_e32 v143, v24
	v_pk_mul_f32 v[154:155], v[54:55], v[142:143]
	v_pk_mul_f32 v[172:173], v[76:77], v[132:133]
	v_mul_f32_e32 v73, 0xbfb8aa3b, v65
	v_add_f32_e32 v20, v155, v20
	v_mov_b32_e32 v134, v162
	v_add_f32_e32 v53, v169, v41
	v_add_f32_e32 v59, v173, v26
	v_exp_f32_e32 v73, v73
	v_add_f32_e32 v57, v154, v20
	v_pk_mul_f32 v[170:171], v[80:81], v[36:37]
	v_pk_mul_f32 v[174:175], v[70:71], v[134:135]
	v_add_f32_e32 v53, v168, v53
	v_add_f32_e32 v59, v172, v59
	v_add_f32_e32 v63, 1.0, v63
	v_mul_f32_e32 v20, 0xbfb8aa3b, v57
	v_add_f32_e32 v53, v171, v53
	v_add_f32_e32 v59, v175, v59
	v_rcp_f32_e32 v63, v63
	v_exp_f32_e32 v20, v20
	v_add_f32_e32 v53, v170, v53
	v_add_f32_e32 v59, v174, v59
	v_mul_f32_e32 v77, 0xbfb8aa3b, v53
	v_mul_f32_e32 v79, 0xbfb8aa3b, v59
	v_add_f32_e32 v73, 1.0, v73
	v_exp_f32_e32 v77, v77
	v_exp_f32_e32 v79, v79
	v_rcp_f32_e32 v73, v73
	v_mul_f32_e32 v155, v45, v63
	v_add_f32_e32 v45, 1.0, v20
	v_mov_b32_e32 v20, v161
	v_pk_mul_f32 v[156:157], v[48:49], v[20:21]
	v_add_f32_e32 v77, 1.0, v77
	v_add_f32_e32 v24, v157, v29
	v_mul_f32_e32 v103, v65, v73
	v_add_f32_e32 v73, 1.0, v79
	v_add_f32_e32 v49, v156, v24
	v_mov_b32_e32 v24, v165
	v_rcp_f32_e32 v65, v77
	v_rcp_f32_e32 v73, v73
	v_pk_mul_f32 v[156:157], v[50:51], v[24:25]
	v_mov_b32_e32 v63, v68
	v_add_f32_e32 v49, v157, v49
	v_add_f32_e32 v49, v156, v49
	v_mov_b32_e32 v156, v69
	v_mov_b32_e32 v157, v110
	v_pk_mul_f32 v[110:111], v[156:157], v[128:129]
	v_mul_f32_e32 v153, v53, v65
	v_mul_f32_e32 v154, v59, v73
	v_mul_f32_e32 v53, 0xbfb8aa3b, v49
	v_add_f32_e32 v59, v111, v38
	v_exp_f32_e32 v53, v53
	v_add_f32_e32 v59, v110, v59
	v_pk_mul_f32 v[110:111], v[62:63], v[138:139]
	v_rcp_f32_e32 v45, v45
	v_add_f32_e32 v59, v111, v59
	v_add_f32_e32 v59, v110, v59
	v_mov_b32_e32 v110, v95
	v_mov_b32_e32 v111, v102
	v_pk_mul_f32 v[110:111], v[110:111], v[30:31]
	v_mul_f32_e32 v65, 0xbfb8aa3b, v59
	v_add_f32_e32 v53, 1.0, v53
	v_add_f32_e32 v73, v111, v39
	v_exp_f32_e32 v65, v65
	v_rcp_f32_e32 v53, v53
	v_add_f32_e32 v73, v110, v73
	v_pk_mul_f32 v[110:111], v[90:91], v[34:35]
	v_add_f32_e32 v65, 1.0, v65
	v_add_f32_e32 v73, v111, v73
	v_add_f32_e32 v79, v110, v73
	v_mov_b32_e32 v110, v87
	v_mov_b32_e32 v111, v96
	v_pk_mul_f32 v[96:97], v[110:111], v[130:131]
	v_mul_f32_e32 v73, 0xbfb8aa3b, v79
	v_mul_f32_e32 v156, v49, v53
	v_add_f32_e32 v53, v97, v40
	v_rcp_f32_e32 v65, v65
	v_exp_f32_e32 v73, v73
	v_add_f32_e32 v53, v96, v53
	v_pk_mul_f32 v[96:97], v[82:83], v[136:137]
	v_mul_f32_e32 v102, v57, v45
	v_add_f32_e32 v53, v97, v53
	v_add_f32_e32 v53, v96, v53
	v_mov_b32_e32 v96, v81
	v_mov_b32_e32 v97, v88
	v_pk_mul_f32 v[88:89], v[96:97], v[32:33]
	v_mul_f32_e32 v49, v59, v65
	v_add_f32_e32 v45, 1.0, v73
	v_add_f32_e32 v59, v89, v41
	v_mov_b32_e32 v73, v80
	v_add_f32_e32 v59, v88, v59
	v_pk_mul_f32 v[88:89], v[72:73], v[36:37]
	v_mul_f32_e32 v57, 0xbfb8aa3b, v53
	v_add_f32_e32 v59, v89, v59
	v_add_f32_e32 v59, v88, v59
	v_mul_f32_e32 v65, 0xbfb8aa3b, v59
	v_exp_f32_e32 v65, v65
	v_mov_b32_e32 v88, v71
	v_mov_b32_e32 v89, v76
	v_pk_mul_f32 v[76:77], v[88:89], v[132:133]
	v_add_f32_e32 v65, 1.0, v65
	v_rcp_f32_e32 v85, v65
	v_add_f32_e32 v65, v77, v26
	v_add_f32_e32 v88, v76, v65
	v_mov_b32_e32 v65, v70
	v_pk_mul_f32 v[76:77], v[64:65], v[134:135]
	v_exp_f32_e32 v57, v57
	v_add_f32_e32 v77, v77, v88
	v_add_f32_e32 v88, v76, v77
	v_mul_f32_e32 v76, 0xbfb8aa3b, v88
	v_rcp_f32_e32 v45, v45
	v_exp_f32_e32 v76, v76
	v_add_f32_e32 v57, 1.0, v57
	v_rcp_f32_e32 v57, v57
	v_mul_f32_e32 v157, v79, v45
	v_add_f32_e32 v45, 1.0, v76
	v_mov_b32_e32 v76, v61
	v_mov_b32_e32 v77, v66
	v_pk_mul_f32 v[76:77], v[76:77], v[18:19]
	v_mul_f32_e32 v158, v53, v57
	v_mul_f32_e32 v159, v59, v85
	v_add_f32_e32 v53, v77, v27
	v_mov_b32_e32 v59, v60
	v_add_f32_e32 v53, v76, v53
	v_pk_mul_f32 v[76:77], v[58:59], v[22:23]
	v_lshlrev_b32_e32 v110, 2, v148
	v_add_f32_e32 v53, v77, v53
	v_add_f32_e32 v66, v76, v53
	v_mov_b32_e32 v76, v55
	v_mov_b32_e32 v77, v56
	v_mul_f32_e32 v53, 0xbfb8aa3b, v66
	v_pk_mul_f32 v[56:57], v[76:77], v[140:141]
	v_exp_f32_e32 v79, v53
	v_add_f32_e32 v53, v57, v28
	v_add_f32_e32 v76, v56, v53
	v_mov_b32_e32 v53, v54
	v_pk_mul_f32 v[56:57], v[52:53], v[142:143]
	v_rcp_f32_e32 v77, v45
	v_add_f32_e32 v57, v57, v76
	v_add_f32_e32 v76, v56, v57
	v_mul_f32_e32 v56, 0xbfb8aa3b, v76
	v_exp_f32_e32 v56, v56
	v_add_f32_e32 v45, 1.0, v79
	v_rcp_f32_e32 v79, v45
	v_mov_b32_e32 v57, v48
	v_add_f32_e32 v45, 1.0, v56
	v_mov_b32_e32 v56, v51
	v_pk_mul_f32 v[56:57], v[56:57], v[20:21]
	v_rcp_f32_e32 v85, v45
	v_add_f32_e32 v45, v57, v29
	v_add_f32_e32 v48, v56, v45
	v_mov_b32_e32 v45, v50
	v_pk_mul_f32 v[56:57], v[44:45], v[24:25]
	v_mul_f32_e32 v161, v76, v85
	v_add_f32_e32 v48, v57, v48
	v_add_f32_e32 v48, v56, v48
	v_mul_f32_e32 v56, 0xbfb8aa3b, v48
	v_exp_f32_e32 v56, v56
	v_mul_f32_e32 v160, v88, v77
	v_mul_f32_e32 v66, v66, v79
	v_pk_mul_f32 v[54:55], v[54:55], v[140:141]
	v_add_f32_e32 v76, 1.0, v56
	v_pk_mul_f32 v[56:57], v[68:69], v[128:129]
	v_rcp_f32_e32 v76, v76
	v_add_f32_e32 v57, v57, v38
	v_add_f32_e32 v68, v56, v57
	v_pk_mul_f32 v[56:57], v[118:119], v[138:139]
	v_mul_f32_e32 v48, v48, v76
	v_add_f32_e32 v57, v57, v68
	v_add_f32_e32 v68, v56, v57
	v_mul_f32_e32 v56, 0xbfb8aa3b, v68
	v_exp_f32_e32 v69, v56
	v_pk_mul_f32 v[56:57], v[94:95], v[30:31]
	v_add_f32_e32 v55, v55, v28
	v_add_f32_e32 v57, v57, v39
	v_add_f32_e32 v77, v56, v57
	v_pk_mul_f32 v[56:57], v[112:113], v[34:35]
	v_pk_mul_f32 v[50:51], v[50:51], v[20:21]
	v_add_f32_e32 v57, v57, v77
	v_add_f32_e32 v77, v56, v57
	v_mul_f32_e32 v56, 0xbfb8aa3b, v77
	v_exp_f32_e32 v56, v56
	v_add_f32_e32 v57, 1.0, v69
	v_rcp_f32_e32 v69, v57
	v_add_f32_e32 v51, v51, v29
	v_add_f32_e32 v56, 1.0, v56
	v_rcp_f32_e32 v79, v56
	v_pk_mul_f32 v[56:57], v[86:87], v[130:131]
	v_mul_f32_e32 v68, v68, v69
	v_add_f32_e32 v57, v57, v40
	v_add_f32_e32 v85, v56, v57
	v_pk_mul_f32 v[56:57], v[106:107], v[136:137]
	v_mul_f32_e32 v69, v77, v79
	v_add_f32_e32 v57, v57, v85
	v_add_f32_e32 v85, v56, v57
	v_mul_f32_e32 v56, 0xbfb8aa3b, v85
	v_exp_f32_e32 v56, v56
	v_pk_mul_f32 v[30:31], v[90:91], v[30:31]
	v_bfe_u32 v112, v146, 6, 1
	v_add_f32_e32 v31, v31, v39
	v_add_f32_e32 v76, 1.0, v56
	v_pk_mul_f32 v[56:57], v[80:81], v[32:33]
	v_add_f32_e32 v39, v30, v31
	v_add_f32_e32 v57, v57, v41
	v_add_f32_e32 v77, v56, v57
	v_pk_mul_f32 v[56:57], v[100:101], v[36:37]
	v_pk_mul_f32 v[30:31], v[126:127], v[34:35]
	v_add_f32_e32 v57, v57, v77
	v_add_f32_e32 v77, v56, v57
	v_mul_f32_e32 v56, 0xbfb8aa3b, v77
	v_exp_f32_e32 v79, v56
	v_pk_mul_f32 v[56:57], v[70:71], v[132:133]
	v_rcp_f32_e32 v71, v76
	v_add_f32_e32 v57, v57, v26
	v_add_f32_e32 v70, v56, v57
	v_pk_mul_f32 v[56:57], v[98:99], v[134:135]
	v_add_f32_e32 v31, v31, v39
	v_add_f32_e32 v57, v57, v70
	v_add_f32_e32 v70, v56, v57
	v_mul_f32_e32 v56, 0xbfb8aa3b, v70
	v_exp_f32_e32 v56, v56
	v_add_f32_e32 v57, 1.0, v79
	v_rcp_f32_e32 v76, v57
	v_add_f32_e32 v34, v30, v31
	v_add_f32_e32 v56, 1.0, v56
	v_rcp_f32_e32 v79, v56
	v_pk_mul_f32 v[56:57], v[60:61], v[18:19]
	v_mul_f32_e32 v30, 0xbfb8aa3b, v34
	v_add_f32_e32 v57, v57, v27
	v_add_f32_e32 v60, v56, v57
	v_pk_mul_f32 v[56:57], v[92:93], v[22:23]
	v_mul_f32_e32 v70, v70, v79
	v_add_f32_e32 v57, v57, v60
	v_mul_f32_e32 v60, v85, v71
	v_mov_b32_e32 v85, v52
	v_add_f32_e32 v71, v54, v55
	v_pk_mul_f32 v[54:55], v[84:85], v[142:143]
	v_mov_b32_e32 v79, v44
	v_add_f32_e32 v55, v55, v71
	v_add_f32_e32 v71, v50, v51
	v_pk_mul_f32 v[50:51], v[78:79], v[24:25]
	v_add_f32_e32 v54, v54, v55
	v_add_f32_e32 v51, v51, v71
	v_add_f32_e32 v71, v50, v51
	v_mul_f32_e32 v55, 0xbfb8aa3b, v54
	v_mul_f32_e32 v50, 0xbfb8aa3b, v71
	v_exp_f32_e32 v55, v55
	v_exp_f32_e32 v50, v50
	v_mul_f32_e32 v61, v77, v76
	v_exp_f32_e32 v35, v30
	v_add_f32_e32 v51, 1.0, v55
	v_add_f32_e32 v50, 1.0, v50
	v_rcp_f32_e32 v55, v51
	v_rcp_f32_e32 v76, v50
	v_pk_mul_f32 v[50:51], v[62:63], v[128:129]
	v_pk_mul_f32 v[30:31], v[82:83], v[130:131]
	v_add_f32_e32 v38, v51, v38
	v_add_f32_e32 v31, v31, v40
	v_add_f32_e32 v38, v50, v38
	v_pk_mul_f32 v[50:51], v[116:117], v[138:139]
	v_add_f32_e32 v39, v30, v31
	v_pk_mul_f32 v[30:31], v[124:125], v[136:137]
	v_add_f32_e32 v38, v51, v38
	v_add_f32_e32 v31, v31, v39
	v_add_f32_e32 v38, v50, v38
	v_add_f32_e32 v39, v30, v31
	v_mul_f32_e32 v50, 0xbfb8aa3b, v38
	v_mul_f32_e32 v30, 0xbfb8aa3b, v39
	v_exp_f32_e32 v50, v50
	v_exp_f32_e32 v30, v30
	v_add_f32_e32 v31, 1.0, v35
	v_rcp_f32_e32 v35, v31
	v_add_f32_e32 v50, 1.0, v50
	v_add_f32_e32 v30, 1.0, v30
	v_rcp_f32_e32 v40, v50
	v_rcp_f32_e32 v50, v30
	v_pk_mul_f32 v[30:31], v[72:73], v[32:33]
	v_mul_f32_e32 v63, v71, v76
	v_add_f32_e32 v31, v31, v41
	v_add_f32_e32 v32, v30, v31
	v_pk_mul_f32 v[30:31], v[122:123], v[36:37]
	v_mul_f32_e32 v71, v34, v35
	v_add_f32_e32 v31, v31, v32
	v_add_f32_e32 v32, v30, v31
	v_mul_f32_e32 v30, 0xbfb8aa3b, v32
	v_exp_f32_e32 v30, v30
	v_pk_mul_f32 v[18:19], v[58:59], v[18:19]
	v_add_f32_e32 v56, v56, v57
	v_add_f32_e32 v19, v19, v27
	v_add_f32_e32 v30, 1.0, v30
	v_rcp_f32_e32 v34, v30
	v_pk_mul_f32 v[30:31], v[64:65], v[132:133]
	v_add_f32_e32 v27, v18, v19
	v_add_f32_e32 v26, v31, v26
	v_add_f32_e32 v26, v30, v26
	v_pk_mul_f32 v[30:31], v[120:121], v[134:135]
	v_pk_mul_f32 v[18:19], v[114:115], v[22:23]
	v_add_f32_e32 v26, v31, v26
	v_add_f32_e32 v26, v30, v26
	v_add_f32_e32 v19, v19, v27
	v_mul_f32_e32 v30, 0xbfb8aa3b, v26
	v_add_f32_e32 v27, v18, v19
	v_exp_f32_e32 v30, v30
	v_mul_f32_e32 v18, 0xbfb8aa3b, v27
	v_exp_f32_e32 v18, v18
	v_mul_f32_e32 v31, v32, v34
	v_add_f32_e32 v19, 1.0, v30
	v_rcp_f32_e32 v30, v19
	v_add_f32_e32 v32, 1.0, v18
	v_pk_mul_f32 v[18:19], v[52:53], v[140:141]
	v_mul_f32_e32 v57, 0xbfb8aa3b, v56
	v_add_f32_e32 v19, v19, v28
	v_add_f32_e32 v22, v18, v19
	v_pk_mul_f32 v[18:19], v[108:109], v[142:143]
	v_exp_f32_e32 v57, v57
	v_add_f32_e32 v19, v19, v22
	v_add_f32_e32 v28, v18, v19
	v_mul_f32_e32 v18, 0xbfb8aa3b, v28
	v_exp_f32_e32 v52, v18
	v_pk_mul_f32 v[18:19], v[44:45], v[20:21]
	v_lshlrev_b64 v[92:93], 2, v[42:43]
	v_add_f32_e32 v19, v19, v29
	v_add_f32_e32 v20, v18, v19
	v_pk_mul_f32 v[18:19], v[104:105], v[24:25]
	v_add_f32_e32 v57, 1.0, v57
	v_add_f32_e32 v19, v19, v20
	v_add_f32_e32 v29, v18, v19
	v_lshl_add_u64 v[18:19], s[20:21], 0, v[92:93]
	s_lshl_b64 s[20:21], s[16:17], 9
	s_add_u32 s20, s26, s20
	s_addc_u32 s21, s27, s21
	s_lshl_b32 s16, s4, 10
	v_rcp_f32_e32 v57, v57
	v_and_or_b32 v80, v151, s34, v147
	s_add_u32 s22, s24, s16
	v_lshl_add_u64 v[18:19], v[18:19], 0, v[74:75]
	s_addc_u32 s23, s25, 0
	v_ashrrev_i32_e32 v81, 31, v80
	v_lshlrev_b32_e32 v111, 5, v112
	v_lshl_add_u64 v[20:21], v[18:19], 0, s[14:15]
	v_add_co_u32_e32 v18, vcc, s35, v18
	s_add_u32 s42, s60, s16
	v_lshl_add_u64 v[82:83], s[18:19], 0, v[80:81]
	v_or_b32_e32 v58, v111, v110
	v_addc_co_u32_e32 v19, vcc, 0, v19, vcc
	s_addc_u32 s43, s61, 0
	v_lshlrev_b64 v[88:89], 11, v[82:83]
	v_or_b32_e32 v78, 16, v80
	v_mul_f32_e32 v51, v56, v57
	v_mul_f32_e32 v62, v54, v55
	v_mul_f32_e32 v33, v38, v40
	v_mul_f32_e32 v50, v39, v50
	global_load_dwordx4 v[38:41], v[18:19], off
	global_load_dwordx4 v[34:37], v[20:21], off offset:48
	global_load_dwordx4 v[42:45], v[20:21], off offset:32
	global_load_dwordx4 v[54:57], v[20:21], off offset:16
	v_lshlrev_b64 v[86:87], 2, v[80:81]
	v_lshl_add_u64 v[20:21], s[22:23], 0, v[88:89]
	v_mov_b64_e32 v[22:23], s[42:43]
	v_lshlrev_b32_e32 v76, 1, v58
	v_mov_b32_e32 v77, v75
	v_ashrrev_i32_e32 v79, 31, v78
	v_lshl_add_u64 v[18:19], s[20:21], 0, v[86:87]
	v_mul_lo_u32 v81, v83, s28
	v_mad_u64_u32 v[24:25], s[20:21], v82, s28, v[22:23]
	v_lshl_add_u64 v[20:21], v[20:21], 0, v[76:77]
	v_lshl_add_u64 v[84:85], s[18:19], 0, v[78:79]
	v_add_u32_e32 v25, v81, v25
	global_load_dword v83, v[18:19], off
	global_load_dwordx2 v[94:95], v[20:21], off
	global_load_dwordx2 v[98:99], v[20:21], off offset:32
	global_load_dword v113, v[18:19], off offset:64
	v_lshlrev_b64 v[90:91], 11, v[84:85]
	v_mul_lo_u32 v79, v85, s28
	v_mad_u64_u32 v[20:21], s[18:19], v84, s28, v[22:23]
	v_lshl_add_u64 v[24:25], v[24:25], 0, v[76:77]
	v_lshl_add_u64 v[18:19], s[22:23], 0, v[90:91]
	v_add_u32_e32 v21, v79, v21
	v_lshl_add_u64 v[18:19], v[18:19], 0, v[76:77]
	v_lshl_add_u64 v[20:21], v[20:21], 0, v[76:77]
	global_load_dwordx2 v[106:107], v[24:25], off
	global_load_dwordx2 v[126:127], v[24:25], off offset:32
	global_load_dwordx2 v[104:105], v[18:19], off
	global_load_dwordx2 v[96:97], v[18:19], off offset:32
	global_load_dwordx2 v[108:109], v[20:21], off
	global_load_dwordx2 v[100:101], v[20:21], off offset:32
	v_mul_f32_e32 v53, 0xbfb8aa3b, v29
	v_exp_f32_e32 v18, v53
	v_add_f32_e32 v20, 1.0, v52
	v_rcp_f32_e32 v19, v32
	v_rcp_f32_e32 v20, v20
	v_add_f32_e32 v18, 1.0, v18
	v_rcp_f32_e32 v18, v18
	v_mul_f32_e32 v23, v26, v30
	v_lshl_add_u32 v22, v152, 1, 0
	v_mul_f32_e32 v26, v27, v19
	v_mul_f32_e32 v27, v28, v20
	v_cvt_pk_bf16_f32 v20, v154, v155
	v_mad_u64_u32 v[24:25], s[18:19], v46, s33, v[22:23]
	v_mul_f32_e32 v28, v29, v18
	v_cvt_pk_bf16_f32 v18, v47, v67
	v_cvt_pk_bf16_f32 v19, v103, v153
	v_cvt_pk_bf16_f32 v21, v102, v156
	ds_write_b128 v24, v[18:21]
	v_cvt_pk_bf16_f32 v20, v160, v66
	v_cvt_pk_bf16_f32 v18, v49, v157
	v_cvt_pk_bf16_f32 v19, v158, v159
	v_cvt_pk_bf16_f32 v21, v161, v48
	ds_write_b128 v24, v[18:21] offset:272
	v_cvt_pk_bf16_f32 v20, v70, v51
	v_cvt_pk_bf16_f32 v18, v68, v69
	v_cvt_pk_bf16_f32 v19, v60, v61
	v_cvt_pk_bf16_f32 v21, v62, v63
	ds_write_b128 v24, v[18:21] offset:544
	v_cvt_pk_bf16_f32 v20, v23, v26
	v_or_b32_e32 v23, 3, v151
	v_cvt_pk_bf16_f32 v18, v33, v71
	v_mad_u64_u32 v[22:23], s[18:19], v23, s33, v[22:23]
	v_cvt_pk_bf16_f32 v19, v50, v31
	v_cvt_pk_bf16_f32 v21, v27, v28
	ds_write_b128 v22, v[18:21]
	v_mul_lo_u32 v18, v150, s33
	v_lshl_add_u32 v46, v148, 4, 0
	v_or_b32_e32 v47, v111, v147
	v_add3_u32 v128, 0, v18, v2
	v_mad_u64_u32 v[22:23], s[18:19], v78, s33, v[46:47]
	v_mad_u64_u32 v[30:31], s[18:19], v80, s33, v[46:47]
	v_mad_u32_u24 v129, v47, s33, v46
	ds_write_b128 v128, v[14:17] offset:34816
	ds_write_b128 v128, v[6:9] offset:34832
	s_waitcnt lgkmcnt(0)
	s_barrier
	ds_read_b128 v[2:5], v22 offset:192
	ds_read_b128 v[10:13], v22 offset:128
	ds_read_b128 v[6:9], v30 offset:192
	ds_read_b128 v[14:17], v30 offset:128
	ds_read_b128 v[18:21], v22 offset:64
	ds_read_b128 v[26:29], v22
	ds_read_b128 v[22:25], v30 offset:64
	ds_read_b128 v[30:33], v30
	ds_read_b128 v[46:49], v129 offset:34816
	ds_read_b128 v[50:53], v129 offset:34880
	ds_read_b128 v[58:61], v129 offset:39168
	ds_read_b128 v[62:65], v129 offset:39232
	ds_read_b128 v[66:69], v129 offset:34944
	ds_read_b128 v[70:73], v129 offset:35008
	ds_read_b128 v[114:117], v129 offset:39296
	ds_read_b128 v[118:121], v129 offset:39360
	s_waitcnt vmcnt(5)
	v_lshlrev_b32_e32 v85, 16, v106
	s_waitcnt lgkmcnt(7)
	v_mfma_f32_16x16x32_bf16 v[122:125], v[46:49], v[30:33], 0
	v_mul_f32_e32 v102, 0xbfb8aa3b, v85
	v_exp_f32_e32 v102, v102
	v_and_b32_e32 v106, 0xffff0000, v106
	s_waitcnt lgkmcnt(6)
	v_mfma_f32_16x16x32_bf16 v[122:125], v[50:53], v[22:25], v[122:125]
	v_mul_f32_e32 v130, 0xbfb8aa3b, v106
	v_add_f32_e32 v102, 1.0, v102
	v_rcp_f32_e32 v102, v102
	v_exp_f32_e32 v134, v130
	s_waitcnt lgkmcnt(3)
	v_mfma_f32_16x16x32_bf16 v[122:125], v[66:69], v[14:17], v[122:125]
	v_mul_f32_e32 v83, 0x3fb8aa3b, v83
	v_mul_f32_e32 v85, v102, v85
	v_add_f32_e32 v102, 1.0, v134
	v_exp_f32_e32 v83, v83
	s_waitcnt lgkmcnt(2)
	v_mfma_f32_16x16x32_bf16 v[122:125], v[70:73], v[6:9], v[122:125]
	v_rcp_f32_e32 v102, v102
	v_lshlrev_b32_e32 v103, 16, v94
	v_and_b32_e32 v94, 0xffff0000, v94
	v_mfma_f32_16x16x32_bf16 v[46:49], v[46:49], v[26:29], 0
	v_mul_f32_e32 v102, v102, v106
	s_nop 2
	v_fmac_f32_e32 v94, v83, v123
	v_fmac_f32_e32 v103, v83, v122
	v_mul_f32_e32 v94, v102, v94
	v_lshlrev_b32_e32 v102, 16, v107
	v_mul_f32_e32 v85, v85, v103
	v_mul_f32_e32 v103, 0xbfb8aa3b, v102
	v_mfma_f32_16x16x32_bf16 v[46:49], v[50:53], v[18:21], v[46:49]
	v_exp_f32_e32 v103, v103
	v_lshlrev_b32_e32 v106, 16, v95
	v_fmac_f32_e32 v106, v83, v124
	v_mfma_f32_16x16x32_bf16 v[130:133], v[58:61], v[30:33], 0
	v_add_f32_e32 v103, 1.0, v103
	v_rcp_f32_e32 v103, v103
	v_and_b32_e32 v107, 0xffff0000, v107
	v_mfma_f32_16x16x32_bf16 v[58:61], v[58:61], v[26:29], 0
	v_mul_f32_e32 v122, 0xbfb8aa3b, v107
	s_or_b32 s20, s40, 1
	s_or_b32 s16, s39, s20
	v_mfma_f32_16x16x32_bf16 v[46:49], v[66:69], v[10:13], v[46:49]
	s_lshl_b64 s[18:19], s[16:17], 15
	s_add_u32 s18, s74, s18
	s_addc_u32 s19, s75, s19
	v_mfma_f32_16x16x32_bf16 v[130:133], v[62:65], v[22:25], v[130:133]
	v_cvt_pk_bf16_f32 v38, v38, v39
	v_cvt_pk_bf16_f32 v39, v40, v41
	v_cvt_pk_bf16_f32 v40, v54, v55
	v_mfma_f32_16x16x32_bf16 v[50:53], v[62:65], v[18:21], v[58:61]
	v_exp_f32_e32 v62, v122
	v_and_b32_e32 v64, 0xffff0000, v95
	v_fmac_f32_e32 v64, v83, v125
	v_mfma_f32_16x16x32_bf16 v[70:73], v[70:73], v[2:5], v[46:49]
	v_mul_f32_e32 v58, v103, v102
	v_mul_f32_e32 v63, v58, v106
	v_add_f32_e32 v62, 1.0, v62
	s_waitcnt vmcnt(4)
	v_lshlrev_b32_e32 v46, 16, v126
	v_mul_f32_e32 v47, 0xbfb8aa3b, v46
	v_exp_f32_e32 v47, v47
	s_waitcnt lgkmcnt(1)
	v_mfma_f32_16x16x32_bf16 v[58:61], v[114:117], v[14:17], v[130:133]
	v_and_b32_e32 v49, 0xffff0000, v126
	v_lshlrev_b32_e32 v48, 16, v98
	v_add_f32_e32 v47, 1.0, v47
	v_mfma_f32_16x16x32_bf16 v[50:53], v[114:117], v[10:13], v[50:53]
	v_rcp_f32_e32 v47, v47
	v_rcp_f32_e32 v62, v62
	v_cvt_pk_bf16_f32 v116, v85, v94
	s_waitcnt lgkmcnt(0)
	v_mfma_f32_16x16x32_bf16 v[58:61], v[118:121], v[6:9], v[58:61]
	v_mul_f32_e32 v46, v47, v46
	v_and_b32_e32 v47, 0xffff0000, v98
	v_mul_f32_e32 v62, v62, v107
	v_mfma_f32_16x16x32_bf16 v[66:69], v[118:121], v[2:5], v[50:53]
	v_mul_f32_e32 v62, v62, v64
	s_nop 2
	v_fmac_f32_e32 v48, v83, v58
	v_mul_f32_e32 v46, v46, v48
	v_mul_f32_e32 v50, 0xbfb8aa3b, v49
	v_exp_f32_e32 v50, v50
	v_fmac_f32_e32 v47, v83, v59
	v_lshlrev_b32_e32 v52, 16, v99
	v_fmac_f32_e32 v52, v83, v60
	v_add_f32_e32 v48, 1.0, v50
	v_lshlrev_b32_e32 v50, 16, v127
	v_rcp_f32_e32 v48, v48
	v_mul_f32_e32 v51, 0xbfb8aa3b, v50
	v_exp_f32_e32 v51, v51
	v_mul_f32_e32 v64, v94, v94
	v_mul_f32_e32 v48, v48, v49
	v_and_b32_e32 v49, 0xffff0000, v127
	v_mul_f32_e32 v47, v48, v47
	v_add_f32_e32 v48, 1.0, v51
	v_mul_f32_e32 v51, 0xbfb8aa3b, v49
	v_rcp_f32_e32 v48, v48
	v_exp_f32_e32 v51, v51
	v_cvt_pk_bf16_f32 v117, v46, v47
	v_fmac_f32_e32 v64, v85, v85
	v_mul_f32_e32 v48, v48, v50
	v_add_f32_e32 v50, 1.0, v51
	v_rcp_f32_e32 v50, v50
	v_and_b32_e32 v51, 0xffff0000, v99
	v_mul_f32_e32 v48, v48, v52
	v_fmac_f32_e32 v51, v83, v61
	v_mul_f32_e32 v49, v50, v49
	v_mul_f32_e32 v50, v47, v47
	v_fmac_f32_e32 v50, v46, v46
	v_mul_f32_e32 v46, 0x3fb8aa3b, v113
	v_exp_f32_e32 v113, v46
	s_waitcnt vmcnt(1)
	v_lshlrev_b32_e32 v46, 16, v108
	v_mul_f32_e32 v47, 0xbfb8aa3b, v46
	v_exp_f32_e32 v47, v47
	v_mul_f32_e32 v49, v49, v51
	v_fmac_f32_e32 v50, v48, v48
	v_cvt_pk_bf16_f32 v118, v48, v49
	v_lshlrev_b32_e32 v48, 16, v104
	v_fmac_f32_e32 v48, v113, v70
	v_add_f32_e32 v47, 1.0, v47
	v_and_b32_e32 v70, 0xffff0000, v108
	v_fmac_f32_e32 v50, v49, v49
	v_rcp_f32_e32 v47, v47
	v_mul_f32_e32 v49, 0xbfb8aa3b, v70
	v_exp_f32_e32 v49, v49
	v_and_b32_e32 v83, 0xffff0000, v104
	v_mul_f32_e32 v46, v47, v46
	v_mul_f32_e32 v119, v46, v48
	v_add_f32_e32 v46, 1.0, v49
	v_lshlrev_b32_e32 v104, 16, v109
	v_rcp_f32_e32 v85, v46
	v_mul_f32_e32 v46, 0xbfb8aa3b, v104
	v_exp_f32_e32 v108, v46
	v_lshl_add_u64 v[46:47], s[18:19], 0, v[92:93]
	s_lshl_b64 s[18:19], s[16:17], 9
	s_add_u32 s18, s26, s18
	s_addc_u32 s19, s27, s19
	s_lshl_b32 s16, s20, 7
	s_add_u32 s20, s24, s16
	s_addc_u32 s21, s25, 0
	v_fmac_f32_e32 v64, v63, v63
	v_lshl_add_u64 v[46:47], v[46:47], 0, v[74:75]
	s_add_u32 s22, s60, s16
	v_fmac_f32_e32 v64, v62, v62
	v_cvt_pk_bf16_f32 v115, v63, v62
	v_lshl_add_u64 v[62:63], v[46:47], 0, s[14:15]
	v_add_co_u32_e32 v46, vcc, s35, v46
	s_addc_u32 s23, s61, 0
	v_lshl_add_u64 v[98:99], s[20:21], 0, v[88:89]
	v_addc_co_u32_e32 v47, vcc, 0, v47, vcc
	v_lshl_add_u64 v[94:95], s[18:19], 0, v[86:87]
	v_mov_b64_e32 v[102:103], s[22:23]
	v_lshl_add_u64 v[98:99], v[98:99], 0, v[76:77]
	v_add_f32_e32 v137, v64, v50
	global_load_dwordx4 v[50:53], v[46:47], off
	s_nop 0
	global_load_dwordx4 v[46:49], v[62:63], off offset:48
	global_load_dwordx4 v[58:61], v[62:63], off offset:32
	s_nop 0
	global_load_dwordx4 v[62:65], v[62:63], off offset:16
	v_mad_u64_u32 v[106:107], s[18:19], v82, s28, v[102:103]
	global_load_dword v124, v[94:95], off
	global_load_dwordx2 v[142:143], v[98:99], off
	global_load_dwordx2 v[154:155], v[98:99], off offset:32
	global_load_dword v149, v[94:95], off offset:64
	v_mad_u64_u32 v[98:99], s[18:19], v84, s28, v[102:103]
	v_add_u32_e32 v107, v81, v107
	v_lshl_add_u64 v[94:95], s[20:21], 0, v[90:91]
	v_add_u32_e32 v99, v79, v99
	v_lshl_add_u64 v[106:107], v[106:107], 0, v[76:77]
	v_lshl_add_u64 v[94:95], v[94:95], 0, v[76:77]
	v_lshl_add_u64 v[98:99], v[98:99], 0, v[76:77]
	global_load_dwordx2 v[156:157], v[106:107], off
	global_load_dwordx2 v[158:159], v[106:107], off offset:32
	global_load_dwordx2 v[102:103], v[94:95], off
	s_nop 0
	global_load_dwordx2 v[94:95], v[94:95], off offset:32
	s_nop 0
	global_load_dwordx2 v[106:107], v[98:99], off
	s_nop 0
	global_load_dwordx2 v[98:99], v[98:99], off offset:32
	v_fmac_f32_e32 v83, v113, v71
	v_mul_f32_e32 v70, v85, v70
	v_and_b32_e32 v71, 0xffff0000, v109
	v_mul_f32_e32 v130, v70, v83
	v_mul_f32_e32 v83, 0xbfb8aa3b, v71
	v_exp_f32_e32 v83, v83
	v_add_f32_e32 v70, 1.0, v108
	v_rcp_f32_e32 v70, v70
	v_lshlrev_b32_e32 v85, 16, v105
	v_fmac_f32_e32 v85, v113, v72
	v_add_f32_e32 v72, 1.0, v83
	v_rcp_f32_e32 v72, v72
	v_mul_f32_e32 v70, v70, v104
	v_mul_f32_e32 v131, v70, v85
	v_and_b32_e32 v70, 0xffff0000, v105
	v_fmac_f32_e32 v70, v113, v73
	v_mul_f32_e32 v71, v72, v71
	v_mul_f32_e32 v132, v71, v70
	s_waitcnt vmcnt(14)
	v_lshlrev_b32_e32 v70, 16, v100
	v_mul_f32_e32 v71, 0xbfb8aa3b, v70
	v_exp_f32_e32 v71, v71
	v_and_b32_e32 v73, 0xffff0000, v100
	v_mul_f32_e32 v100, 0xbfb8aa3b, v73
	v_exp_f32_e32 v100, v100
	v_add_f32_e32 v71, 1.0, v71
	v_rcp_f32_e32 v71, v71
	v_lshlrev_b32_e32 v72, 16, v96
	v_fmac_f32_e32 v72, v113, v66
	v_cvt_pk_bf16_f32 v41, v56, v57
	v_mul_f32_e32 v66, v71, v70
	v_mul_f32_e32 v133, v66, v72
	v_add_f32_e32 v66, 1.0, v100
	v_lshlrev_b32_e32 v70, 16, v101
	v_rcp_f32_e32 v66, v66
	v_mul_f32_e32 v71, 0xbfb8aa3b, v70
	v_exp_f32_e32 v71, v71
	v_and_b32_e32 v72, 0xffff0000, v96
	v_fmac_f32_e32 v72, v113, v67
	v_mul_f32_e32 v66, v66, v73
	v_add_f32_e32 v67, 1.0, v71
	v_mul_f32_e32 v134, v66, v72
	v_lshlrev_b32_e32 v66, 16, v97
	v_and_b32_e32 v96, 0xffff0000, v101
	v_rcp_f32_e32 v67, v67
	v_fmac_f32_e32 v66, v113, v68
	v_mul_f32_e32 v68, 0xbfb8aa3b, v96
	v_exp_f32_e32 v68, v68
	v_mul_f32_e32 v67, v67, v70
	v_mul_f32_e32 v135, v67, v66
	v_and_b32_e32 v97, 0xffff0000, v97
	v_add_f32_e32 v66, 1.0, v68
	v_cvt_pk_bf16_f32 v42, v42, v43
	v_cvt_pk_bf16_f32 v43, v44, v45
	v_cvt_pk_bf16_f32 v44, v34, v35
	v_cvt_pk_bf16_f32 v45, v36, v37
	v_fmac_f32_e32 v97, v113, v69
	v_rcp_f32_e32 v100, v66
	ds_write_b128 v128, v[38:41] offset:52224
	ds_write_b128 v128, v[42:45] offset:52240
	s_waitcnt lgkmcnt(0)
	s_barrier
	ds_read_b128 v[34:37], v129 offset:52224
	ds_read_b128 v[38:41], v129 offset:52288
	ds_read_b128 v[42:45], v129 offset:56576
	ds_read_b128 v[54:57], v129 offset:56640
	ds_read_b128 v[66:69], v129 offset:52352
	ds_read_b128 v[70:73], v129 offset:52416
	ds_read_b128 v[120:123], v129 offset:56704
	ds_read_b128 v[138:141], v129 offset:56768
	v_mul_f32_e32 v96, v100, v96
	v_mul_f32_e32 v136, v96, v97
	v_cvt_pk_bf16_f32 v85, v119, v130
	v_cvt_pk_bf16_f32 v83, v131, v132
	v_cvt_pk_bf16_f32 v114, v133, v134
	v_cvt_pk_bf16_f32 v113, v135, v136
	s_waitcnt vmcnt(9)
	v_mul_f32_e32 v96, 0x3fb8aa3b, v124
	s_waitcnt lgkmcnt(7)
	v_mfma_f32_16x16x32_bf16 v[124:127], v[34:37], v[30:33], 0
	s_waitcnt vmcnt(5)
	v_lshlrev_b32_e32 v97, 16, v156
	v_mul_f32_e32 v100, 0xbfb8aa3b, v97
	v_exp_f32_e32 v100, v100
	s_waitcnt lgkmcnt(6)
	v_mfma_f32_16x16x32_bf16 v[124:127], v[38:41], v[22:25], v[124:127]
	v_and_b32_e32 v104, 0xffff0000, v156
	v_mul_f32_e32 v105, 0xbfb8aa3b, v104
	v_add_f32_e32 v100, 1.0, v100
	s_waitcnt lgkmcnt(3)
	v_mfma_f32_16x16x32_bf16 v[124:127], v[66:69], v[14:17], v[124:127]
	v_rcp_f32_e32 v100, v100
	v_exp_f32_e32 v105, v105
	v_exp_f32_e32 v96, v96
	s_waitcnt lgkmcnt(2)
	v_mfma_f32_16x16x32_bf16 v[124:127], v[70:73], v[6:9], v[124:127]
	v_mul_f32_e32 v97, v100, v97
	v_add_f32_e32 v100, 1.0, v105
	v_rcp_f32_e32 v100, v100
	v_lshlrev_b32_e32 v101, 16, v142
	v_mfma_f32_16x16x32_bf16 v[34:37], v[34:37], v[26:29], 0
	s_nop 2
	v_fmac_f32_e32 v101, v96, v124
	v_mul_f32_e32 v97, v97, v101
	v_and_b32_e32 v101, 0xffff0000, v142
	v_fmac_f32_e32 v101, v96, v125
	v_mul_f32_e32 v100, v100, v104
	v_mul_f32_e32 v100, v100, v101
	v_lshlrev_b32_e32 v101, 16, v157
	v_mul_f32_e32 v104, 0xbfb8aa3b, v101
	v_exp_f32_e32 v104, v104
	v_mfma_f32_16x16x32_bf16 v[150:153], v[42:45], v[30:33], 0
	v_lshlrev_b32_e32 v105, 16, v143
	v_fmac_f32_e32 v105, v96, v126
	v_add_f32_e32 v104, 1.0, v104
	v_mfma_f32_16x16x32_bf16 v[34:37], v[38:41], v[18:21], v[34:37]
	v_rcp_f32_e32 v104, v104
	v_and_b32_e32 v108, 0xffff0000, v157
	v_mul_f32_e32 v109, 0xbfb8aa3b, v108
	v_mfma_f32_16x16x32_bf16 v[42:45], v[42:45], v[26:29], 0
	s_or_b32 s20, s40, 2
	s_or_b32 s16, s39, s20
	s_lshl_b64 s[18:19], s[16:17], 15
	v_mfma_f32_16x16x32_bf16 v[150:153], v[54:57], v[22:25], v[150:153]
	s_add_u32 s18, s74, s18
	s_addc_u32 s19, s75, s19
	v_mfma_f32_16x16x32_bf16 v[34:37], v[66:69], v[10:13], v[34:37]
	v_mfma_f32_16x16x32_bf16 v[38:41], v[54:57], v[18:21], v[42:45]
	v_exp_f32_e32 v54, v109
	v_and_b32_e32 v56, 0xffff0000, v143
	v_fmac_f32_e32 v56, v96, v127
	v_mul_f32_e32 v42, v104, v101
	v_mul_f32_e32 v55, v42, v105
	s_waitcnt lgkmcnt(1)
	v_mfma_f32_16x16x32_bf16 v[42:45], v[120:123], v[14:17], v[150:153]
	v_add_f32_e32 v54, 1.0, v54
	v_rcp_f32_e32 v54, v54
	v_cvt_pk_bf16_f32 v127, v97, v100
	v_mfma_f32_16x16x32_bf16 v[70:73], v[70:73], v[2:5], v[34:37]
	v_mul_f32_e32 v54, v54, v108
	v_mul_f32_e32 v54, v54, v56
	s_waitcnt vmcnt(4)
	v_lshlrev_b32_e32 v34, 16, v158
	v_mul_f32_e32 v35, 0xbfb8aa3b, v34
	v_exp_f32_e32 v35, v35
	s_waitcnt lgkmcnt(0)
	v_mfma_f32_16x16x32_bf16 v[42:45], v[138:141], v[6:9], v[42:45]
	v_lshlrev_b32_e32 v36, 16, v154
	v_and_b32_e32 v37, 0xffff0000, v158
	v_add_f32_e32 v35, 1.0, v35
	v_rcp_f32_e32 v35, v35
	v_mul_f32_e32 v56, v100, v100
	s_nop 2
	v_fmac_f32_e32 v36, v96, v42
	v_mul_f32_e32 v42, 0xbfb8aa3b, v37
	v_exp_f32_e32 v42, v42
	v_fmac_f32_e32 v56, v97, v97
	v_mul_f32_e32 v34, v35, v34
	v_fmac_f32_e32 v56, v55, v55
	v_mul_f32_e32 v34, v34, v36
	v_add_f32_e32 v36, 1.0, v42
	v_lshlrev_b32_e32 v42, 16, v159
	v_mfma_f32_16x16x32_bf16 v[38:41], v[120:123], v[10:13], v[38:41]
	v_fmac_f32_e32 v56, v54, v54
	v_cvt_pk_bf16_f32 v122, v55, v54
	v_rcp_f32_e32 v36, v36
	v_mul_f32_e32 v54, 0xbfb8aa3b, v42
	v_exp_f32_e32 v54, v54
	v_and_b32_e32 v35, 0xffff0000, v154
	v_fmac_f32_e32 v35, v96, v43
	v_mul_f32_e32 v36, v36, v37
	v_and_b32_e32 v37, 0xffff0000, v159
	v_mul_f32_e32 v35, v36, v35
	v_add_f32_e32 v36, 1.0, v54
	v_mul_f32_e32 v43, 0xbfb8aa3b, v37
	v_rcp_f32_e32 v36, v36
	v_exp_f32_e32 v43, v43
	v_cvt_pk_bf16_f32 v125, v34, v35
	v_lshlrev_b32_e32 v54, 16, v155
	v_mul_f32_e32 v36, v36, v42
	v_add_f32_e32 v42, 1.0, v43
	v_rcp_f32_e32 v42, v42
	v_fmac_f32_e32 v54, v96, v44
	v_and_b32_e32 v43, 0xffff0000, v155
	v_mul_f32_e32 v36, v36, v54
	v_mul_f32_e32 v37, v42, v37
	v_mul_f32_e32 v42, v35, v35
	v_fmac_f32_e32 v42, v34, v34
	v_mul_f32_e32 v34, 0x3fb8aa3b, v149
	v_exp_f32_e32 v123, v34
	s_waitcnt vmcnt(1)
	v_lshlrev_b32_e32 v34, 16, v106
	v_mul_f32_e32 v35, 0xbfb8aa3b, v34
	v_exp_f32_e32 v35, v35
	v_fmac_f32_e32 v43, v96, v45
	v_mul_f32_e32 v37, v37, v43
	v_fmac_f32_e32 v42, v36, v36
	v_cvt_pk_bf16_f32 v126, v36, v37
	v_lshlrev_b32_e32 v36, 16, v102
	v_fmac_f32_e32 v36, v123, v70
	v_add_f32_e32 v35, 1.0, v35
	v_and_b32_e32 v70, 0xffff0000, v106
	v_fmac_f32_e32 v42, v37, v37
	v_rcp_f32_e32 v35, v35
	v_mul_f32_e32 v37, 0xbfb8aa3b, v70
	v_exp_f32_e32 v37, v37
	v_add_f32_e32 v56, v137, v56
	v_mul_f32_e32 v34, v35, v34
	v_mul_f32_e32 v137, v34, v36
	v_add_f32_e32 v34, 1.0, v37
	v_lshlrev_b32_e32 v120, 16, v107
	v_rcp_f32_e32 v106, v34
	v_mul_f32_e32 v34, 0xbfb8aa3b, v120
	v_exp_f32_e32 v121, v34
	v_lshl_add_u64 v[34:35], s[18:19], 0, v[92:93]
	s_lshl_b64 s[18:19], s[16:17], 9
	s_add_u32 s18, s26, s18
	s_addc_u32 s19, s27, s19
	s_lshl_b32 s16, s20, 7
	s_add_u32 s20, s24, s16
	s_addc_u32 s21, s25, 0
	v_lshl_add_u64 v[34:35], v[34:35], 0, v[74:75]
	s_add_u32 s22, s60, s16
	v_lshl_add_u64 v[66:67], v[34:35], 0, s[14:15]
	v_add_co_u32_e32 v34, vcc, s35, v34
	s_addc_u32 s23, s61, 0
	v_lshl_add_u64 v[100:101], s[20:21], 0, v[88:89]
	v_addc_co_u32_e32 v35, vcc, 0, v35, vcc
	v_lshl_add_u64 v[96:97], s[18:19], 0, v[86:87]
	v_mov_b64_e32 v[104:105], s[22:23]
	v_lshl_add_u64 v[100:101], v[100:101], 0, v[76:77]
	v_add_f32_e32 v150, v56, v42
	global_load_dwordx4 v[42:45], v[34:35], off
	s_nop 0
	global_load_dwordx4 v[34:37], v[66:67], off offset:48
	global_load_dwordx4 v[54:57], v[66:67], off offset:32
	s_nop 0
	global_load_dwordx4 v[66:69], v[66:67], off offset:16
	v_mad_u64_u32 v[108:109], s[18:19], v82, s28, v[104:105]
	global_load_dword v149, v[96:97], off
	global_load_dwordx2 v[142:143], v[100:101], off
	global_load_dwordx2 v[170:171], v[100:101], off offset:32
	global_load_dword v176, v[96:97], off offset:64
	v_mad_u64_u32 v[100:101], s[18:19], v84, s28, v[104:105]
	v_add_u32_e32 v109, v81, v109
	v_lshl_add_u64 v[96:97], s[20:21], 0, v[90:91]
	v_add_u32_e32 v101, v79, v101
	v_lshl_add_u64 v[108:109], v[108:109], 0, v[76:77]
	v_lshl_add_u64 v[96:97], v[96:97], 0, v[76:77]
	v_lshl_add_u64 v[100:101], v[100:101], 0, v[76:77]
	global_load_dwordx2 v[172:173], v[108:109], off
	global_load_dwordx2 v[174:175], v[108:109], off offset:32
	global_load_dwordx2 v[104:105], v[96:97], off
	s_nop 0
	global_load_dwordx2 v[96:97], v[96:97], off offset:32
	s_nop 0
	global_load_dwordx2 v[108:109], v[100:101], off
	s_nop 0
	global_load_dwordx2 v[100:101], v[100:101], off offset:32
	v_and_b32_e32 v102, 0xffff0000, v102
	v_fmac_f32_e32 v102, v123, v71
	v_mul_f32_e32 v70, v106, v70
	v_and_b32_e32 v71, 0xffff0000, v107
	v_mul_f32_e32 v151, v70, v102
	v_mul_f32_e32 v102, 0xbfb8aa3b, v71
	v_exp_f32_e32 v102, v102
	v_add_f32_e32 v70, 1.0, v121
	v_rcp_f32_e32 v70, v70
	v_lshlrev_b32_e32 v106, 16, v103
	v_fmac_f32_e32 v106, v123, v72
	v_add_f32_e32 v72, 1.0, v102
	v_rcp_f32_e32 v72, v72
	v_mul_f32_e32 v70, v70, v120
	v_mul_f32_e32 v152, v70, v106
	v_and_b32_e32 v70, 0xffff0000, v103
	v_fmac_f32_e32 v70, v123, v73
	v_mul_f32_e32 v71, v72, v71
	v_mul_f32_e32 v153, v71, v70
	s_waitcnt vmcnt(14)
	v_lshlrev_b32_e32 v70, 16, v98
	v_mul_f32_e32 v71, 0xbfb8aa3b, v70
	v_exp_f32_e32 v71, v71
	v_and_b32_e32 v73, 0xffff0000, v98
	v_mfma_f32_16x16x32_bf16 v[38:41], v[138:141], v[2:5], v[38:41]
	v_mul_f32_e32 v98, 0xbfb8aa3b, v73
	v_add_f32_e32 v71, 1.0, v71
	v_rcp_f32_e32 v71, v71
	v_exp_f32_e32 v98, v98
	v_lshlrev_b32_e32 v72, 16, v94
	s_nop 2
	v_fmac_f32_e32 v72, v123, v38
	v_mul_f32_e32 v38, v71, v70
	v_mul_f32_e32 v154, v38, v72
	v_add_f32_e32 v38, 1.0, v98
	v_lshlrev_b32_e32 v70, 16, v99
	v_rcp_f32_e32 v38, v38
	v_mul_f32_e32 v71, 0xbfb8aa3b, v70
	v_exp_f32_e32 v71, v71
	v_and_b32_e32 v72, 0xffff0000, v94
	v_fmac_f32_e32 v72, v123, v39
	v_mul_f32_e32 v38, v38, v73
	v_add_f32_e32 v39, 1.0, v71
	v_mul_f32_e32 v155, v38, v72
	v_lshlrev_b32_e32 v38, 16, v95
	v_and_b32_e32 v94, 0xffff0000, v99
	v_rcp_f32_e32 v39, v39
	v_fmac_f32_e32 v38, v123, v40
	v_mul_f32_e32 v40, 0xbfb8aa3b, v94
	v_exp_f32_e32 v40, v40
	v_mul_f32_e32 v39, v39, v70
	v_mul_f32_e32 v156, v39, v38
	v_and_b32_e32 v95, 0xffff0000, v95
	v_add_f32_e32 v38, 1.0, v40
	v_fmac_f32_e32 v95, v123, v41
	v_rcp_f32_e32 v98, v38
	v_cvt_pk_bf16_f32 v38, v50, v51
	v_cvt_pk_bf16_f32 v39, v52, v53
	v_cvt_pk_bf16_f32 v40, v62, v63
	v_cvt_pk_bf16_f32 v41, v64, v65
	v_cvt_pk_bf16_f32 v50, v58, v59
	v_cvt_pk_bf16_f32 v51, v60, v61
	v_cvt_pk_bf16_f32 v52, v46, v47
	v_cvt_pk_bf16_f32 v53, v48, v49
	ds_write_b128 v128, v[38:41] offset:34816
	ds_write_b128 v128, v[50:53] offset:34832
	s_waitcnt lgkmcnt(0)
	s_barrier
	ds_read_b128 v[38:41], v129 offset:34816
	ds_read_b128 v[46:49], v129 offset:34880
	ds_read_b128 v[50:53], v129 offset:39168
	ds_read_b128 v[58:61], v129 offset:39232
	ds_read_b128 v[62:65], v129 offset:34944
	ds_read_b128 v[70:73], v129 offset:35008
	ds_read_b128 v[138:141], v129 offset:39296
	ds_read_b128 v[158:161], v129 offset:39360
	v_mul_f32_e32 v94, v98, v94
	v_mul_f32_e32 v157, v94, v95
	v_cvt_pk_bf16_f32 v121, v137, v151
	v_cvt_pk_bf16_f32 v120, v152, v153
	v_cvt_pk_bf16_f32 v124, v154, v155
	v_cvt_pk_bf16_f32 v123, v156, v157
	s_waitcnt lgkmcnt(7)
	v_mfma_f32_16x16x32_bf16 v[162:165], v[38:41], v[30:33], 0
	s_waitcnt vmcnt(5)
	v_lshlrev_b32_e32 v95, 16, v172
	v_mul_f32_e32 v98, 0xbfb8aa3b, v95
	v_exp_f32_e32 v98, v98
	s_waitcnt lgkmcnt(6)
	v_mfma_f32_16x16x32_bf16 v[162:165], v[46:49], v[22:25], v[162:165]
	v_and_b32_e32 v102, 0xffff0000, v172
	v_mul_f32_e32 v103, 0xbfb8aa3b, v102
	v_add_f32_e32 v98, 1.0, v98
	s_waitcnt lgkmcnt(3)
	v_mfma_f32_16x16x32_bf16 v[162:165], v[62:65], v[14:17], v[162:165]
	v_rcp_f32_e32 v98, v98
	v_exp_f32_e32 v103, v103
	v_mul_f32_e32 v94, 0x3fb8aa3b, v149
	v_exp_f32_e32 v94, v94
	s_waitcnt lgkmcnt(2)
	v_mfma_f32_16x16x32_bf16 v[162:165], v[70:73], v[6:9], v[162:165]
	v_mul_f32_e32 v95, v98, v95
	v_add_f32_e32 v98, 1.0, v103
	v_rcp_f32_e32 v98, v98
	v_lshlrev_b32_e32 v99, 16, v142
	v_mfma_f32_16x16x32_bf16 v[38:41], v[38:41], v[26:29], 0
	s_nop 2
	v_fmac_f32_e32 v99, v94, v162
	v_mul_f32_e32 v95, v95, v99
	v_and_b32_e32 v99, 0xffff0000, v142
	v_fmac_f32_e32 v99, v94, v163
	v_mul_f32_e32 v98, v98, v102
	v_mul_f32_e32 v98, v98, v99
	v_lshlrev_b32_e32 v99, 16, v173
	v_mul_f32_e32 v102, 0xbfb8aa3b, v99
	v_mfma_f32_16x16x32_bf16 v[38:41], v[46:49], v[18:21], v[38:41]
	v_exp_f32_e32 v102, v102
	v_lshlrev_b32_e32 v103, 16, v143
	v_fmac_f32_e32 v103, v94, v164
	v_mfma_f32_16x16x32_bf16 v[166:169], v[50:53], v[30:33], 0
	v_add_f32_e32 v102, 1.0, v102
	v_rcp_f32_e32 v102, v102
	v_and_b32_e32 v106, 0xffff0000, v173
	v_mfma_f32_16x16x32_bf16 v[50:53], v[50:53], v[26:29], 0
	v_mul_f32_e32 v107, 0xbfb8aa3b, v106
	s_or_b32 s20, s40, 3
	s_or_b32 s16, s39, s20
	v_mfma_f32_16x16x32_bf16 v[38:41], v[62:65], v[10:13], v[38:41]
	s_lshl_b64 s[18:19], s[16:17], 15
	s_add_u32 s18, s74, s18
	s_addc_u32 s19, s75, s19
	v_mfma_f32_16x16x32_bf16 v[166:169], v[58:61], v[22:25], v[166:169]
	v_cvt_pk_bf16_f32 v42, v42, v43
	v_cvt_pk_bf16_f32 v43, v44, v45
	v_cvt_pk_bf16_f32 v44, v66, v67
	v_mfma_f32_16x16x32_bf16 v[46:49], v[58:61], v[18:21], v[50:53]
	v_exp_f32_e32 v58, v107
	v_and_b32_e32 v60, 0xffff0000, v143
	v_fmac_f32_e32 v60, v94, v165
	v_mfma_f32_16x16x32_bf16 v[70:73], v[70:73], v[2:5], v[38:41]
	v_mul_f32_e32 v50, v102, v99
	v_mul_f32_e32 v59, v50, v103
	v_add_f32_e32 v58, 1.0, v58
	s_waitcnt vmcnt(4)
	v_lshlrev_b32_e32 v38, 16, v174
	v_mul_f32_e32 v39, 0xbfb8aa3b, v38
	v_exp_f32_e32 v39, v39
	s_waitcnt lgkmcnt(1)
	v_mfma_f32_16x16x32_bf16 v[50:53], v[138:141], v[14:17], v[166:169]
	v_and_b32_e32 v41, 0xffff0000, v174
	v_lshlrev_b32_e32 v40, 16, v170
	v_add_f32_e32 v39, 1.0, v39
	v_mfma_f32_16x16x32_bf16 v[46:49], v[138:141], v[10:13], v[46:49]
	v_rcp_f32_e32 v39, v39
	v_rcp_f32_e32 v58, v58
	s_waitcnt vmcnt(1)
	v_lshlrev_b32_e32 v138, 16, v109
	s_waitcnt lgkmcnt(0)
	v_mfma_f32_16x16x32_bf16 v[50:53], v[158:161], v[6:9], v[50:53]
	v_mul_f32_e32 v38, v39, v38
	v_and_b32_e32 v39, 0xffff0000, v170
	v_mul_f32_e32 v58, v58, v106
	v_mfma_f32_16x16x32_bf16 v[62:65], v[158:161], v[2:5], v[46:49]
	v_mul_f32_e32 v58, v58, v60
	s_nop 2
	v_fmac_f32_e32 v40, v94, v50
	v_mul_f32_e32 v38, v38, v40
	v_mul_f32_e32 v46, 0xbfb8aa3b, v41
	v_exp_f32_e32 v46, v46
	v_fmac_f32_e32 v39, v94, v51
	v_mul_f32_e32 v60, v98, v98
	v_fmac_f32_e32 v60, v95, v95
	v_add_f32_e32 v40, 1.0, v46
	v_lshlrev_b32_e32 v46, 16, v175
	v_rcp_f32_e32 v40, v40
	v_mul_f32_e32 v47, 0xbfb8aa3b, v46
	v_exp_f32_e32 v47, v47
	v_lshlrev_b32_e32 v48, 16, v171
	v_mul_f32_e32 v40, v40, v41
	v_and_b32_e32 v41, 0xffff0000, v175
	v_mul_f32_e32 v39, v40, v39
	v_add_f32_e32 v40, 1.0, v47
	v_mul_f32_e32 v47, 0xbfb8aa3b, v41
	v_rcp_f32_e32 v40, v40
	v_exp_f32_e32 v47, v47
	v_cvt_pk_bf16_f32 v149, v38, v39
	v_fmac_f32_e32 v60, v59, v59
	v_mul_f32_e32 v40, v40, v46
	v_add_f32_e32 v46, 1.0, v47
	v_rcp_f32_e32 v46, v46
	v_fmac_f32_e32 v48, v94, v52
	v_and_b32_e32 v47, 0xffff0000, v171
	v_fmac_f32_e32 v60, v58, v58
	v_mul_f32_e32 v41, v46, v41
	v_mul_f32_e32 v46, v39, v39
	v_fmac_f32_e32 v46, v38, v38
	v_mul_f32_e32 v38, 0x3fb8aa3b, v176
	v_exp_f32_e32 v142, v38
	v_lshlrev_b32_e32 v38, 16, v108
	v_mul_f32_e32 v39, 0xbfb8aa3b, v38
	v_exp_f32_e32 v39, v39
	v_mul_f32_e32 v40, v40, v48
	v_fmac_f32_e32 v47, v94, v53
	v_add_f32_e32 v60, v150, v60
	v_mul_f32_e32 v41, v41, v47
	v_fmac_f32_e32 v46, v40, v40
	v_cvt_pk_bf16_f32 v150, v40, v41
	v_lshlrev_b32_e32 v40, 16, v104
	v_fmac_f32_e32 v40, v142, v70
	v_add_f32_e32 v39, 1.0, v39
	v_and_b32_e32 v70, 0xffff0000, v108
	v_fmac_f32_e32 v46, v41, v41
	v_rcp_f32_e32 v39, v39
	v_mul_f32_e32 v41, 0xbfb8aa3b, v70
	v_exp_f32_e32 v41, v41
	v_cvt_pk_bf16_f32 v140, v95, v98
	v_mul_f32_e32 v38, v39, v38
	v_mul_f32_e32 v160, v38, v40
	v_add_f32_e32 v38, 1.0, v41
	v_rcp_f32_e32 v108, v38
	v_mul_f32_e32 v38, 0xbfb8aa3b, v138
	v_exp_f32_e32 v139, v38
	v_lshl_add_u64 v[38:39], s[18:19], 0, v[92:93]
	s_lshl_b64 s[18:19], s[16:17], 9
	s_add_u32 s18, s26, s18
	s_addc_u32 s19, s27, s19
	s_lshl_b32 s16, s20, 7
	s_add_u32 s20, s24, s16
	s_addc_u32 s21, s25, 0
	v_lshl_add_u64 v[38:39], v[38:39], 0, v[74:75]
	s_add_u32 s22, s60, s16
	v_cvt_pk_bf16_f32 v141, v59, v58
	v_lshl_add_u64 v[58:59], v[38:39], 0, s[14:15]
	v_add_co_u32_e32 v38, vcc, s35, v38
	s_addc_u32 s23, s61, 0
	v_lshl_add_u64 v[98:99], s[20:21], 0, v[88:89]
	v_addc_co_u32_e32 v39, vcc, 0, v39, vcc
	v_lshl_add_u64 v[94:95], s[18:19], 0, v[86:87]
	v_mov_b64_e32 v[102:103], s[22:23]
	v_lshl_add_u64 v[98:99], v[98:99], 0, v[76:77]
	v_add_f32_e32 v161, v60, v46
	global_load_dwordx4 v[46:49], v[38:39], off
	s_nop 0
	global_load_dwordx4 v[38:41], v[58:59], off offset:48
	global_load_dwordx4 v[50:53], v[58:59], off offset:32
	s_nop 0
	global_load_dwordx4 v[58:61], v[58:59], off offset:16
	v_mad_u64_u32 v[106:107], s[18:19], v82, s28, v[102:103]
	global_load_dword v166, v[94:95], off
	global_load_dwordx2 v[158:159], v[98:99], off
	global_load_dwordx2 v[182:183], v[98:99], off offset:32
	global_load_dword v185, v[94:95], off offset:64
	v_mad_u64_u32 v[98:99], s[18:19], v84, s28, v[102:103]
	v_add_u32_e32 v107, v81, v107
	v_lshl_add_u64 v[94:95], s[20:21], 0, v[90:91]
	v_add_u32_e32 v99, v79, v99
	v_lshl_add_u64 v[106:107], v[106:107], 0, v[76:77]
	v_lshl_add_u64 v[94:95], v[94:95], 0, v[76:77]
	v_lshl_add_u64 v[98:99], v[98:99], 0, v[76:77]
	global_load_dwordx2 v[190:191], v[106:107], off
	global_load_dwordx2 v[192:193], v[106:107], off offset:32
	global_load_dwordx2 v[102:103], v[94:95], off
	s_nop 0
	global_load_dwordx2 v[94:95], v[94:95], off offset:32
	s_nop 0
	global_load_dwordx2 v[106:107], v[98:99], off
	s_nop 0
	global_load_dwordx2 v[98:99], v[98:99], off offset:32
	v_and_b32_e32 v104, 0xffff0000, v104
	v_fmac_f32_e32 v104, v142, v71
	v_mul_f32_e32 v70, v108, v70
	v_and_b32_e32 v71, 0xffff0000, v109
	v_mul_f32_e32 v167, v70, v104
	v_mul_f32_e32 v104, 0xbfb8aa3b, v71
	v_exp_f32_e32 v104, v104
	v_add_f32_e32 v70, 1.0, v139
	v_rcp_f32_e32 v70, v70
	v_lshlrev_b32_e32 v108, 16, v105
	v_fmac_f32_e32 v108, v142, v72
	v_add_f32_e32 v72, 1.0, v104
	v_rcp_f32_e32 v72, v72
	v_mul_f32_e32 v70, v70, v138
	v_mul_f32_e32 v168, v70, v108
	v_and_b32_e32 v70, 0xffff0000, v105
	v_fmac_f32_e32 v70, v142, v73
	v_mul_f32_e32 v71, v72, v71
	v_mul_f32_e32 v169, v71, v70
	s_waitcnt vmcnt(14)
	v_lshlrev_b32_e32 v70, 16, v100
	v_mul_f32_e32 v71, 0xbfb8aa3b, v70
	v_exp_f32_e32 v71, v71
	v_and_b32_e32 v73, 0xffff0000, v100
	v_mul_f32_e32 v100, 0xbfb8aa3b, v73
	v_exp_f32_e32 v100, v100
	v_add_f32_e32 v71, 1.0, v71
	v_rcp_f32_e32 v71, v71
	v_lshlrev_b32_e32 v72, 16, v96
	v_fmac_f32_e32 v72, v142, v62
	v_cvt_pk_bf16_f32 v45, v68, v69
	v_mul_f32_e32 v62, v71, v70
	v_mul_f32_e32 v170, v62, v72
	v_add_f32_e32 v62, 1.0, v100
	v_lshlrev_b32_e32 v70, 16, v101
	v_rcp_f32_e32 v62, v62
	v_mul_f32_e32 v71, 0xbfb8aa3b, v70
	v_exp_f32_e32 v71, v71
	v_and_b32_e32 v72, 0xffff0000, v96
	v_fmac_f32_e32 v72, v142, v63
	v_mul_f32_e32 v62, v62, v73
	v_add_f32_e32 v63, 1.0, v71
	v_mul_f32_e32 v171, v62, v72
	v_lshlrev_b32_e32 v62, 16, v97
	v_and_b32_e32 v96, 0xffff0000, v101
	v_rcp_f32_e32 v63, v63
	v_fmac_f32_e32 v62, v142, v64
	v_mul_f32_e32 v64, 0xbfb8aa3b, v96
	v_exp_f32_e32 v64, v64
	v_mul_f32_e32 v63, v63, v70
	v_mul_f32_e32 v172, v63, v62
	v_and_b32_e32 v97, 0xffff0000, v97
	v_add_f32_e32 v62, 1.0, v64
	v_cvt_pk_bf16_f32 v54, v54, v55
	v_cvt_pk_bf16_f32 v55, v56, v57
	v_cvt_pk_bf16_f32 v56, v34, v35
	v_cvt_pk_bf16_f32 v57, v36, v37
	v_fmac_f32_e32 v97, v142, v65
	v_rcp_f32_e32 v100, v62
	ds_write_b128 v128, v[42:45] offset:52224
	ds_write_b128 v128, v[54:57] offset:52240
	s_waitcnt lgkmcnt(0)
	s_barrier
	ds_read_b128 v[34:37], v129 offset:52224
	ds_read_b128 v[42:45], v129 offset:52288
	ds_read_b128 v[54:57], v129 offset:56576
	ds_read_b128 v[62:65], v129 offset:56640
	ds_read_b128 v[66:69], v129 offset:52352
	ds_read_b128 v[70:73], v129 offset:52416
	ds_read_b128 v[162:165], v129 offset:56704
	ds_read_b128 v[174:177], v129 offset:56768
	v_mul_f32_e32 v96, v100, v96
	v_mul_f32_e32 v173, v96, v97
	v_cvt_pk_bf16_f32 v139, v160, v167
	v_cvt_pk_bf16_f32 v138, v168, v169
	v_cvt_pk_bf16_f32 v143, v170, v171
	v_cvt_pk_bf16_f32 v142, v172, v173
	s_waitcnt lgkmcnt(7)
	v_mfma_f32_16x16x32_bf16 v[178:181], v[34:37], v[30:33], 0
	s_waitcnt vmcnt(5)
	v_lshlrev_b32_e32 v97, 16, v190
	v_mul_f32_e32 v100, 0xbfb8aa3b, v97
	v_exp_f32_e32 v100, v100
	s_waitcnt lgkmcnt(6)
	v_mfma_f32_16x16x32_bf16 v[178:181], v[42:45], v[22:25], v[178:181]
	v_and_b32_e32 v104, 0xffff0000, v190
	v_mul_f32_e32 v105, 0xbfb8aa3b, v104
	v_add_f32_e32 v100, 1.0, v100
	s_waitcnt lgkmcnt(3)
	v_mfma_f32_16x16x32_bf16 v[178:181], v[66:69], v[14:17], v[178:181]
	v_rcp_f32_e32 v100, v100
	v_exp_f32_e32 v105, v105
	v_mul_f32_e32 v96, 0x3fb8aa3b, v166
	v_exp_f32_e32 v96, v96
	s_waitcnt lgkmcnt(2)
	v_mfma_f32_16x16x32_bf16 v[178:181], v[70:73], v[6:9], v[178:181]
	v_mul_f32_e32 v97, v100, v97
	v_add_f32_e32 v100, 1.0, v105
	v_rcp_f32_e32 v100, v100
	v_lshlrev_b32_e32 v101, 16, v158
	v_mfma_f32_16x16x32_bf16 v[34:37], v[34:37], v[26:29], 0
	s_nop 2
	v_fmac_f32_e32 v101, v96, v178
	v_mul_f32_e32 v97, v97, v101
	v_and_b32_e32 v101, 0xffff0000, v158
	v_fmac_f32_e32 v101, v96, v179
	v_mul_f32_e32 v100, v100, v104
	v_mul_f32_e32 v100, v100, v101
	v_lshlrev_b32_e32 v101, 16, v191
	v_mul_f32_e32 v104, 0xbfb8aa3b, v101
	v_mfma_f32_16x16x32_bf16 v[34:37], v[42:45], v[18:21], v[34:37]
	v_exp_f32_e32 v104, v104
	v_lshlrev_b32_e32 v105, 16, v159
	v_fmac_f32_e32 v105, v96, v180
	v_mfma_f32_16x16x32_bf16 v[186:189], v[54:57], v[30:33], 0
	v_add_f32_e32 v104, 1.0, v104
	v_rcp_f32_e32 v104, v104
	v_and_b32_e32 v108, 0xffff0000, v191
	v_mfma_f32_16x16x32_bf16 v[54:57], v[54:57], v[26:29], 0
	v_mul_f32_e32 v109, 0xbfb8aa3b, v108
	s_or_b32 s20, s40, 4
	s_or_b32 s16, s39, s20
	v_mfma_f32_16x16x32_bf16 v[34:37], v[66:69], v[10:13], v[34:37]
	s_lshl_b64 s[18:19], s[16:17], 15
	s_waitcnt vmcnt(1)
	v_lshlrev_b32_e32 v158, 16, v107
	s_add_u32 s18, s74, s18
	v_mfma_f32_16x16x32_bf16 v[186:189], v[62:65], v[22:25], v[186:189]
	s_addc_u32 s19, s75, s19
	v_cvt_pk_bf16_f32 v46, v46, v47
	v_cvt_pk_bf16_f32 v47, v48, v49
	v_mfma_f32_16x16x32_bf16 v[42:45], v[62:65], v[18:21], v[54:57]
	v_exp_f32_e32 v62, v109
	v_and_b32_e32 v64, 0xffff0000, v159
	v_fmac_f32_e32 v64, v96, v181
	v_mfma_f32_16x16x32_bf16 v[70:73], v[70:73], v[2:5], v[34:37]
	v_mul_f32_e32 v54, v104, v101
	v_mul_f32_e32 v63, v54, v105
	v_add_f32_e32 v62, 1.0, v62
	v_lshlrev_b32_e32 v34, 16, v192
	v_mul_f32_e32 v35, 0xbfb8aa3b, v34
	v_exp_f32_e32 v35, v35
	s_waitcnt lgkmcnt(1)
	v_mfma_f32_16x16x32_bf16 v[54:57], v[162:165], v[14:17], v[186:189]
	v_and_b32_e32 v37, 0xffff0000, v192
	v_lshlrev_b32_e32 v36, 16, v182
	v_add_f32_e32 v35, 1.0, v35
	v_mfma_f32_16x16x32_bf16 v[42:45], v[162:165], v[10:13], v[42:45]
	v_rcp_f32_e32 v35, v35
	v_rcp_f32_e32 v62, v62
	v_cvt_pk_bf16_f32 v48, v58, v59
	s_waitcnt lgkmcnt(0)
	v_mfma_f32_16x16x32_bf16 v[54:57], v[174:177], v[6:9], v[54:57]
	v_mul_f32_e32 v34, v35, v34
	v_and_b32_e32 v35, 0xffff0000, v182
	v_mul_f32_e32 v62, v62, v108
	v_mfma_f32_16x16x32_bf16 v[66:69], v[174:177], v[2:5], v[42:45]
	v_mul_f32_e32 v62, v62, v64
	s_nop 2
	v_fmac_f32_e32 v36, v96, v54
	v_mul_f32_e32 v34, v34, v36
	v_mul_f32_e32 v42, 0xbfb8aa3b, v37
	v_exp_f32_e32 v42, v42
	v_fmac_f32_e32 v35, v96, v55
	v_lshlrev_b32_e32 v44, 16, v183
	v_fmac_f32_e32 v44, v96, v56
	v_add_f32_e32 v36, 1.0, v42
	v_lshlrev_b32_e32 v42, 16, v193
	v_rcp_f32_e32 v36, v36
	v_mul_f32_e32 v43, 0xbfb8aa3b, v42
	v_exp_f32_e32 v43, v43
	v_mul_f32_e32 v64, v100, v100
	v_mul_f32_e32 v36, v36, v37
	v_and_b32_e32 v37, 0xffff0000, v193
	v_mul_f32_e32 v35, v36, v35
	v_add_f32_e32 v36, 1.0, v43
	v_mul_f32_e32 v43, 0xbfb8aa3b, v37
	v_rcp_f32_e32 v36, v36
	v_exp_f32_e32 v43, v43
	v_cvt_pk_bf16_f32 v165, v34, v35
	v_fmac_f32_e32 v64, v97, v97
	v_mul_f32_e32 v36, v36, v42
	v_add_f32_e32 v42, 1.0, v43
	v_rcp_f32_e32 v42, v42
	v_and_b32_e32 v43, 0xffff0000, v183
	v_mul_f32_e32 v36, v36, v44
	v_fmac_f32_e32 v43, v96, v57
	v_mul_f32_e32 v37, v42, v37
	v_mul_f32_e32 v42, v35, v35
	v_fmac_f32_e32 v42, v34, v34
	v_mul_f32_e32 v34, 0x3fb8aa3b, v185
	v_exp_f32_e32 v163, v34
	v_lshlrev_b32_e32 v34, 16, v106
	v_mul_f32_e32 v35, 0xbfb8aa3b, v34
	v_exp_f32_e32 v35, v35
	v_mul_f32_e32 v37, v37, v43
	v_fmac_f32_e32 v42, v36, v36
	v_cvt_pk_bf16_f32 v166, v36, v37
	v_lshlrev_b32_e32 v36, 16, v102
	v_fmac_f32_e32 v36, v163, v70
	v_add_f32_e32 v35, 1.0, v35
	v_and_b32_e32 v70, 0xffff0000, v106
	v_fmac_f32_e32 v42, v37, v37
	v_rcp_f32_e32 v35, v35
	v_mul_f32_e32 v37, 0xbfb8aa3b, v70
	v_exp_f32_e32 v37, v37
	v_fmac_f32_e32 v64, v63, v63
	v_mul_f32_e32 v34, v35, v34
	v_mul_f32_e32 v176, v34, v36
	v_add_f32_e32 v34, 1.0, v37
	v_rcp_f32_e32 v106, v34
	v_mul_f32_e32 v34, 0xbfb8aa3b, v158
	v_exp_f32_e32 v159, v34
	v_lshl_add_u64 v[34:35], s[18:19], 0, v[92:93]
	s_lshl_b64 s[18:19], s[16:17], 9
	s_add_u32 s18, s26, s18
	s_addc_u32 s19, s27, s19
	s_lshl_b32 s16, s20, 7
	s_add_u32 s20, s24, s16
	s_addc_u32 s21, s25, 0
	v_fmac_f32_e32 v64, v62, v62
	v_lshl_add_u64 v[34:35], v[34:35], 0, v[74:75]
	s_add_u32 s22, s60, s16
	v_add_f32_e32 v64, v161, v64
	v_cvt_pk_bf16_f32 v161, v97, v100
	v_cvt_pk_bf16_f32 v162, v63, v62
	v_lshl_add_u64 v[62:63], v[34:35], 0, s[14:15]
	v_add_co_u32_e32 v34, vcc, s35, v34
	s_addc_u32 s23, s61, 0
	v_lshl_add_u64 v[100:101], s[20:21], 0, v[88:89]
	v_addc_co_u32_e32 v35, vcc, 0, v35, vcc
	v_lshl_add_u64 v[96:97], s[18:19], 0, v[86:87]
	v_mov_b64_e32 v[104:105], s[22:23]
	v_lshl_add_u64 v[100:101], v[100:101], 0, v[76:77]
	v_add_f32_e32 v177, v64, v42
	global_load_dwordx4 v[42:45], v[34:35], off
	s_nop 0
	global_load_dwordx4 v[34:37], v[62:63], off offset:48
	global_load_dwordx4 v[54:57], v[62:63], off offset:32
	s_nop 0
	global_load_dwordx4 v[62:65], v[62:63], off offset:16
	v_mad_u64_u32 v[108:109], s[18:19], v82, s28, v[104:105]
	global_load_dword v180, v[96:97], off
	global_load_dwordx2 v[174:175], v[100:101], off
	global_load_dwordx2 v[178:179], v[100:101], off offset:32
	global_load_dword v189, v[96:97], off offset:64
	v_mad_u64_u32 v[100:101], s[18:19], v84, s28, v[104:105]
	v_add_u32_e32 v109, v81, v109
	v_lshl_add_u64 v[96:97], s[20:21], 0, v[90:91]
	v_add_u32_e32 v101, v79, v101
	v_lshl_add_u64 v[108:109], v[108:109], 0, v[76:77]
	v_lshl_add_u64 v[96:97], v[96:97], 0, v[76:77]
	v_lshl_add_u64 v[100:101], v[100:101], 0, v[76:77]
	global_load_dwordx2 v[206:207], v[108:109], off
	global_load_dwordx2 v[208:209], v[108:109], off offset:32
	global_load_dwordx2 v[104:105], v[96:97], off
	s_nop 0
	global_load_dwordx2 v[96:97], v[96:97], off offset:32
	s_nop 0
	global_load_dwordx2 v[108:109], v[100:101], off
	s_nop 0
	global_load_dwordx2 v[100:101], v[100:101], off offset:32
	v_and_b32_e32 v102, 0xffff0000, v102
	v_fmac_f32_e32 v102, v163, v71
	v_mul_f32_e32 v70, v106, v70
	v_and_b32_e32 v71, 0xffff0000, v107
	v_mul_f32_e32 v181, v70, v102
	v_mul_f32_e32 v102, 0xbfb8aa3b, v71
	v_exp_f32_e32 v102, v102
	v_add_f32_e32 v70, 1.0, v159
	v_rcp_f32_e32 v70, v70
	v_lshlrev_b32_e32 v106, 16, v103
	v_fmac_f32_e32 v106, v163, v72
	v_add_f32_e32 v72, 1.0, v102
	v_rcp_f32_e32 v72, v72
	v_mul_f32_e32 v70, v70, v158
	v_mul_f32_e32 v182, v70, v106
	v_and_b32_e32 v70, 0xffff0000, v103
	v_fmac_f32_e32 v70, v163, v73
	v_mul_f32_e32 v71, v72, v71
	v_mul_f32_e32 v183, v71, v70
	s_waitcnt vmcnt(14)
	v_lshlrev_b32_e32 v70, 16, v98
	v_mul_f32_e32 v71, 0xbfb8aa3b, v70
	v_exp_f32_e32 v71, v71
	v_and_b32_e32 v73, 0xffff0000, v98
	v_mul_f32_e32 v98, 0xbfb8aa3b, v73
	v_exp_f32_e32 v98, v98
	v_add_f32_e32 v71, 1.0, v71
	v_rcp_f32_e32 v71, v71
	v_lshlrev_b32_e32 v72, 16, v94
	v_fmac_f32_e32 v72, v163, v66
	v_cvt_pk_bf16_f32 v49, v60, v61
	v_mul_f32_e32 v66, v71, v70
	v_mul_f32_e32 v185, v66, v72
	v_add_f32_e32 v66, 1.0, v98
	v_lshlrev_b32_e32 v70, 16, v99
	v_rcp_f32_e32 v66, v66
	v_mul_f32_e32 v71, 0xbfb8aa3b, v70
	v_exp_f32_e32 v71, v71
	v_and_b32_e32 v72, 0xffff0000, v94
	v_fmac_f32_e32 v72, v163, v67
	v_mul_f32_e32 v66, v66, v73
	v_add_f32_e32 v67, 1.0, v71
	v_mul_f32_e32 v186, v66, v72
	v_lshlrev_b32_e32 v66, 16, v95
	v_and_b32_e32 v94, 0xffff0000, v99
	v_rcp_f32_e32 v67, v67
	v_fmac_f32_e32 v66, v163, v68
	v_mul_f32_e32 v68, 0xbfb8aa3b, v94
	v_exp_f32_e32 v68, v68
	v_mul_f32_e32 v67, v67, v70
	v_mul_f32_e32 v187, v67, v66
	v_and_b32_e32 v95, 0xffff0000, v95
	v_add_f32_e32 v66, 1.0, v68
	v_cvt_pk_bf16_f32 v50, v50, v51
	v_cvt_pk_bf16_f32 v51, v52, v53
	v_cvt_pk_bf16_f32 v52, v38, v39
	v_cvt_pk_bf16_f32 v53, v40, v41
	v_fmac_f32_e32 v95, v163, v69
	v_rcp_f32_e32 v98, v66
	ds_write_b128 v128, v[46:49] offset:34816
	ds_write_b128 v128, v[50:53] offset:34832
	s_waitcnt lgkmcnt(0)
	s_barrier
	ds_read_b128 v[38:41], v129 offset:34816
	ds_read_b128 v[46:49], v129 offset:34880
	ds_read_b128 v[50:53], v129 offset:39168
	ds_read_b128 v[58:61], v129 offset:39232
	ds_read_b128 v[66:69], v129 offset:34944
	ds_read_b128 v[70:73], v129 offset:35008
	ds_read_b128 v[190:193], v129 offset:39296
	ds_read_b128 v[194:197], v129 offset:39360
	v_mul_f32_e32 v94, v98, v94
	v_mul_f32_e32 v188, v94, v95
	v_cvt_pk_bf16_f32 v159, v176, v181
	v_cvt_pk_bf16_f32 v158, v182, v183
	v_cvt_pk_bf16_f32 v164, v185, v186
	v_cvt_pk_bf16_f32 v163, v187, v188
	s_waitcnt lgkmcnt(7)
	v_mfma_f32_16x16x32_bf16 v[198:201], v[38:41], v[30:33], 0
	s_waitcnt vmcnt(5)
	v_lshlrev_b32_e32 v95, 16, v206
	v_mul_f32_e32 v98, 0xbfb8aa3b, v95
	v_exp_f32_e32 v98, v98
	s_waitcnt lgkmcnt(6)
	v_mfma_f32_16x16x32_bf16 v[198:201], v[46:49], v[22:25], v[198:201]
	v_and_b32_e32 v102, 0xffff0000, v206
	v_mul_f32_e32 v103, 0xbfb8aa3b, v102
	v_add_f32_e32 v98, 1.0, v98
	s_waitcnt lgkmcnt(3)
	v_mfma_f32_16x16x32_bf16 v[198:201], v[66:69], v[14:17], v[198:201]
	v_rcp_f32_e32 v98, v98
	v_exp_f32_e32 v103, v103
	v_mul_f32_e32 v94, 0x3fb8aa3b, v180
	v_exp_f32_e32 v94, v94
	s_waitcnt lgkmcnt(2)
	v_mfma_f32_16x16x32_bf16 v[198:201], v[70:73], v[6:9], v[198:201]
	v_mul_f32_e32 v95, v98, v95
	v_add_f32_e32 v98, 1.0, v103
	v_rcp_f32_e32 v98, v98
	v_lshlrev_b32_e32 v99, 16, v174
	v_mfma_f32_16x16x32_bf16 v[38:41], v[38:41], v[26:29], 0
	s_nop 2
	v_fmac_f32_e32 v99, v94, v198
	v_mul_f32_e32 v95, v95, v99
	v_and_b32_e32 v99, 0xffff0000, v174
	v_fmac_f32_e32 v99, v94, v199
	v_mul_f32_e32 v98, v98, v102
	v_mul_f32_e32 v98, v98, v99
	v_lshlrev_b32_e32 v99, 16, v207
	v_mul_f32_e32 v102, 0xbfb8aa3b, v99
	v_mfma_f32_16x16x32_bf16 v[38:41], v[46:49], v[18:21], v[38:41]
	v_exp_f32_e32 v102, v102
	v_lshlrev_b32_e32 v103, 16, v175
	v_fmac_f32_e32 v103, v94, v200
	v_mfma_f32_16x16x32_bf16 v[202:205], v[50:53], v[30:33], 0
	v_add_f32_e32 v102, 1.0, v102
	v_rcp_f32_e32 v102, v102
	v_and_b32_e32 v106, 0xffff0000, v207
	v_mfma_f32_16x16x32_bf16 v[50:53], v[50:53], v[26:29], 0
	v_mul_f32_e32 v107, 0xbfb8aa3b, v106
	s_or_b32 s20, s40, 5
	s_or_b32 s16, s39, s20
	v_mfma_f32_16x16x32_bf16 v[38:41], v[66:69], v[10:13], v[38:41]
	s_lshl_b64 s[18:19], s[16:17], 15
	s_add_u32 s18, s74, s18
	s_addc_u32 s19, s75, s19
	v_mfma_f32_16x16x32_bf16 v[202:205], v[58:61], v[22:25], v[202:205]
	v_cvt_pk_bf16_f32 v174, v95, v98
	v_cvt_pk_bf16_f32 v42, v42, v43
	v_cvt_pk_bf16_f32 v43, v44, v45
	v_mfma_f32_16x16x32_bf16 v[46:49], v[58:61], v[18:21], v[50:53]
	v_exp_f32_e32 v58, v107
	v_and_b32_e32 v60, 0xffff0000, v175
	v_fmac_f32_e32 v60, v94, v201
	v_mfma_f32_16x16x32_bf16 v[70:73], v[70:73], v[2:5], v[38:41]
	v_mul_f32_e32 v50, v102, v99
	v_mul_f32_e32 v59, v50, v103
	v_add_f32_e32 v58, 1.0, v58
	s_waitcnt vmcnt(4)
	v_lshlrev_b32_e32 v38, 16, v208
	v_mul_f32_e32 v39, 0xbfb8aa3b, v38
	v_exp_f32_e32 v39, v39
	s_waitcnt lgkmcnt(1)
	v_mfma_f32_16x16x32_bf16 v[50:53], v[190:193], v[14:17], v[202:205]
	v_and_b32_e32 v41, 0xffff0000, v208
	v_lshlrev_b32_e32 v40, 16, v178
	v_add_f32_e32 v39, 1.0, v39
	v_mfma_f32_16x16x32_bf16 v[46:49], v[190:193], v[10:13], v[46:49]
	v_rcp_f32_e32 v39, v39
	v_rcp_f32_e32 v58, v58
	v_cvt_pk_bf16_f32 v44, v62, v63
	s_waitcnt lgkmcnt(0)
	v_mfma_f32_16x16x32_bf16 v[50:53], v[194:197], v[6:9], v[50:53]
	v_mul_f32_e32 v38, v39, v38
	v_and_b32_e32 v39, 0xffff0000, v178
	v_mul_f32_e32 v58, v58, v106
	v_mfma_f32_16x16x32_bf16 v[66:69], v[194:197], v[2:5], v[46:49]
	v_mul_f32_e32 v58, v58, v60
	s_nop 2
	v_fmac_f32_e32 v40, v94, v50
	v_mul_f32_e32 v38, v38, v40
	v_mul_f32_e32 v46, 0xbfb8aa3b, v41
	v_exp_f32_e32 v46, v46
	v_fmac_f32_e32 v39, v94, v51
	v_mul_f32_e32 v60, v98, v98
	v_fmac_f32_e32 v60, v95, v95
	v_add_f32_e32 v40, 1.0, v46
	v_lshlrev_b32_e32 v46, 16, v209
	v_rcp_f32_e32 v40, v40
	v_mul_f32_e32 v47, 0xbfb8aa3b, v46
	v_exp_f32_e32 v47, v47
	v_fmac_f32_e32 v60, v59, v59
	v_mul_f32_e32 v40, v40, v41
	v_and_b32_e32 v41, 0xffff0000, v209
	v_mul_f32_e32 v39, v40, v39
	v_add_f32_e32 v40, 1.0, v47
	v_mul_f32_e32 v47, 0xbfb8aa3b, v41
	v_rcp_f32_e32 v40, v40
	v_exp_f32_e32 v47, v47
	v_fmac_f32_e32 v60, v58, v58
	v_lshlrev_b32_e32 v48, 16, v179
	v_mul_f32_e32 v40, v40, v46
	v_add_f32_e32 v46, 1.0, v47
	v_rcp_f32_e32 v46, v46
	v_and_b32_e32 v47, 0xffff0000, v179
	v_cvt_pk_bf16_f32 v179, v38, v39
	v_add_f32_e32 v60, v177, v60
	v_mul_f32_e32 v41, v46, v41
	v_mul_f32_e32 v46, v39, v39
	v_fmac_f32_e32 v46, v38, v38
	v_mul_f32_e32 v38, 0x3fb8aa3b, v189
	v_exp_f32_e32 v177, v38
	s_waitcnt vmcnt(1)
	v_lshlrev_b32_e32 v38, 16, v108
	v_mul_f32_e32 v39, 0xbfb8aa3b, v38
	v_exp_f32_e32 v39, v39
	v_fmac_f32_e32 v48, v94, v52
	v_mul_f32_e32 v40, v40, v48
	v_fmac_f32_e32 v47, v94, v53
	v_mul_f32_e32 v41, v41, v47
	v_fmac_f32_e32 v46, v40, v40
	v_cvt_pk_bf16_f32 v180, v40, v41
	v_lshlrev_b32_e32 v40, 16, v104
	v_fmac_f32_e32 v40, v177, v70
	v_add_f32_e32 v39, 1.0, v39
	v_and_b32_e32 v70, 0xffff0000, v108
	v_fmac_f32_e32 v46, v41, v41
	v_rcp_f32_e32 v39, v39
	v_mul_f32_e32 v41, 0xbfb8aa3b, v70
	v_exp_f32_e32 v41, v41
	v_lshlrev_b32_e32 v178, 16, v109
	v_mul_f32_e32 v38, v39, v38
	v_mul_f32_e32 v191, v38, v40
	v_add_f32_e32 v38, 1.0, v41
	v_rcp_f32_e32 v108, v38
	v_mul_f32_e32 v38, 0xbfb8aa3b, v178
	v_exp_f32_e32 v189, v38
	v_lshl_add_u64 v[38:39], s[18:19], 0, v[92:93]
	s_lshl_b64 s[18:19], s[16:17], 9
	s_add_u32 s18, s26, s18
	s_addc_u32 s19, s27, s19
	s_lshl_b32 s16, s20, 7
	s_add_u32 s20, s24, s16
	s_addc_u32 s21, s25, 0
	v_lshl_add_u64 v[38:39], v[38:39], 0, v[74:75]
	s_add_u32 s22, s60, s16
	v_cvt_pk_bf16_f32 v175, v59, v58
	v_lshl_add_u64 v[58:59], v[38:39], 0, s[14:15]
	v_add_co_u32_e32 v38, vcc, s35, v38
	s_addc_u32 s23, s61, 0
	v_lshl_add_u64 v[98:99], s[20:21], 0, v[88:89]
	v_addc_co_u32_e32 v39, vcc, 0, v39, vcc
	v_lshl_add_u64 v[94:95], s[18:19], 0, v[86:87]
	v_mov_b64_e32 v[102:103], s[22:23]
	v_lshl_add_u64 v[98:99], v[98:99], 0, v[76:77]
	v_add_f32_e32 v190, v60, v46
	global_load_dwordx4 v[46:49], v[38:39], off
	s_nop 0
	global_load_dwordx4 v[38:41], v[58:59], off offset:48
	global_load_dwordx4 v[50:53], v[58:59], off offset:32
	s_nop 0
	global_load_dwordx4 v[58:61], v[58:59], off offset:16
	v_mad_u64_u32 v[106:107], s[18:19], v82, s28, v[102:103]
	global_load_dword v201, v[94:95], off
	global_load_dwordx2 v[192:193], v[98:99], off
	global_load_dwordx2 v[218:219], v[98:99], off offset:32
	global_load_dword v224, v[94:95], off offset:64
	v_mad_u64_u32 v[98:99], s[18:19], v84, s28, v[102:103]
	v_add_u32_e32 v107, v81, v107
	v_lshl_add_u64 v[94:95], s[20:21], 0, v[90:91]
	v_add_u32_e32 v99, v79, v99
	v_lshl_add_u64 v[106:107], v[106:107], 0, v[76:77]
	v_lshl_add_u64 v[94:95], v[94:95], 0, v[76:77]
	v_lshl_add_u64 v[98:99], v[98:99], 0, v[76:77]
	global_load_dwordx2 v[220:221], v[106:107], off
	global_load_dwordx2 v[222:223], v[106:107], off offset:32
	global_load_dwordx2 v[102:103], v[94:95], off
	s_nop 0
	global_load_dwordx2 v[94:95], v[94:95], off offset:32
	s_nop 0
	global_load_dwordx2 v[106:107], v[98:99], off
	s_nop 0
	global_load_dwordx2 v[98:99], v[98:99], off offset:32
	v_and_b32_e32 v104, 0xffff0000, v104
	v_fmac_f32_e32 v104, v177, v71
	v_mul_f32_e32 v70, v108, v70
	v_and_b32_e32 v71, 0xffff0000, v109
	v_mul_f32_e32 v194, v70, v104
	v_mul_f32_e32 v104, 0xbfb8aa3b, v71
	v_exp_f32_e32 v104, v104
	v_add_f32_e32 v70, 1.0, v189
	v_rcp_f32_e32 v70, v70
	v_lshlrev_b32_e32 v108, 16, v105
	v_fmac_f32_e32 v108, v177, v72
	v_add_f32_e32 v72, 1.0, v104
	v_rcp_f32_e32 v72, v72
	v_mul_f32_e32 v70, v70, v178
	v_mul_f32_e32 v195, v70, v108
	v_and_b32_e32 v70, 0xffff0000, v105
	v_fmac_f32_e32 v70, v177, v73
	v_mul_f32_e32 v71, v72, v71
	v_mul_f32_e32 v196, v71, v70
	s_waitcnt vmcnt(14)
	v_lshlrev_b32_e32 v70, 16, v100
	v_mul_f32_e32 v71, 0xbfb8aa3b, v70
	v_exp_f32_e32 v71, v71
	v_and_b32_e32 v73, 0xffff0000, v100
	v_mul_f32_e32 v100, 0xbfb8aa3b, v73
	v_exp_f32_e32 v100, v100
	v_add_f32_e32 v71, 1.0, v71
	v_rcp_f32_e32 v71, v71
	v_lshlrev_b32_e32 v72, 16, v96
	v_fmac_f32_e32 v72, v177, v66
	v_cvt_pk_bf16_f32 v45, v64, v65
	v_mul_f32_e32 v66, v71, v70
	v_mul_f32_e32 v197, v66, v72
	v_add_f32_e32 v66, 1.0, v100
	v_lshlrev_b32_e32 v70, 16, v101
	v_rcp_f32_e32 v66, v66
	v_mul_f32_e32 v71, 0xbfb8aa3b, v70
	v_exp_f32_e32 v71, v71
	v_and_b32_e32 v72, 0xffff0000, v96
	v_fmac_f32_e32 v72, v177, v67
	v_mul_f32_e32 v66, v66, v73
	v_add_f32_e32 v67, 1.0, v71
	v_mul_f32_e32 v198, v66, v72
	v_lshlrev_b32_e32 v66, 16, v97
	v_and_b32_e32 v96, 0xffff0000, v101
	v_rcp_f32_e32 v67, v67
	v_fmac_f32_e32 v66, v177, v68
	v_mul_f32_e32 v68, 0xbfb8aa3b, v96
	v_exp_f32_e32 v68, v68
	v_mul_f32_e32 v67, v67, v70
	v_mul_f32_e32 v199, v67, v66
	v_and_b32_e32 v97, 0xffff0000, v97
	v_add_f32_e32 v66, 1.0, v68
	v_cvt_pk_bf16_f32 v54, v54, v55
	v_cvt_pk_bf16_f32 v55, v56, v57
	v_cvt_pk_bf16_f32 v56, v34, v35
	v_cvt_pk_bf16_f32 v57, v36, v37
	v_fmac_f32_e32 v97, v177, v69
	v_rcp_f32_e32 v100, v66
	ds_write_b128 v128, v[42:45] offset:52224
	ds_write_b128 v128, v[54:57] offset:52240
	s_waitcnt lgkmcnt(0)
	s_barrier
	ds_read_b128 v[34:37], v129 offset:52224
	ds_read_b128 v[42:45], v129 offset:52288
	ds_read_b128 v[54:57], v129 offset:56576
	ds_read_b128 v[62:65], v129 offset:56640
	ds_read_b128 v[66:69], v129 offset:52352
	ds_read_b128 v[70:73], v129 offset:52416
	ds_read_b128 v[202:205], v129 offset:56704
	ds_read_b128 v[206:209], v129 offset:56768
	v_mul_f32_e32 v96, v100, v96
	v_mul_f32_e32 v200, v96, v97
	v_cvt_pk_bf16_f32 v109, v191, v194
	v_cvt_pk_bf16_f32 v108, v195, v196
	v_cvt_pk_bf16_f32 v178, v197, v198
	v_cvt_pk_bf16_f32 v177, v199, v200
	s_waitcnt lgkmcnt(7)
	v_mfma_f32_16x16x32_bf16 v[210:213], v[34:37], v[30:33], 0
	s_waitcnt vmcnt(5)
	v_lshlrev_b32_e32 v97, 16, v220
	v_mul_f32_e32 v100, 0xbfb8aa3b, v97
	v_exp_f32_e32 v100, v100
	s_waitcnt lgkmcnt(6)
	v_mfma_f32_16x16x32_bf16 v[210:213], v[42:45], v[22:25], v[210:213]
	v_and_b32_e32 v104, 0xffff0000, v220
	v_mul_f32_e32 v105, 0xbfb8aa3b, v104
	v_add_f32_e32 v100, 1.0, v100
	s_waitcnt lgkmcnt(3)
	v_mfma_f32_16x16x32_bf16 v[210:213], v[66:69], v[14:17], v[210:213]
	v_rcp_f32_e32 v100, v100
	v_exp_f32_e32 v105, v105
	v_mul_f32_e32 v96, 0x3fb8aa3b, v201
	v_exp_f32_e32 v96, v96
	s_waitcnt lgkmcnt(2)
	v_mfma_f32_16x16x32_bf16 v[210:213], v[70:73], v[6:9], v[210:213]
	v_mul_f32_e32 v97, v100, v97
	v_add_f32_e32 v100, 1.0, v105
	v_rcp_f32_e32 v100, v100
	v_lshlrev_b32_e32 v101, 16, v192
	v_mfma_f32_16x16x32_bf16 v[34:37], v[34:37], v[26:29], 0
	s_nop 2
	v_fmac_f32_e32 v101, v96, v210
	v_mul_f32_e32 v97, v97, v101
	v_and_b32_e32 v101, 0xffff0000, v192
	v_fmac_f32_e32 v101, v96, v211
	v_mul_f32_e32 v100, v100, v104
	v_mul_f32_e32 v100, v100, v101
	v_lshlrev_b32_e32 v101, 16, v221
	v_mul_f32_e32 v104, 0xbfb8aa3b, v101
	v_mfma_f32_16x16x32_bf16 v[34:37], v[42:45], v[18:21], v[34:37]
	v_exp_f32_e32 v104, v104
	v_lshlrev_b32_e32 v105, 16, v193
	v_fmac_f32_e32 v105, v96, v212
	v_mfma_f32_16x16x32_bf16 v[214:217], v[54:57], v[30:33], 0
	v_add_f32_e32 v104, 1.0, v104
	v_rcp_f32_e32 v104, v104
	v_and_b32_e32 v189, 0xffff0000, v221
	v_mfma_f32_16x16x32_bf16 v[54:57], v[54:57], v[26:29], 0
	v_mul_f32_e32 v192, 0xbfb8aa3b, v189
	s_or_b32 s20, s40, 6
	s_or_b32 s16, s39, s20
	v_mfma_f32_16x16x32_bf16 v[34:37], v[66:69], v[10:13], v[34:37]
	s_lshl_b64 s[18:19], s[16:17], 15
	s_add_u32 s18, s74, s18
	s_addc_u32 s19, s75, s19
	v_mfma_f32_16x16x32_bf16 v[214:217], v[62:65], v[22:25], v[214:217]
	v_cvt_pk_bf16_f32 v46, v46, v47
	v_cvt_pk_bf16_f32 v47, v48, v49
	v_cvt_pk_bf16_f32 v48, v58, v59
	v_mfma_f32_16x16x32_bf16 v[42:45], v[62:65], v[18:21], v[54:57]
	v_exp_f32_e32 v62, v192
	v_and_b32_e32 v64, 0xffff0000, v193
	v_fmac_f32_e32 v64, v96, v213
	v_mfma_f32_16x16x32_bf16 v[70:73], v[70:73], v[2:5], v[34:37]
	v_mul_f32_e32 v54, v104, v101
	v_mul_f32_e32 v63, v54, v105
	v_add_f32_e32 v62, 1.0, v62
	s_waitcnt vmcnt(4)
	v_lshlrev_b32_e32 v34, 16, v222
	v_mul_f32_e32 v35, 0xbfb8aa3b, v34
	v_exp_f32_e32 v35, v35
	s_waitcnt lgkmcnt(1)
	v_mfma_f32_16x16x32_bf16 v[54:57], v[202:205], v[14:17], v[214:217]
	v_and_b32_e32 v37, 0xffff0000, v222
	v_lshlrev_b32_e32 v36, 16, v218
	v_add_f32_e32 v35, 1.0, v35
	v_mfma_f32_16x16x32_bf16 v[42:45], v[202:205], v[10:13], v[42:45]
	v_rcp_f32_e32 v35, v35
	v_rcp_f32_e32 v62, v62
	s_waitcnt vmcnt(1)
	v_lshlrev_b32_e32 v204, 16, v107
	s_waitcnt lgkmcnt(0)
	v_mfma_f32_16x16x32_bf16 v[54:57], v[206:209], v[6:9], v[54:57]
	v_mul_f32_e32 v34, v35, v34
	v_and_b32_e32 v35, 0xffff0000, v218
	v_mul_f32_e32 v62, v62, v189
	v_mfma_f32_16x16x32_bf16 v[66:69], v[206:209], v[2:5], v[42:45]
	v_mul_f32_e32 v62, v62, v64
	s_nop 2
	v_fmac_f32_e32 v36, v96, v54
	v_mul_f32_e32 v34, v34, v36
	v_mul_f32_e32 v42, 0xbfb8aa3b, v37
	v_exp_f32_e32 v42, v42
	v_fmac_f32_e32 v35, v96, v55
	v_lshlrev_b32_e32 v44, 16, v219
	v_fmac_f32_e32 v44, v96, v56
	v_add_f32_e32 v36, 1.0, v42
	v_lshlrev_b32_e32 v42, 16, v223
	v_rcp_f32_e32 v36, v36
	v_mul_f32_e32 v43, 0xbfb8aa3b, v42
	v_exp_f32_e32 v43, v43
	v_mul_f32_e32 v64, v100, v100
	v_mul_f32_e32 v36, v36, v37
	v_and_b32_e32 v37, 0xffff0000, v223
	v_mul_f32_e32 v35, v36, v35
	v_add_f32_e32 v36, 1.0, v43
	v_mul_f32_e32 v43, 0xbfb8aa3b, v37
	v_rcp_f32_e32 v36, v36
	v_exp_f32_e32 v43, v43
	v_cvt_pk_bf16_f32 v192, v34, v35
	v_fmac_f32_e32 v64, v97, v97
	v_mul_f32_e32 v36, v36, v42
	v_add_f32_e32 v42, 1.0, v43
	v_rcp_f32_e32 v42, v42
	v_and_b32_e32 v43, 0xffff0000, v219
	v_mul_f32_e32 v36, v36, v44
	v_fmac_f32_e32 v43, v96, v57
	v_mul_f32_e32 v37, v42, v37
	v_mul_f32_e32 v42, v35, v35
	v_fmac_f32_e32 v42, v34, v34
	v_mul_f32_e32 v34, 0x3fb8aa3b, v224
	v_exp_f32_e32 v202, v34
	v_lshlrev_b32_e32 v34, 16, v106
	v_mul_f32_e32 v35, 0xbfb8aa3b, v34
	v_exp_f32_e32 v35, v35
	v_mul_f32_e32 v37, v37, v43
	v_fmac_f32_e32 v42, v36, v36
	v_cvt_pk_bf16_f32 v193, v36, v37
	v_lshlrev_b32_e32 v36, 16, v102
	v_fmac_f32_e32 v36, v202, v70
	v_add_f32_e32 v35, 1.0, v35
	v_and_b32_e32 v70, 0xffff0000, v106
	v_fmac_f32_e32 v42, v37, v37
	v_rcp_f32_e32 v35, v35
	v_mul_f32_e32 v37, 0xbfb8aa3b, v70
	v_exp_f32_e32 v37, v37
	v_fmac_f32_e32 v64, v63, v63
	v_mul_f32_e32 v34, v35, v34
	v_mul_f32_e32 v106, v34, v36
	v_add_f32_e32 v34, 1.0, v37
	v_rcp_f32_e32 v203, v34
	v_mul_f32_e32 v34, 0xbfb8aa3b, v204
	v_exp_f32_e32 v205, v34
	v_lshl_add_u64 v[34:35], s[18:19], 0, v[92:93]
	s_lshl_b64 s[18:19], s[16:17], 9
	s_add_u32 s18, s26, s18
	s_addc_u32 s19, s27, s19
	s_lshl_b32 s16, s20, 7
	s_add_u32 s20, s24, s16
	s_addc_u32 s21, s25, 0
	v_fmac_f32_e32 v64, v62, v62
	v_lshl_add_u64 v[34:35], v[34:35], 0, v[74:75]
	s_add_u32 s22, s60, s16
	v_add_f32_e32 v64, v190, v64
	v_cvt_pk_bf16_f32 v189, v97, v100
	v_cvt_pk_bf16_f32 v190, v63, v62
	v_lshl_add_u64 v[62:63], v[34:35], 0, s[14:15]
	v_add_co_u32_e32 v34, vcc, s35, v34
	s_addc_u32 s23, s61, 0
	v_lshl_add_u64 v[96:97], s[20:21], 0, v[88:89]
	v_addc_co_u32_e32 v35, vcc, 0, v35, vcc
	v_lshl_add_u64 v[92:93], s[18:19], 0, v[86:87]
	v_mov_b64_e32 v[100:101], s[22:23]
	v_lshl_add_u64 v[96:97], v[96:97], 0, v[76:77]
	v_add_f32_e32 v201, v64, v42
	global_load_dwordx4 v[42:45], v[34:35], off
	s_nop 0
	global_load_dwordx4 v[34:37], v[62:63], off offset:48
	global_load_dwordx4 v[54:57], v[62:63], off offset:32
	s_nop 0
	global_load_dwordx4 v[62:65], v[62:63], off offset:16
	v_mad_u64_u32 v[104:105], s[18:19], v82, s28, v[100:101]
	global_load_dword v222, v[92:93], off
	global_load_dwordx2 v[230:231], v[96:97], off
	global_load_dwordx2 v[232:233], v[96:97], off offset:32
	global_load_dword v238, v[92:93], off offset:64
	v_mad_u64_u32 v[96:97], s[18:19], v84, s28, v[100:101]
	v_add_u32_e32 v105, v81, v105
	v_lshl_add_u64 v[92:93], s[20:21], 0, v[90:91]
	v_add_u32_e32 v97, v79, v97
	v_lshl_add_u64 v[104:105], v[104:105], 0, v[76:77]
	v_lshl_add_u64 v[92:93], v[92:93], 0, v[76:77]
	v_lshl_add_u64 v[96:97], v[96:97], 0, v[76:77]
	global_load_dwordx2 v[234:235], v[104:105], off
	global_load_dwordx2 v[236:237], v[104:105], off offset:32
	global_load_dwordx2 v[100:101], v[92:93], off
	s_nop 0
	global_load_dwordx2 v[92:93], v[92:93], off offset:32
	s_nop 0
	global_load_dwordx2 v[104:105], v[96:97], off
	s_nop 0
	global_load_dwordx2 v[96:97], v[96:97], off offset:32
	v_and_b32_e32 v102, 0xffff0000, v102
	v_fmac_f32_e32 v102, v202, v71
	v_mul_f32_e32 v70, v203, v70
	v_and_b32_e32 v71, 0xffff0000, v107
	v_mul_f32_e32 v74, v70, v102
	v_mul_f32_e32 v102, 0xbfb8aa3b, v71
	v_exp_f32_e32 v102, v102
	v_add_f32_e32 v70, 1.0, v205
	v_rcp_f32_e32 v70, v70
	v_lshlrev_b32_e32 v107, 16, v103
	v_fmac_f32_e32 v107, v202, v72
	v_add_f32_e32 v72, 1.0, v102
	v_rcp_f32_e32 v72, v72
	v_mul_f32_e32 v70, v70, v204
	v_mul_f32_e32 v102, v70, v107
	v_and_b32_e32 v70, 0xffff0000, v103
	v_fmac_f32_e32 v70, v202, v73
	v_mul_f32_e32 v71, v72, v71
	s_waitcnt vmcnt(14)
	v_lshlrev_b32_e32 v72, 16, v98
	v_mul_f32_e32 v103, v71, v70
	v_mul_f32_e32 v70, 0xbfb8aa3b, v72
	v_exp_f32_e32 v73, v70
	v_and_b32_e32 v98, 0xffff0000, v98
	v_mul_f32_e32 v203, 0xbfb8aa3b, v98
	v_exp_f32_e32 v203, v203
	v_add_f32_e32 v73, 1.0, v73
	v_rcp_f32_e32 v73, v73
	v_lshlrev_b32_e32 v107, 16, v94
	v_fmac_f32_e32 v107, v202, v66
	v_and_b32_e32 v94, 0xffff0000, v94
	v_mul_f32_e32 v66, v73, v72
	v_lshlrev_b32_e32 v73, 16, v99
	v_mul_f32_e32 v66, v66, v107
	v_add_f32_e32 v72, 1.0, v203
	v_mul_f32_e32 v107, 0xbfb8aa3b, v73
	v_rcp_f32_e32 v72, v72
	v_exp_f32_e32 v107, v107
	v_fmac_f32_e32 v94, v202, v67
	v_cvt_pk_bf16_f32 v49, v60, v61
	v_mul_f32_e32 v67, v72, v98
	v_add_f32_e32 v72, 1.0, v107
	v_rcp_f32_e32 v72, v72
	v_mul_f32_e32 v67, v67, v94
	v_lshlrev_b32_e32 v94, 16, v95
	v_fmac_f32_e32 v94, v202, v68
	v_mul_f32_e32 v68, v72, v73
	v_and_b32_e32 v72, 0xffff0000, v99
	v_mul_f32_e32 v73, 0xbfb8aa3b, v72
	v_mul_f32_e32 v68, v68, v94
	v_and_b32_e32 v94, 0xffff0000, v95
	v_cvt_pk_bf16_f32 v50, v50, v51
	v_cvt_pk_bf16_f32 v51, v52, v53
	v_cvt_pk_bf16_f32 v52, v38, v39
	v_cvt_pk_bf16_f32 v53, v40, v41
	v_exp_f32_e32 v73, v73
	v_fmac_f32_e32 v94, v202, v69
	ds_write_b128 v128, v[46:49] offset:34816
	ds_write_b128 v128, v[50:53] offset:34832
	s_waitcnt lgkmcnt(0)
	s_barrier
	ds_read_b128 v[38:41], v129 offset:34816
	ds_read_b128 v[46:49], v129 offset:34880
	ds_read_b128 v[50:53], v129 offset:39168
	ds_read_b128 v[202:205], v129 offset:39232
	ds_read_b128 v[206:209], v129 offset:34944
	ds_read_b128 v[210:213], v129 offset:35008
	ds_read_b128 v[214:217], v129 offset:39296
	ds_read_b128 v[218:221], v129 offset:39360
	v_add_f32_e32 v69, 1.0, v73
	v_rcp_f32_e32 v69, v69
	v_cvt_pk_bf16_f32 v71, v106, v74
	v_cvt_pk_bf16_f32 v70, v102, v103
	v_cvt_pk_bf16_f32 v73, v66, v67
	s_nop 0
	v_mul_f32_e32 v58, v69, v72
	v_mul_f32_e32 v58, v58, v94
	v_cvt_pk_bf16_f32 v72, v68, v58
	s_waitcnt vmcnt(9)
	v_mul_f32_e32 v59, 0x3fb8aa3b, v222
	s_waitcnt lgkmcnt(7)
	v_mfma_f32_16x16x32_bf16 v[222:225], v[38:41], v[30:33], 0
	s_waitcnt vmcnt(5)
	v_lshlrev_b32_e32 v60, 16, v234
	v_mul_f32_e32 v61, 0xbfb8aa3b, v60
	v_exp_f32_e32 v61, v61
	s_waitcnt lgkmcnt(6)
	v_mfma_f32_16x16x32_bf16 v[222:225], v[46:49], v[22:25], v[222:225]
	v_and_b32_e32 v94, 0xffff0000, v234
	v_mul_f32_e32 v95, 0xbfb8aa3b, v94
	v_add_f32_e32 v61, 1.0, v61
	s_waitcnt lgkmcnt(3)
	v_mfma_f32_16x16x32_bf16 v[222:225], v[206:209], v[14:17], v[222:225]
	v_rcp_f32_e32 v61, v61
	v_exp_f32_e32 v95, v95
	v_exp_f32_e32 v59, v59
	s_waitcnt lgkmcnt(2)
	v_mfma_f32_16x16x32_bf16 v[222:225], v[210:213], v[6:9], v[222:225]
	v_mul_f32_e32 v60, v61, v60
	v_add_f32_e32 v61, 1.0, v95
	v_rcp_f32_e32 v61, v61
	v_lshlrev_b32_e32 v69, 16, v230
	v_and_b32_e32 v98, 0xffff0000, v235
	s_nop 2
	v_fmac_f32_e32 v69, v59, v222
	v_mul_f32_e32 v60, v60, v69
	v_and_b32_e32 v69, 0xffff0000, v230
	v_fmac_f32_e32 v69, v59, v223
	v_mul_f32_e32 v61, v61, v94
	v_mul_f32_e32 v61, v61, v69
	v_lshlrev_b32_e32 v69, 16, v235
	v_mul_f32_e32 v94, 0xbfb8aa3b, v69
	v_exp_f32_e32 v94, v94
	v_mul_f32_e32 v99, 0xbfb8aa3b, v98
	v_mfma_f32_16x16x32_bf16 v[226:229], v[50:53], v[30:33], 0
	v_exp_f32_e32 v99, v99
	v_add_f32_e32 v94, 1.0, v94
	v_rcp_f32_e32 v94, v94
	v_mfma_f32_16x16x32_bf16 v[38:41], v[38:41], v[26:29], 0
	v_lshlrev_b32_e32 v95, 16, v231
	v_fmac_f32_e32 v95, v59, v224
	s_or_b32 s18, s40, 7
	v_mfma_f32_16x16x32_bf16 v[50:53], v[50:53], v[26:29], 0
	s_or_b32 s16, s39, s18
	s_lshl_b64 s[16:17], s[16:17], 9
	s_add_u32 s16, s26, s16
	v_mfma_f32_16x16x32_bf16 v[38:41], v[46:49], v[18:21], v[38:41]
	s_addc_u32 s17, s27, s17
	s_lshl_b32 s20, s18, 7
	s_add_u32 s18, s24, s20
	v_mfma_f32_16x16x32_bf16 v[46:49], v[202:205], v[18:21], v[50:53]
	s_addc_u32 s19, s25, 0
	s_add_u32 s20, s60, s20
	s_addc_u32 s21, s61, 0
	v_mul_f32_e32 v50, v94, v69
	v_add_f32_e32 v94, 1.0, v99
	v_rcp_f32_e32 v94, v94
	v_mul_f32_e32 v69, v50, v95
	v_and_b32_e32 v95, 0xffff0000, v231
	v_fmac_f32_e32 v95, v59, v225
	v_mul_f32_e32 v94, v94, v98
	v_mul_f32_e32 v95, v94, v95
	v_mul_f32_e32 v94, v61, v61
	v_mfma_f32_16x16x32_bf16 v[38:41], v[206:209], v[10:13], v[38:41]
	v_fmac_f32_e32 v94, v60, v60
	v_fmac_f32_e32 v94, v69, v69
	v_fmac_f32_e32 v94, v95, v95
	v_mfma_f32_16x16x32_bf16 v[226:229], v[202:205], v[22:25], v[226:229]
	v_add_f32_e32 v98, v201, v94
	v_cvt_pk_bf16_f32 v94, v60, v61
	s_waitcnt vmcnt(4)
	v_lshlrev_b32_e32 v60, 16, v236
	s_waitcnt lgkmcnt(1)
	v_mfma_f32_16x16x32_bf16 v[46:49], v[214:217], v[10:13], v[46:49]
	v_cvt_pk_bf16_f32 v95, v69, v95
	v_cvt_pk_bf16_f32 v42, v42, v43
	v_cvt_pk_bf16_f32 v43, v44, v45
	v_mfma_f32_16x16x32_bf16 v[202:205], v[210:213], v[2:5], v[38:41]
	v_cvt_pk_bf16_f32 v44, v62, v63
	v_cvt_pk_bf16_f32 v45, v64, v65
	v_cvt_pk_bf16_f32 v54, v54, v55
	v_mfma_f32_16x16x32_bf16 v[50:53], v[214:217], v[14:17], v[226:229]
	v_cvt_pk_bf16_f32 v55, v56, v57
	s_nop 1
	v_mul_f32_e32 v38, 0xbfb8aa3b, v60
	v_exp_f32_e32 v61, v38
	s_waitcnt lgkmcnt(0)
	v_mfma_f32_16x16x32_bf16 v[38:41], v[218:221], v[2:5], v[46:49]
	v_cvt_pk_bf16_f32 v56, v34, v35
	v_cvt_pk_bf16_f32 v57, v36, v37
	v_mfma_f32_16x16x32_bf16 v[50:53], v[218:221], v[6:9], v[50:53]
	s_nop 1
	v_and_b32_e32 v48, 0xffff0000, v236
	v_mul_f32_e32 v49, 0xbfb8aa3b, v48
	v_add_f32_e32 v47, 1.0, v61
	v_exp_f32_e32 v49, v49
	v_rcp_f32_e32 v47, v47
	v_lshlrev_b32_e32 v46, 16, v232
	v_fmac_f32_e32 v46, v59, v50
	v_add_f32_e32 v49, 1.0, v49
	v_lshlrev_b32_e32 v50, 16, v237
	v_mul_f32_e32 v47, v47, v60
	v_rcp_f32_e32 v49, v49
	v_mul_f32_e32 v60, 0xbfb8aa3b, v50
	v_exp_f32_e32 v60, v60
	v_mul_f32_e32 v46, v47, v46
	v_and_b32_e32 v47, 0xffff0000, v232
	v_fmac_f32_e32 v47, v59, v51
	v_mul_f32_e32 v48, v49, v48
	v_and_b32_e32 v49, 0xffff0000, v237
	v_mul_f32_e32 v47, v48, v47
	v_add_f32_e32 v48, 1.0, v60
	v_mul_f32_e32 v51, 0xbfb8aa3b, v49
	v_rcp_f32_e32 v48, v48
	v_exp_f32_e32 v51, v51
	v_lshlrev_b32_e32 v60, 16, v233
	v_fmac_f32_e32 v60, v59, v52
	v_mul_f32_e32 v48, v48, v50
	v_add_f32_e32 v50, 1.0, v51
	v_rcp_f32_e32 v50, v50
	v_and_b32_e32 v51, 0xffff0000, v233
	v_mul_f32_e32 v48, v48, v60
	v_fmac_f32_e32 v51, v59, v53
	v_mul_f32_e32 v49, v50, v49
	v_mul_f32_e32 v50, v47, v47
	v_fmac_f32_e32 v50, v46, v46
	v_mul_f32_e32 v49, v49, v51
	v_fmac_f32_e32 v50, v48, v48
	v_fmac_f32_e32 v50, v49, v49
	v_add_f32_e32 v107, v98, v50
	v_cvt_pk_bf16_f32 v98, v46, v47
	v_mul_f32_e32 v46, 0x3fb8aa3b, v238
	v_exp_f32_e32 v201, v46
	s_waitcnt vmcnt(1)
	v_lshlrev_b32_e32 v46, 16, v104
	v_mul_f32_e32 v47, 0xbfb8aa3b, v46
	v_exp_f32_e32 v47, v47
	v_and_b32_e32 v60, 0xffff0000, v104
	v_cvt_pk_bf16_f32 v99, v48, v49
	v_mul_f32_e32 v49, 0xbfb8aa3b, v60
	v_add_f32_e32 v47, 1.0, v47
	v_rcp_f32_e32 v47, v47
	v_exp_f32_e32 v49, v49
	v_lshlrev_b32_e32 v48, 16, v100
	v_fmac_f32_e32 v48, v201, v202
	v_mul_f32_e32 v46, v47, v46
	v_mul_f32_e32 v59, v46, v48
	v_and_b32_e32 v61, 0xffff0000, v100
	v_add_f32_e32 v46, 1.0, v49
	v_lshlrev_b32_e32 v100, 16, v105
	v_rcp_f32_e32 v69, v46
	v_mul_f32_e32 v46, 0xbfb8aa3b, v100
	v_lshl_add_u64 v[48:49], s[18:19], 0, v[88:89]
	v_exp_f32_e32 v104, v46
	v_lshl_add_u64 v[46:47], s[16:17], 0, v[86:87]
	v_mov_b64_e32 v[50:51], s[20:21]
	v_lshl_add_u64 v[48:49], v[48:49], 0, v[76:77]
	v_mad_u64_u32 v[52:53], s[16:17], v82, s28, v[50:51]
	global_load_dword v218, v[46:47], off
	global_load_dwordx2 v[222:223], v[48:49], off
	global_load_dwordx2 v[224:225], v[48:49], off offset:32
	global_load_dword v230, v[46:47], off offset:64
	v_mad_u64_u32 v[48:49], s[16:17], v84, s28, v[50:51]
	v_add_u32_e32 v53, v81, v53
	v_lshl_add_u64 v[46:47], s[18:19], 0, v[90:91]
	v_add_u32_e32 v49, v79, v49
	v_lshl_add_u64 v[52:53], v[52:53], 0, v[76:77]
	v_lshl_add_u64 v[46:47], v[46:47], 0, v[76:77]
	v_lshl_add_u64 v[48:49], v[48:49], 0, v[76:77]
	global_load_dwordx2 v[226:227], v[52:53], off
	global_load_dwordx2 v[228:229], v[52:53], off offset:32
	global_load_dwordx2 v[50:51], v[46:47], off
	s_nop 0
	global_load_dwordx2 v[46:47], v[46:47], off offset:32
	s_nop 0
	global_load_dwordx2 v[52:53], v[48:49], off
	s_nop 0
	global_load_dwordx2 v[48:49], v[48:49], off offset:32
	v_mul_f32_e32 v60, v69, v60
	v_and_b32_e32 v69, 0xffff0000, v105
	v_mul_f32_e32 v77, 0xbfb8aa3b, v69
	v_exp_f32_e32 v77, v77
	v_fmac_f32_e32 v61, v201, v203
	v_mul_f32_e32 v60, v60, v61
	v_add_f32_e32 v61, 1.0, v104
	v_rcp_f32_e32 v61, v61
	v_add_f32_e32 v77, 1.0, v77
	v_rcp_f32_e32 v77, v77
	v_lshlrev_b32_e32 v86, 16, v101
	v_fmac_f32_e32 v86, v201, v204
	v_mul_f32_e32 v61, v61, v100
	v_mul_f32_e32 v61, v61, v86
	v_and_b32_e32 v86, 0xffff0000, v101
	v_fmac_f32_e32 v86, v201, v205
	v_mul_f32_e32 v69, v77, v69
	s_waitcnt vmcnt(10)
	v_lshlrev_b32_e32 v77, 16, v96
	v_mul_f32_e32 v69, v69, v86
	v_mul_f32_e32 v86, 0xbfb8aa3b, v77
	v_exp_f32_e32 v88, v86
	v_and_b32_e32 v90, 0xffff0000, v96
	v_mul_f32_e32 v91, 0xbfb8aa3b, v90
	v_exp_f32_e32 v91, v91
	v_add_f32_e32 v88, 1.0, v88
	v_rcp_f32_e32 v88, v88
	v_lshlrev_b32_e32 v89, 16, v92
	v_fmac_f32_e32 v89, v201, v38
	ds_write_b128 v128, v[42:45] offset:52224
	ds_write_b128 v128, v[54:57] offset:52240
	v_mul_f32_e32 v38, v88, v77
	v_lshlrev_b32_e32 v88, 16, v97
	v_mul_f32_e32 v38, v38, v89
	v_add_f32_e32 v77, 1.0, v91
	v_mul_f32_e32 v89, 0xbfb8aa3b, v88
	v_rcp_f32_e32 v77, v77
	v_exp_f32_e32 v89, v89
	v_and_b32_e32 v91, 0xffff0000, v92
	v_fmac_f32_e32 v91, v201, v39
	v_mul_f32_e32 v39, v77, v90
	v_add_f32_e32 v77, 1.0, v89
	v_rcp_f32_e32 v77, v77
	v_lshlrev_b32_e32 v89, 16, v93
	v_fmac_f32_e32 v89, v201, v40
	v_mul_f32_e32 v39, v39, v91
	v_mul_f32_e32 v40, v77, v88
	v_and_b32_e32 v77, 0xffff0000, v97
	v_mul_f32_e32 v88, 0xbfb8aa3b, v77
	v_exp_f32_e32 v88, v88
	v_mul_f32_e32 v40, v40, v89
	v_and_b32_e32 v89, 0xffff0000, v93
	s_waitcnt lgkmcnt(0)
	s_barrier
	ds_read_b128 v[42:45], v129 offset:52224
	ds_read_b128 v[54:57], v129 offset:52288
	ds_read_b128 v[62:65], v129 offset:56576
	ds_read_b128 v[90:93], v129 offset:56640
	ds_read_b128 v[202:205], v129 offset:52352
	ds_read_b128 v[206:209], v129 offset:52416
	ds_read_b128 v[210:213], v129 offset:56704
	ds_read_b128 v[214:217], v129 offset:56768
	v_fmac_f32_e32 v89, v201, v41
	v_add_f32_e32 v41, 1.0, v88
	v_rcp_f32_e32 v41, v41
	v_cvt_pk_bf16_f32 v87, v59, v60
	v_cvt_pk_bf16_f32 v86, v61, v69
	s_nop 0
	v_mul_f32_e32 v34, v41, v77
	v_mul_f32_e32 v34, v34, v89
	v_cvt_pk_bf16_f32 v89, v38, v39
	v_cvt_pk_bf16_f32 v88, v40, v34
	s_waitcnt vmcnt(9)
	v_mul_f32_e32 v35, 0x3fb8aa3b, v218
	s_waitcnt lgkmcnt(7)
	v_mfma_f32_16x16x32_bf16 v[218:221], v[42:45], v[30:33], 0
	s_waitcnt vmcnt(5)
	v_lshlrev_b32_e32 v36, 16, v226
	v_mul_f32_e32 v37, 0xbfb8aa3b, v36
	v_exp_f32_e32 v37, v37
	s_waitcnt lgkmcnt(5)
	v_mfma_f32_16x16x32_bf16 v[30:33], v[62:65], v[30:33], 0
	v_exp_f32_e32 v35, v35
	v_and_b32_e32 v77, 0xffff0000, v226
	v_add_f32_e32 v37, 1.0, v37
	v_mfma_f32_16x16x32_bf16 v[42:45], v[42:45], v[26:29], 0
	v_mul_f32_e32 v96, 0xbfb8aa3b, v77
	v_rcp_f32_e32 v37, v37
	v_exp_f32_e32 v96, v96
	v_mfma_f32_16x16x32_bf16 v[26:29], v[62:65], v[26:29], 0
	v_lshlrev_b32_e32 v41, 16, v222
	v_mul_f32_e32 v36, v37, v36
	v_add_f32_e32 v37, 1.0, v96
	v_mfma_f32_16x16x32_bf16 v[218:221], v[54:57], v[22:25], v[218:221]
	v_rcp_f32_e32 v37, v37
	v_lshlrev_b32_e32 v63, 16, v223
	v_mul_f32_e32 v37, v37, v77
	s_waitcnt lgkmcnt(4)
	v_mfma_f32_16x16x32_bf16 v[22:25], v[90:93], v[22:25], v[30:33]
	v_mfma_f32_16x16x32_bf16 v[30:33], v[54:57], v[18:21], v[42:45]
	s_nop 2
	v_and_b32_e32 v43, 0xffff0000, v227
	v_mul_f32_e32 v44, 0xbfb8aa3b, v43
	v_mfma_f32_16x16x32_bf16 v[18:21], v[90:93], v[18:21], v[26:29]
	s_nop 2
	v_exp_f32_e32 v26, v44
	s_waitcnt lgkmcnt(3)
	v_mfma_f32_16x16x32_bf16 v[218:221], v[202:205], v[14:17], v[218:221]
	v_and_b32_e32 v28, 0xffff0000, v223
	s_waitcnt lgkmcnt(1)
	v_mfma_f32_16x16x32_bf16 v[14:17], v[210:213], v[14:17], v[22:25]
	s_nop 2
	v_add_f32_e32 v22, 1.0, v26
	v_rcp_f32_e32 v26, v22
	v_mfma_f32_16x16x32_bf16 v[22:25], v[202:205], v[10:13], v[30:33]
	v_mul_f32_e32 v26, v26, v43
	v_mfma_f32_16x16x32_bf16 v[10:13], v[210:213], v[10:13], v[18:21]
	s_waitcnt vmcnt(4)
	s_nop 1
	v_lshlrev_b32_e32 v19, 16, v228
	v_mul_f32_e32 v20, 0xbfb8aa3b, v19
	v_exp_f32_e32 v20, v20
	v_mfma_f32_16x16x32_bf16 v[218:221], v[206:209], v[6:9], v[218:221]
	s_waitcnt lgkmcnt(0)
	v_mfma_f32_16x16x32_bf16 v[6:9], v[214:217], v[6:9], v[14:17]
	v_mfma_f32_16x16x32_bf16 v[14:17], v[206:209], v[2:5], v[22:25]
	s_nop 4
	v_fmac_f32_e32 v41, v35, v218
	v_mul_f32_e32 v36, v36, v41
	v_and_b32_e32 v41, 0xffff0000, v222
	v_mfma_f32_16x16x32_bf16 v[10:13], v[214:217], v[2:5], v[10:13]
	v_and_b32_e32 v4, 0xffff0000, v228
	v_mul_f32_e32 v5, 0xbfb8aa3b, v4
	v_add_f32_e32 v3, 1.0, v20
	v_exp_f32_e32 v5, v5
	v_rcp_f32_e32 v3, v3
	v_lshlrev_b32_e32 v2, 16, v224
	v_fmac_f32_e32 v2, v35, v6
	v_add_f32_e32 v5, 1.0, v5
	v_lshlrev_b32_e32 v6, 16, v229
	v_mul_f32_e32 v3, v3, v19
	v_rcp_f32_e32 v5, v5
	v_mul_f32_e32 v19, 0xbfb8aa3b, v6
	v_exp_f32_e32 v19, v19
	v_mul_f32_e32 v2, v3, v2
	v_and_b32_e32 v3, 0xffff0000, v224
	v_fmac_f32_e32 v3, v35, v7
	v_mul_f32_e32 v4, v5, v4
	v_and_b32_e32 v5, 0xffff0000, v229
	v_mul_f32_e32 v3, v4, v3
	v_add_f32_e32 v4, 1.0, v19
	v_mul_f32_e32 v7, 0xbfb8aa3b, v5
	v_rcp_f32_e32 v4, v4
	v_exp_f32_e32 v7, v7
	v_fmac_f32_e32 v41, v35, v219
	v_mul_f32_e32 v37, v37, v41
	v_lshlrev_b32_e32 v41, 16, v227
	v_mul_f32_e32 v62, 0xbfb8aa3b, v41
	v_exp_f32_e32 v62, v62
	v_mul_f32_e32 v4, v4, v6
	v_add_f32_e32 v6, 1.0, v7
	v_rcp_f32_e32 v6, v6
	v_add_f32_e32 v62, 1.0, v62
	v_rcp_f32_e32 v42, v62
	v_and_b32_e32 v7, 0xffff0000, v225
	v_mul_f32_e32 v5, v6, v5
	v_mul_f32_e32 v6, v3, v3
	v_fmac_f32_e32 v6, v2, v2
	v_cvt_pk_bf16_f32 v101, v2, v3
	v_mul_f32_e32 v2, 0x3fb8aa3b, v230
	v_fmac_f32_e32 v7, v35, v9
	v_exp_f32_e32 v9, v2
	s_waitcnt vmcnt(1)
	v_lshlrev_b32_e32 v2, 16, v52
	v_mul_f32_e32 v3, 0xbfb8aa3b, v2
	v_fmac_f32_e32 v63, v35, v220
	v_mul_f32_e32 v27, v42, v41
	v_mul_f32_e32 v18, v37, v37
	v_lshlrev_b32_e32 v19, 16, v225
	v_exp_f32_e32 v3, v3
	v_mul_f32_e32 v27, v27, v63
	v_fmac_f32_e32 v28, v35, v221
	v_fmac_f32_e32 v18, v36, v36
	v_fmac_f32_e32 v19, v35, v8
	v_mul_f32_e32 v26, v26, v28
	v_fmac_f32_e32 v18, v27, v27
	v_mul_f32_e32 v4, v4, v19
	v_fmac_f32_e32 v18, v26, v26
	v_mul_f32_e32 v5, v5, v7
	v_fmac_f32_e32 v6, v4, v4
	v_add_f32_e32 v18, v107, v18
	v_fmac_f32_e32 v6, v5, v5
	v_cvt_pk_bf16_f32 v100, v4, v5
	v_add_f32_e32 v3, 1.0, v3
	v_and_b32_e32 v5, 0xffff0000, v52
	v_add_f32_e32 v18, v18, v6
	v_rcp_f32_e32 v3, v3
	v_mul_f32_e32 v6, 0xbfb8aa3b, v5
	v_exp_f32_e32 v6, v6
	v_lshlrev_b32_e32 v4, 16, v50
	v_fmac_f32_e32 v4, v9, v14
	v_mul_f32_e32 v2, v3, v2
	v_mul_f32_e32 v2, v2, v4
	v_add_f32_e32 v4, 1.0, v6
	v_lshlrev_b32_e32 v6, 16, v53
	v_rcp_f32_e32 v4, v4
	v_mul_f32_e32 v7, 0xbfb8aa3b, v6
	v_exp_f32_e32 v7, v7
	v_and_b32_e32 v3, 0xffff0000, v50
	v_fmac_f32_e32 v3, v9, v15
	v_mul_f32_e32 v4, v4, v5
	v_and_b32_e32 v5, 0xffff0000, v53
	v_mul_f32_e32 v3, v4, v3
	v_add_f32_e32 v4, 1.0, v7
	v_mul_f32_e32 v7, 0xbfb8aa3b, v5
	v_rcp_f32_e32 v4, v4
	v_exp_f32_e32 v7, v7
	v_lshlrev_b32_e32 v8, 16, v51
	v_fmac_f32_e32 v8, v9, v16
	v_mul_f32_e32 v4, v4, v6
	v_add_f32_e32 v6, 1.0, v7
	v_rcp_f32_e32 v6, v6
	v_and_b32_e32 v7, 0xffff0000, v51
	v_fmac_f32_e32 v7, v9, v17
	v_mul_f32_e32 v4, v4, v8
	v_mul_f32_e32 v5, v6, v5
	s_waitcnt vmcnt(0)
	v_lshlrev_b32_e32 v6, 16, v48
	v_mul_f32_e32 v5, v5, v7
	v_mul_f32_e32 v7, 0xbfb8aa3b, v6
	v_exp_f32_e32 v7, v7
	v_lshlrev_b32_e32 v8, 16, v46
	v_fmac_f32_e32 v8, v9, v10
	v_and_b32_e32 v10, 0xffff0000, v48
	v_add_f32_e32 v7, 1.0, v7
	v_rcp_f32_e32 v7, v7
	v_mul_f32_e32 v14, 0xbfb8aa3b, v10
	v_exp_f32_e32 v14, v14
	v_lshlrev_b32_e32 v16, 2, v147
	v_mul_f32_e32 v6, v7, v6
	v_mul_f32_e32 v6, v6, v8
	v_add_f32_e32 v8, 1.0, v14
	v_rcp_f32_e32 v8, v8
	v_and_b32_e32 v7, 0xffff0000, v46
	v_fmac_f32_e32 v7, v9, v11
	v_lshlrev_b32_e32 v14, 16, v49
	v_mul_f32_e32 v8, v8, v10
	v_and_b32_e32 v10, 0xffff0000, v49
	v_mul_f32_e32 v11, 0xbfb8aa3b, v10
	v_exp_f32_e32 v11, v11
	v_mul_f32_e32 v15, 0xbfb8aa3b, v14
	v_exp_f32_e32 v15, v15
	v_mul_f32_e32 v7, v8, v7
	v_add_f32_e32 v11, 1.0, v11
	v_rcp_f32_e32 v11, v11
	v_add_f32_e32 v8, 1.0, v15
	v_lshlrev_b32_e32 v15, 16, v47
	v_fmac_f32_e32 v15, v9, v12
	v_and_b32_e32 v12, 0xffff0000, v47
	v_fmac_f32_e32 v12, v9, v13
	v_mul_f32_e32 v9, v11, v10
	v_and_b32_e32 v11, 64, v144
	v_xor_b32_e32 v10, 16, v144
	v_add_u32_e32 v11, 64, v11
	v_cmp_lt_i32_e32 vcc, v10, v11
	v_rcp_f32_e32 v8, v8
	v_mul_f32_e32 v9, v9, v12
	v_cndmask_b32_e32 v10, v144, v10, vcc
	v_lshlrev_b32_e32 v10, 2, v10
	ds_bpermute_b32 v13, v10, v18
	v_xor_b32_e32 v12, 32, v144
	v_cmp_lt_i32_e32 vcc, v12, v11
	v_mul_f32_e32 v8, v8, v14
	v_mul_f32_e32 v8, v8, v15
	v_cndmask_b32_e32 v11, v144, v12, vcc
	v_lshlrev_b32_e32 v12, 2, v11
	s_waitcnt lgkmcnt(0)
	v_add_f32_e32 v13, v18, v13
	ds_bpermute_b32 v14, v12, v13
	v_lshl_add_u32 v11, v112, 9, s36
	v_and_b32_e32 v15, 0xffffff80, v146
	v_cmp_eq_u32_e32 vcc, 0, v148
	v_add3_u32 v11, v11, v15, v16
	v_cvt_pk_bf16_f32 v96, v36, v37
	v_cvt_pk_bf16_f32 v97, v27, v26
	v_cvt_pk_bf16_f32 v90, v2, v3
	v_cvt_pk_bf16_f32 v91, v4, v5
	v_cvt_pk_bf16_f32 v93, v6, v7
	v_cvt_pk_bf16_f32 v92, v8, v9
	s_and_saveexec_b64 s[16:17], vcc
	s_cbranch_execz .LBB0_546
	s_waitcnt lgkmcnt(0)
	v_add_f32_e32 v13, v13, v14
	ds_write_b32 v11, v13
